# load segment end: s_setprio 1 moved ahead of the counted wait, so the wave goes from the wait straight to the barrier
# baseline (speedup 1.0000x reference)
.LBB0_141:
	s_lshl_b32 s34, s11, 8
	s_ashr_i32 s35, s34, 31
	s_lshl_b64 s[34:35], s[34:35], 11
	s_add_u32 s82, s49, s34
	s_addc_u32 s83, s53, s35
	s_and_b64 s[34:35], s[0:1], exec
	s_cselect_b32 s5, s83, s7
	s_cselect_b32 s22, s82, s6
	s_ashr_i32 s81, s80, 31
	s_lshl_b64 s[34:35], s[80:81], 19
	s_add_u32 s84, s55, s34
	s_addc_u32 s85, s57, s35
	s_and_b64 s[34:35], s[0:1], exec
	s_cselect_b32 s34, s85, s9
	s_cselect_b32 s35, s84, s8
	s_add_u32 s40, s8, 0x100
	s_addc_u32 s41, s9, 0
	s_mov_b32 s50, -2
	s_waitcnt vmcnt(0)
	s_waitcnt lgkmcnt(0)
	ds_read_b128 v[128:131], v175
	ds_read_b128 v[132:135], v175 offset:1024
	ds_read_b128 v[136:139], v175 offset:2048
	ds_read_b128 v[140:143], v175 offset:3072
	ds_read_b128 v[166:169], v176
	ds_read_b128 v[170:173], v176 offset:1024
	ds_read_b128 v[182:185], v176 offset:2048
	ds_read_b128 v[186:189], v176 offset:3072
	s_add_u32 s8, s6, 0x100
	s_addc_u32 s9, s7, 0
	s_cmp_eq_u32 s50, 12
	s_cselect_b32 s89, s5, s9
	s_cselect_b32 s88, s22, s8
	s_cselect_b32 s87, s34, s41
	s_cselect_b32 s86, s35, s40
	v_lshl_add_u64 v[220:221], s[6:7], 0, v[158:159]
	s_add_i32 m0, s61, 0xc000
	ds_read_b128 v[190:193], v177
	ds_read_b128 v[194:197], v177 offset:1024
	ds_read_b128 v[198:201], v177 offset:2048
	ds_read_b128 v[202:205], v177 offset:3072
	ds_read_b128 v[206:209], v177 offset:4096
	ds_read_b128 v[210:213], v177 offset:5120
	ds_read_b128 v[214:217], v177 offset:6144
	ds_read_b128 v[224:227], v177 offset:7168
	global_load_lds_dwordx4 v[220:221], off
	s_add_i32 m0, s61, 0xe000
	v_lshl_add_u64 v[220:221], s[6:7], 0, v[160:161]
	global_load_lds_dwordx4 v[220:221], off
	s_setprio 1
	s_waitcnt vmcnt(8) lgkmcnt(0)
	s_barrier
	v_mfma_f32_16x16x32_bf16 v[124:127], v[128:131], v[190:193], 0
	v_mfma_f32_16x16x32_bf16 v[120:123], v[136:139], v[190:193], 0
	v_mfma_f32_16x16x32_bf16 v[108:111], v[128:131], v[198:201], 0
	v_mfma_f32_16x16x32_bf16 v[104:107], v[136:139], v[198:201], 0
	v_mfma_f32_16x16x32_bf16 v[92:95], v[128:131], v[206:209], 0
	v_mfma_f32_16x16x32_bf16 v[88:91], v[136:139], v[206:209], 0
	v_mfma_f32_16x16x32_bf16 v[76:79], v[128:131], v[214:217], 0
	v_mfma_f32_16x16x32_bf16 v[72:75], v[136:139], v[214:217], 0
	v_mfma_f32_16x16x32_bf16 v[124:127], v[132:135], v[194:197], v[124:127]
	v_mfma_f32_16x16x32_bf16 v[120:123], v[140:143], v[194:197], v[120:123]
	v_mfma_f32_16x16x32_bf16 v[108:111], v[132:135], v[202:205], v[108:111]
	v_mfma_f32_16x16x32_bf16 v[104:107], v[140:143], v[202:205], v[104:107]
	v_mfma_f32_16x16x32_bf16 v[92:95], v[132:135], v[210:213], v[92:95]
	v_mfma_f32_16x16x32_bf16 v[88:91], v[140:143], v[210:213], v[88:91]
	v_mfma_f32_16x16x32_bf16 v[76:79], v[132:135], v[224:227], v[76:79]
	v_mfma_f32_16x16x32_bf16 v[72:75], v[140:143], v[224:227], v[72:75]
	v_mfma_f32_16x16x32_bf16 v[116:119], v[166:169], v[190:193], 0
	v_mfma_f32_16x16x32_bf16 v[112:115], v[182:185], v[190:193], 0
	v_mfma_f32_16x16x32_bf16 v[100:103], v[166:169], v[198:201], 0
	v_mfma_f32_16x16x32_bf16 v[96:99], v[182:185], v[198:201], 0
	v_mfma_f32_16x16x32_bf16 v[84:87], v[166:169], v[206:209], 0
	v_mfma_f32_16x16x32_bf16 v[80:83], v[182:185], v[206:209], 0
	v_mfma_f32_16x16x32_bf16 v[68:71], v[166:169], v[214:217], 0
	v_mfma_f32_16x16x32_bf16 v[64:67], v[182:185], v[214:217], 0
	v_mfma_f32_16x16x32_bf16 v[116:119], v[170:173], v[194:197], v[116:119]
	v_mfma_f32_16x16x32_bf16 v[112:115], v[186:189], v[194:197], v[112:115]
	v_mfma_f32_16x16x32_bf16 v[100:103], v[170:173], v[202:205], v[100:103]
	v_mfma_f32_16x16x32_bf16 v[96:99], v[186:189], v[202:205], v[96:99]
	v_mfma_f32_16x16x32_bf16 v[84:87], v[170:173], v[210:213], v[84:87]
	v_mfma_f32_16x16x32_bf16 v[80:83], v[186:189], v[210:213], v[80:83]
	v_mfma_f32_16x16x32_bf16 v[68:71], v[170:173], v[224:227], v[68:71]
	v_mfma_f32_16x16x32_bf16 v[64:67], v[186:189], v[224:227], v[64:67]
	s_barrier
	s_setprio 0
	s_add_i32 s6, s37, s59
	v_lshl_add_u64 v[220:221], s[86:87], 0, v[148:149]
	s_mov_b32 m0, s6
	ds_read_b128 v[190:193], v177 offset:16384
	ds_read_b128 v[194:197], v177 offset:17408
	ds_read_b128 v[198:201], v177 offset:18432
	ds_read_b128 v[202:205], v177 offset:19456
	ds_read_b128 v[206:209], v177 offset:20480
	ds_read_b128 v[210:213], v177 offset:21504
	ds_read_b128 v[214:217], v177 offset:22528
	ds_read_b128 v[224:227], v177 offset:23552
	global_load_lds_dwordx4 v[220:221], off
	s_add_i32 m0, s6, 0x2000
	s_add_u32 s6, s86, 0x40000
	v_lshl_add_u64 v[228:229], s[86:87], 0, v[152:153]
	s_addc_u32 s7, s87, 0
	s_add_i32 s51, s97, s59
	global_load_lds_dwordx4 v[228:229], off
	v_lshl_add_u64 v[230:231], s[6:7], 0, v[148:149]
	s_mov_b32 m0, s51
	v_lshl_add_u64 v[232:233], s[88:89], 0, v[150:151]
	global_load_lds_dwordx4 v[230:231], off
	v_lshl_add_u64 v[230:231], s[6:7], 0, v[152:153]
	s_add_i32 m0, s51, 0x2000
	v_lshl_add_u64 v[234:235], v[232:233], 0, s[68:69]
	global_load_lds_dwordx4 v[230:231], off
	s_mov_b32 m0, s61
	v_lshl_add_u64 v[230:231], s[88:89], 0, v[146:147]
	global_load_lds_dwordx4 v[230:231], off
	s_mov_b32 m0, s63
	s_nop 0
	global_load_lds_dwordx4 v[234:235], off
	s_setprio 1
	s_waitcnt vmcnt(8) lgkmcnt(0)
	s_barrier
	v_mfma_f32_16x16x32_bf16 v[60:63], v[128:131], v[190:193], 0
	v_mfma_f32_16x16x32_bf16 v[56:59], v[136:139], v[190:193], 0
	v_mfma_f32_16x16x32_bf16 v[44:47], v[128:131], v[198:201], 0
	v_mfma_f32_16x16x32_bf16 v[40:43], v[136:139], v[198:201], 0
	v_mfma_f32_16x16x32_bf16 v[28:31], v[128:131], v[206:209], 0
	v_mfma_f32_16x16x32_bf16 v[24:27], v[136:139], v[206:209], 0
	v_mfma_f32_16x16x32_bf16 v[12:15], v[128:131], v[214:217], 0
	v_mfma_f32_16x16x32_bf16 v[8:11], v[136:139], v[214:217], 0
	v_mfma_f32_16x16x32_bf16 v[60:63], v[132:135], v[194:197], v[60:63]
	v_mfma_f32_16x16x32_bf16 v[56:59], v[140:143], v[194:197], v[56:59]
	v_mfma_f32_16x16x32_bf16 v[44:47], v[132:135], v[202:205], v[44:47]
	v_mfma_f32_16x16x32_bf16 v[40:43], v[140:143], v[202:205], v[40:43]
	v_mfma_f32_16x16x32_bf16 v[28:31], v[132:135], v[210:213], v[28:31]
	v_mfma_f32_16x16x32_bf16 v[24:27], v[140:143], v[210:213], v[24:27]
	v_mfma_f32_16x16x32_bf16 v[12:15], v[132:135], v[224:227], v[12:15]
	v_mfma_f32_16x16x32_bf16 v[8:11], v[140:143], v[224:227], v[8:11]
	v_mfma_f32_16x16x32_bf16 v[52:55], v[166:169], v[190:193], 0
	v_mfma_f32_16x16x32_bf16 v[48:51], v[182:185], v[190:193], 0
	v_mfma_f32_16x16x32_bf16 v[36:39], v[166:169], v[198:201], 0
	v_mfma_f32_16x16x32_bf16 v[32:35], v[182:185], v[198:201], 0
	v_mfma_f32_16x16x32_bf16 v[20:23], v[166:169], v[206:209], 0
	v_mfma_f32_16x16x32_bf16 v[16:19], v[182:185], v[206:209], 0
	v_mfma_f32_16x16x32_bf16 v[4:7], v[166:169], v[214:217], 0
	v_mfma_f32_16x16x32_bf16 v[0:3], v[182:185], v[214:217], 0
	v_mfma_f32_16x16x32_bf16 v[52:55], v[170:173], v[194:197], v[52:55]
	v_mfma_f32_16x16x32_bf16 v[48:51], v[186:189], v[194:197], v[48:51]
	v_mfma_f32_16x16x32_bf16 v[36:39], v[170:173], v[202:205], v[36:39]
	v_mfma_f32_16x16x32_bf16 v[32:35], v[186:189], v[202:205], v[32:35]
	v_mfma_f32_16x16x32_bf16 v[20:23], v[170:173], v[210:213], v[20:23]
	v_mfma_f32_16x16x32_bf16 v[16:19], v[186:189], v[210:213], v[16:19]
	v_mfma_f32_16x16x32_bf16 v[4:7], v[170:173], v[224:227], v[4:7]
	v_mfma_f32_16x16x32_bf16 v[0:3], v[186:189], v[224:227], v[0:3]
	s_barrier
	s_setprio 0
	s_add_i32 s6, 0, 0x18000
	s_add_i32 s51, 0, 0x1c000
	v_add_u32_e32 v140, s6, v174
	v_add_u32_e32 v154, s51, v174
	ds_read_b128 v[128:131], v140
	ds_read_b128 v[132:135], v140 offset:1024
	ds_read_b128 v[136:139], v140 offset:2048
	ds_read_b128 v[140:143], v140 offset:3072
	ds_read_b128 v[166:169], v154
	ds_read_b128 v[170:173], v154 offset:1024
	ds_read_b128 v[182:185], v154 offset:2048
	ds_read_b128 v[186:189], v154 offset:3072
	s_mov_b32 m0, s65
	v_lshl_add_u64 v[234:235], v[230:231], 0, s[66:67]
	ds_read_b128 v[190:193], v177 offset:32768
	ds_read_b128 v[194:197], v177 offset:33792
	ds_read_b128 v[198:201], v177 offset:34816
	ds_read_b128 v[202:205], v177 offset:35840
	ds_read_b128 v[206:209], v177 offset:36864
	ds_read_b128 v[210:213], v177 offset:37888
	ds_read_b128 v[214:217], v177 offset:38912
	ds_read_b128 v[224:227], v177 offset:39936
	global_load_lds_dwordx4 v[234:235], off
	s_mov_b32 m0, s77
	v_lshl_add_u64 v[234:235], v[232:233], 0, s[46:47]
	global_load_lds_dwordx4 v[234:235], off
	s_setprio 1
	s_waitcnt vmcnt(8) lgkmcnt(0)
	s_barrier
	v_mfma_f32_16x16x32_bf16 v[124:127], v[128:131], v[190:193], v[124:127]
	v_mfma_f32_16x16x32_bf16 v[120:123], v[136:139], v[190:193], v[120:123]
	v_mfma_f32_16x16x32_bf16 v[108:111], v[128:131], v[198:201], v[108:111]
	v_mfma_f32_16x16x32_bf16 v[104:107], v[136:139], v[198:201], v[104:107]
	v_mfma_f32_16x16x32_bf16 v[92:95], v[128:131], v[206:209], v[92:95]
	v_mfma_f32_16x16x32_bf16 v[88:91], v[136:139], v[206:209], v[88:91]
	v_mfma_f32_16x16x32_bf16 v[76:79], v[128:131], v[214:217], v[76:79]
	v_mfma_f32_16x16x32_bf16 v[72:75], v[136:139], v[214:217], v[72:75]
	v_mfma_f32_16x16x32_bf16 v[124:127], v[132:135], v[194:197], v[124:127]
	v_mfma_f32_16x16x32_bf16 v[120:123], v[140:143], v[194:197], v[120:123]
	v_mfma_f32_16x16x32_bf16 v[108:111], v[132:135], v[202:205], v[108:111]
	v_mfma_f32_16x16x32_bf16 v[104:107], v[140:143], v[202:205], v[104:107]
	v_mfma_f32_16x16x32_bf16 v[92:95], v[132:135], v[210:213], v[92:95]
	v_mfma_f32_16x16x32_bf16 v[88:91], v[140:143], v[210:213], v[88:91]
	v_mfma_f32_16x16x32_bf16 v[76:79], v[132:135], v[224:227], v[76:79]
	v_mfma_f32_16x16x32_bf16 v[72:75], v[140:143], v[224:227], v[72:75]
	v_mfma_f32_16x16x32_bf16 v[116:119], v[166:169], v[190:193], v[116:119]
	v_mfma_f32_16x16x32_bf16 v[112:115], v[182:185], v[190:193], v[112:115]
	v_mfma_f32_16x16x32_bf16 v[100:103], v[166:169], v[198:201], v[100:103]
	v_mfma_f32_16x16x32_bf16 v[96:99], v[182:185], v[198:201], v[96:99]
	v_mfma_f32_16x16x32_bf16 v[84:87], v[166:169], v[206:209], v[84:87]
	v_mfma_f32_16x16x32_bf16 v[80:83], v[182:185], v[206:209], v[80:83]
	v_mfma_f32_16x16x32_bf16 v[68:71], v[166:169], v[214:217], v[68:71]
	v_mfma_f32_16x16x32_bf16 v[64:67], v[182:185], v[214:217], v[64:67]
	v_mfma_f32_16x16x32_bf16 v[116:119], v[170:173], v[194:197], v[116:119]
	v_mfma_f32_16x16x32_bf16 v[112:115], v[186:189], v[194:197], v[112:115]
	v_mfma_f32_16x16x32_bf16 v[100:103], v[170:173], v[202:205], v[100:103]
	v_mfma_f32_16x16x32_bf16 v[96:99], v[186:189], v[202:205], v[96:99]
	v_mfma_f32_16x16x32_bf16 v[84:87], v[170:173], v[210:213], v[84:87]
	v_mfma_f32_16x16x32_bf16 v[80:83], v[186:189], v[210:213], v[80:83]
	v_mfma_f32_16x16x32_bf16 v[68:71], v[170:173], v[224:227], v[68:71]
	v_mfma_f32_16x16x32_bf16 v[64:67], v[186:189], v[224:227], v[64:67]
	s_barrier
	s_setprio 0
	s_add_i32 s6, s6, s59
	v_lshl_add_u64 v[220:221], v[220:221], 0, s[42:43]
	s_mov_b32 m0, s6
	ds_read_b128 v[190:193], v177 offset:49152
	ds_read_b128 v[194:197], v177 offset:50176
	ds_read_b128 v[198:201], v177 offset:51200
	ds_read_b128 v[202:205], v177 offset:52224
	ds_read_b128 v[206:209], v177 offset:53248
	ds_read_b128 v[210:213], v177 offset:54272
	ds_read_b128 v[214:217], v177 offset:55296
	ds_read_b128 v[224:227], v177 offset:56320
	global_load_lds_dwordx4 v[220:221], off
	s_add_i32 m0, s6, 0x2000
	s_add_u32 s6, s86, 0x40080
	v_lshl_add_u64 v[220:221], v[228:229], 0, s[42:43]
	s_addc_u32 s7, s87, 0
	s_add_i32 s51, s51, s59
	global_load_lds_dwordx4 v[220:221], off
	s_mov_b32 m0, s51
	v_lshl_add_u64 v[220:221], s[6:7], 0, v[148:149]
	global_load_lds_dwordx4 v[220:221], off
	s_add_i32 m0, s51, 0x2000
	v_lshl_add_u64 v[220:221], s[6:7], 0, v[152:153]
	global_load_lds_dwordx4 v[220:221], off
	s_mov_b32 m0, s91
	v_lshl_add_u64 v[220:221], v[230:231], 0, s[42:43]
	global_load_lds_dwordx4 v[220:221], off
	s_mov_b32 m0, s92
	v_lshl_add_u64 v[220:221], v[232:233], 0, s[44:45]
	global_load_lds_dwordx4 v[220:221], off
	s_setprio 1
	s_waitcnt vmcnt(8) lgkmcnt(0)
	s_barrier
	v_mfma_f32_16x16x32_bf16 v[60:63], v[128:131], v[190:193], v[60:63]
	v_mfma_f32_16x16x32_bf16 v[56:59], v[136:139], v[190:193], v[56:59]
	v_mfma_f32_16x16x32_bf16 v[44:47], v[128:131], v[198:201], v[44:47]
	v_mfma_f32_16x16x32_bf16 v[40:43], v[136:139], v[198:201], v[40:43]
	v_mfma_f32_16x16x32_bf16 v[28:31], v[128:131], v[206:209], v[28:31]
	v_mfma_f32_16x16x32_bf16 v[24:27], v[136:139], v[206:209], v[24:27]
	v_mfma_f32_16x16x32_bf16 v[12:15], v[128:131], v[214:217], v[12:15]
	v_mfma_f32_16x16x32_bf16 v[8:11], v[136:139], v[214:217], v[8:11]
	v_mfma_f32_16x16x32_bf16 v[60:63], v[132:135], v[194:197], v[60:63]
	v_mfma_f32_16x16x32_bf16 v[56:59], v[140:143], v[194:197], v[56:59]
	v_mfma_f32_16x16x32_bf16 v[44:47], v[132:135], v[202:205], v[44:47]
	v_mfma_f32_16x16x32_bf16 v[40:43], v[140:143], v[202:205], v[40:43]
	v_mfma_f32_16x16x32_bf16 v[28:31], v[132:135], v[210:213], v[28:31]
	v_mfma_f32_16x16x32_bf16 v[24:27], v[140:143], v[210:213], v[24:27]
	v_mfma_f32_16x16x32_bf16 v[12:15], v[132:135], v[224:227], v[12:15]
	v_mfma_f32_16x16x32_bf16 v[8:11], v[140:143], v[224:227], v[8:11]
	v_mfma_f32_16x16x32_bf16 v[52:55], v[166:169], v[190:193], v[52:55]
	v_mfma_f32_16x16x32_bf16 v[48:51], v[182:185], v[190:193], v[48:51]
	v_mfma_f32_16x16x32_bf16 v[36:39], v[166:169], v[198:201], v[36:39]
	v_mfma_f32_16x16x32_bf16 v[32:35], v[182:185], v[198:201], v[32:35]
	v_mfma_f32_16x16x32_bf16 v[20:23], v[166:169], v[206:209], v[20:23]
	v_mfma_f32_16x16x32_bf16 v[16:19], v[182:185], v[206:209], v[16:19]
	v_mfma_f32_16x16x32_bf16 v[4:7], v[166:169], v[214:217], v[4:7]
	v_mfma_f32_16x16x32_bf16 v[0:3], v[182:185], v[214:217], v[0:3]
	v_mfma_f32_16x16x32_bf16 v[52:55], v[170:173], v[194:197], v[52:55]
	v_mfma_f32_16x16x32_bf16 v[48:51], v[186:189], v[194:197], v[48:51]
	v_mfma_f32_16x16x32_bf16 v[36:39], v[170:173], v[202:205], v[36:39]
	v_mfma_f32_16x16x32_bf16 v[32:35], v[186:189], v[202:205], v[32:35]
	v_mfma_f32_16x16x32_bf16 v[20:23], v[170:173], v[210:213], v[20:23]
	v_mfma_f32_16x16x32_bf16 v[16:19], v[186:189], v[210:213], v[16:19]
	v_mfma_f32_16x16x32_bf16 v[4:7], v[170:173], v[224:227], v[4:7]
	v_mfma_f32_16x16x32_bf16 v[0:3], v[186:189], v[224:227], v[0:3]
	s_barrier
	s_setprio 0
	s_add_i32 s50, s50, 2
	s_add_u32 s40, s40, 0x100
	s_addc_u32 s41, s41, 0
	s_cmp_gt_u32 s50, 13
	s_mov_b64 s[6:7], s[8:9]
.LBB0_142:
	ds_read_b128 v[128:131], v175
	ds_read_b128 v[132:135], v175 offset:1024
	ds_read_b128 v[136:139], v175 offset:2048
	ds_read_b128 v[140:143], v175 offset:3072
	ds_read_b128 v[166:169], v176
	ds_read_b128 v[170:173], v176 offset:1024
	ds_read_b128 v[182:185], v176 offset:2048
	ds_read_b128 v[186:189], v176 offset:3072
	s_add_u32 s8, s6, 0x100
	s_addc_u32 s9, s7, 0
	s_cmp_eq_u32 s50, 12
	s_cselect_b32 s89, s5, s9
	s_cselect_b32 s88, s22, s8
	s_cselect_b32 s87, s34, s41
	s_cselect_b32 s86, s35, s40
	v_lshl_add_u64 v[220:221], s[6:7], 0, v[158:159]
	s_add_i32 m0, s61, 0xc000
	ds_read_b128 v[190:193], v177
	ds_read_b128 v[194:197], v177 offset:1024
	ds_read_b128 v[198:201], v177 offset:2048
	ds_read_b128 v[202:205], v177 offset:3072
	ds_read_b128 v[206:209], v177 offset:4096
	ds_read_b128 v[210:213], v177 offset:5120
	ds_read_b128 v[214:217], v177 offset:6144
	ds_read_b128 v[224:227], v177 offset:7168
	global_load_lds_dwordx4 v[220:221], off
	s_add_i32 m0, s61, 0xe000
	v_lshl_add_u64 v[220:221], s[6:7], 0, v[160:161]
	global_load_lds_dwordx4 v[220:221], off
	s_setprio 1
	s_waitcnt vmcnt(8) lgkmcnt(0)
	s_barrier
	v_mfma_f32_16x16x32_bf16 v[124:127], v[128:131], v[190:193], v[124:127]
	v_mfma_f32_16x16x32_bf16 v[120:123], v[136:139], v[190:193], v[120:123]
	v_mfma_f32_16x16x32_bf16 v[108:111], v[128:131], v[198:201], v[108:111]
	v_mfma_f32_16x16x32_bf16 v[104:107], v[136:139], v[198:201], v[104:107]
	v_mfma_f32_16x16x32_bf16 v[92:95], v[128:131], v[206:209], v[92:95]
	v_mfma_f32_16x16x32_bf16 v[88:91], v[136:139], v[206:209], v[88:91]
	v_mfma_f32_16x16x32_bf16 v[76:79], v[128:131], v[214:217], v[76:79]
	v_mfma_f32_16x16x32_bf16 v[72:75], v[136:139], v[214:217], v[72:75]
	v_mfma_f32_16x16x32_bf16 v[124:127], v[132:135], v[194:197], v[124:127]
	v_mfma_f32_16x16x32_bf16 v[120:123], v[140:143], v[194:197], v[120:123]
	v_mfma_f32_16x16x32_bf16 v[108:111], v[132:135], v[202:205], v[108:111]
	v_mfma_f32_16x16x32_bf16 v[104:107], v[140:143], v[202:205], v[104:107]
	v_mfma_f32_16x16x32_bf16 v[92:95], v[132:135], v[210:213], v[92:95]
	v_mfma_f32_16x16x32_bf16 v[88:91], v[140:143], v[210:213], v[88:91]
	v_mfma_f32_16x16x32_bf16 v[76:79], v[132:135], v[224:227], v[76:79]
	v_mfma_f32_16x16x32_bf16 v[72:75], v[140:143], v[224:227], v[72:75]
	v_mfma_f32_16x16x32_bf16 v[116:119], v[166:169], v[190:193], v[116:119]
	v_mfma_f32_16x16x32_bf16 v[112:115], v[182:185], v[190:193], v[112:115]
	v_mfma_f32_16x16x32_bf16 v[100:103], v[166:169], v[198:201], v[100:103]
	v_mfma_f32_16x16x32_bf16 v[96:99], v[182:185], v[198:201], v[96:99]
	v_mfma_f32_16x16x32_bf16 v[84:87], v[166:169], v[206:209], v[84:87]
	v_mfma_f32_16x16x32_bf16 v[80:83], v[182:185], v[206:209], v[80:83]
	v_mfma_f32_16x16x32_bf16 v[68:71], v[166:169], v[214:217], v[68:71]
	v_mfma_f32_16x16x32_bf16 v[64:67], v[182:185], v[214:217], v[64:67]
	v_mfma_f32_16x16x32_bf16 v[116:119], v[170:173], v[194:197], v[116:119]
	v_mfma_f32_16x16x32_bf16 v[112:115], v[186:189], v[194:197], v[112:115]
	v_mfma_f32_16x16x32_bf16 v[100:103], v[170:173], v[202:205], v[100:103]
	v_mfma_f32_16x16x32_bf16 v[96:99], v[186:189], v[202:205], v[96:99]
	v_mfma_f32_16x16x32_bf16 v[84:87], v[170:173], v[210:213], v[84:87]
	v_mfma_f32_16x16x32_bf16 v[80:83], v[186:189], v[210:213], v[80:83]
	v_mfma_f32_16x16x32_bf16 v[68:71], v[170:173], v[224:227], v[68:71]
	v_mfma_f32_16x16x32_bf16 v[64:67], v[186:189], v[224:227], v[64:67]
	s_barrier
	s_setprio 0
	s_add_i32 s6, s37, s59
	v_lshl_add_u64 v[220:221], s[86:87], 0, v[148:149]
	s_mov_b32 m0, s6
	ds_read_b128 v[190:193], v177 offset:16384
	ds_read_b128 v[194:197], v177 offset:17408
	ds_read_b128 v[198:201], v177 offset:18432
	ds_read_b128 v[202:205], v177 offset:19456
	ds_read_b128 v[206:209], v177 offset:20480
	ds_read_b128 v[210:213], v177 offset:21504
	ds_read_b128 v[214:217], v177 offset:22528
	ds_read_b128 v[224:227], v177 offset:23552
	global_load_lds_dwordx4 v[220:221], off
	s_add_i32 m0, s6, 0x2000
	s_add_u32 s6, s86, 0x40000
	v_lshl_add_u64 v[228:229], s[86:87], 0, v[152:153]
	s_addc_u32 s7, s87, 0
	s_add_i32 s51, s97, s59
	global_load_lds_dwordx4 v[228:229], off
	v_lshl_add_u64 v[230:231], s[6:7], 0, v[148:149]
	s_mov_b32 m0, s51
	v_lshl_add_u64 v[232:233], s[88:89], 0, v[150:151]
	global_load_lds_dwordx4 v[230:231], off
	v_lshl_add_u64 v[230:231], s[6:7], 0, v[152:153]
	s_add_i32 m0, s51, 0x2000
	v_lshl_add_u64 v[234:235], v[232:233], 0, s[68:69]
	global_load_lds_dwordx4 v[230:231], off
	s_mov_b32 m0, s61
	v_lshl_add_u64 v[230:231], s[88:89], 0, v[146:147]
	global_load_lds_dwordx4 v[230:231], off
	s_mov_b32 m0, s63
	s_nop 0
	global_load_lds_dwordx4 v[234:235], off
	s_setprio 1
	s_waitcnt vmcnt(8) lgkmcnt(0)
	s_barrier
	v_mfma_f32_16x16x32_bf16 v[60:63], v[128:131], v[190:193], v[60:63]
	v_mfma_f32_16x16x32_bf16 v[56:59], v[136:139], v[190:193], v[56:59]
	v_mfma_f32_16x16x32_bf16 v[44:47], v[128:131], v[198:201], v[44:47]
	v_mfma_f32_16x16x32_bf16 v[40:43], v[136:139], v[198:201], v[40:43]
	v_mfma_f32_16x16x32_bf16 v[28:31], v[128:131], v[206:209], v[28:31]
	v_mfma_f32_16x16x32_bf16 v[24:27], v[136:139], v[206:209], v[24:27]
	v_mfma_f32_16x16x32_bf16 v[12:15], v[128:131], v[214:217], v[12:15]
	v_mfma_f32_16x16x32_bf16 v[8:11], v[136:139], v[214:217], v[8:11]
	v_mfma_f32_16x16x32_bf16 v[60:63], v[132:135], v[194:197], v[60:63]
	v_mfma_f32_16x16x32_bf16 v[56:59], v[140:143], v[194:197], v[56:59]
	v_mfma_f32_16x16x32_bf16 v[44:47], v[132:135], v[202:205], v[44:47]
	v_mfma_f32_16x16x32_bf16 v[40:43], v[140:143], v[202:205], v[40:43]
	v_mfma_f32_16x16x32_bf16 v[28:31], v[132:135], v[210:213], v[28:31]
	v_mfma_f32_16x16x32_bf16 v[24:27], v[140:143], v[210:213], v[24:27]
	v_mfma_f32_16x16x32_bf16 v[12:15], v[132:135], v[224:227], v[12:15]
	v_mfma_f32_16x16x32_bf16 v[8:11], v[140:143], v[224:227], v[8:11]
	v_mfma_f32_16x16x32_bf16 v[52:55], v[166:169], v[190:193], v[52:55]
	v_mfma_f32_16x16x32_bf16 v[48:51], v[182:185], v[190:193], v[48:51]
	v_mfma_f32_16x16x32_bf16 v[36:39], v[166:169], v[198:201], v[36:39]
	v_mfma_f32_16x16x32_bf16 v[32:35], v[182:185], v[198:201], v[32:35]
	v_mfma_f32_16x16x32_bf16 v[20:23], v[166:169], v[206:209], v[20:23]
	v_mfma_f32_16x16x32_bf16 v[16:19], v[182:185], v[206:209], v[16:19]
	v_mfma_f32_16x16x32_bf16 v[4:7], v[166:169], v[214:217], v[4:7]
	v_mfma_f32_16x16x32_bf16 v[0:3], v[182:185], v[214:217], v[0:3]
	v_mfma_f32_16x16x32_bf16 v[52:55], v[170:173], v[194:197], v[52:55]
	v_mfma_f32_16x16x32_bf16 v[48:51], v[186:189], v[194:197], v[48:51]
	v_mfma_f32_16x16x32_bf16 v[36:39], v[170:173], v[202:205], v[36:39]
	v_mfma_f32_16x16x32_bf16 v[32:35], v[186:189], v[202:205], v[32:35]
	v_mfma_f32_16x16x32_bf16 v[20:23], v[170:173], v[210:213], v[20:23]
	v_mfma_f32_16x16x32_bf16 v[16:19], v[186:189], v[210:213], v[16:19]
	v_mfma_f32_16x16x32_bf16 v[4:7], v[170:173], v[224:227], v[4:7]
	v_mfma_f32_16x16x32_bf16 v[0:3], v[186:189], v[224:227], v[0:3]
	s_barrier
	s_setprio 0
	s_add_i32 s6, 0, 0x18000
	s_add_i32 s51, 0, 0x1c000
	v_add_u32_e32 v140, s6, v174
	v_add_u32_e32 v154, s51, v174
	ds_read_b128 v[128:131], v140
	ds_read_b128 v[132:135], v140 offset:1024
	ds_read_b128 v[136:139], v140 offset:2048
	ds_read_b128 v[140:143], v140 offset:3072
	ds_read_b128 v[166:169], v154
	ds_read_b128 v[170:173], v154 offset:1024
	ds_read_b128 v[182:185], v154 offset:2048
	ds_read_b128 v[186:189], v154 offset:3072
	s_mov_b32 m0, s65
	v_lshl_add_u64 v[234:235], v[230:231], 0, s[66:67]
	ds_read_b128 v[190:193], v177 offset:32768
	ds_read_b128 v[194:197], v177 offset:33792
	ds_read_b128 v[198:201], v177 offset:34816
	ds_read_b128 v[202:205], v177 offset:35840
	ds_read_b128 v[206:209], v177 offset:36864
	ds_read_b128 v[210:213], v177 offset:37888
	ds_read_b128 v[214:217], v177 offset:38912
	ds_read_b128 v[224:227], v177 offset:39936
	global_load_lds_dwordx4 v[234:235], off
	s_mov_b32 m0, s77
	v_lshl_add_u64 v[234:235], v[232:233], 0, s[46:47]
	global_load_lds_dwordx4 v[234:235], off
	s_setprio 1
	s_waitcnt vmcnt(8) lgkmcnt(0)
	s_barrier
	v_mfma_f32_16x16x32_bf16 v[124:127], v[128:131], v[190:193], v[124:127]
	v_mfma_f32_16x16x32_bf16 v[120:123], v[136:139], v[190:193], v[120:123]
	v_mfma_f32_16x16x32_bf16 v[108:111], v[128:131], v[198:201], v[108:111]
	v_mfma_f32_16x16x32_bf16 v[104:107], v[136:139], v[198:201], v[104:107]
	v_mfma_f32_16x16x32_bf16 v[92:95], v[128:131], v[206:209], v[92:95]
	v_mfma_f32_16x16x32_bf16 v[88:91], v[136:139], v[206:209], v[88:91]
	v_mfma_f32_16x16x32_bf16 v[76:79], v[128:131], v[214:217], v[76:79]
	v_mfma_f32_16x16x32_bf16 v[72:75], v[136:139], v[214:217], v[72:75]
	v_mfma_f32_16x16x32_bf16 v[124:127], v[132:135], v[194:197], v[124:127]
	v_mfma_f32_16x16x32_bf16 v[120:123], v[140:143], v[194:197], v[120:123]
	v_mfma_f32_16x16x32_bf16 v[108:111], v[132:135], v[202:205], v[108:111]
	v_mfma_f32_16x16x32_bf16 v[104:107], v[140:143], v[202:205], v[104:107]
	v_mfma_f32_16x16x32_bf16 v[92:95], v[132:135], v[210:213], v[92:95]
	v_mfma_f32_16x16x32_bf16 v[88:91], v[140:143], v[210:213], v[88:91]
	v_mfma_f32_16x16x32_bf16 v[76:79], v[132:135], v[224:227], v[76:79]
	v_mfma_f32_16x16x32_bf16 v[72:75], v[140:143], v[224:227], v[72:75]
	v_mfma_f32_16x16x32_bf16 v[116:119], v[166:169], v[190:193], v[116:119]
	v_mfma_f32_16x16x32_bf16 v[112:115], v[182:185], v[190:193], v[112:115]
	v_mfma_f32_16x16x32_bf16 v[100:103], v[166:169], v[198:201], v[100:103]
	v_mfma_f32_16x16x32_bf16 v[96:99], v[182:185], v[198:201], v[96:99]
	v_mfma_f32_16x16x32_bf16 v[84:87], v[166:169], v[206:209], v[84:87]
	v_mfma_f32_16x16x32_bf16 v[80:83], v[182:185], v[206:209], v[80:83]
	v_mfma_f32_16x16x32_bf16 v[68:71], v[166:169], v[214:217], v[68:71]
	v_mfma_f32_16x16x32_bf16 v[64:67], v[182:185], v[214:217], v[64:67]
	v_mfma_f32_16x16x32_bf16 v[116:119], v[170:173], v[194:197], v[116:119]
	v_mfma_f32_16x16x32_bf16 v[112:115], v[186:189], v[194:197], v[112:115]
	v_mfma_f32_16x16x32_bf16 v[100:103], v[170:173], v[202:205], v[100:103]
	v_mfma_f32_16x16x32_bf16 v[96:99], v[186:189], v[202:205], v[96:99]
	v_mfma_f32_16x16x32_bf16 v[84:87], v[170:173], v[210:213], v[84:87]
	v_mfma_f32_16x16x32_bf16 v[80:83], v[186:189], v[210:213], v[80:83]
	v_mfma_f32_16x16x32_bf16 v[68:71], v[170:173], v[224:227], v[68:71]
	v_mfma_f32_16x16x32_bf16 v[64:67], v[186:189], v[224:227], v[64:67]
	s_barrier
	s_setprio 0
	s_add_i32 s6, s6, s59
	v_lshl_add_u64 v[220:221], v[220:221], 0, s[42:43]
	s_mov_b32 m0, s6
	ds_read_b128 v[190:193], v177 offset:49152
	ds_read_b128 v[194:197], v177 offset:50176
	ds_read_b128 v[198:201], v177 offset:51200
	ds_read_b128 v[202:205], v177 offset:52224
	ds_read_b128 v[206:209], v177 offset:53248
	ds_read_b128 v[210:213], v177 offset:54272
	ds_read_b128 v[214:217], v177 offset:55296
	ds_read_b128 v[224:227], v177 offset:56320
	global_load_lds_dwordx4 v[220:221], off
	s_add_i32 m0, s6, 0x2000
	s_add_u32 s6, s86, 0x40080
	v_lshl_add_u64 v[220:221], v[228:229], 0, s[42:43]
	s_addc_u32 s7, s87, 0
	s_add_i32 s51, s51, s59
	global_load_lds_dwordx4 v[220:221], off
	s_mov_b32 m0, s51
	v_lshl_add_u64 v[220:221], s[6:7], 0, v[148:149]
	global_load_lds_dwordx4 v[220:221], off
	s_add_i32 m0, s51, 0x2000
	v_lshl_add_u64 v[220:221], s[6:7], 0, v[152:153]
	global_load_lds_dwordx4 v[220:221], off
	s_mov_b32 m0, s91
	v_lshl_add_u64 v[220:221], v[230:231], 0, s[42:43]
	global_load_lds_dwordx4 v[220:221], off
	s_mov_b32 m0, s92
	v_lshl_add_u64 v[220:221], v[232:233], 0, s[44:45]
	global_load_lds_dwordx4 v[220:221], off
	s_setprio 1
	s_waitcnt vmcnt(8) lgkmcnt(0)
	s_barrier
	v_mfma_f32_16x16x32_bf16 v[60:63], v[128:131], v[190:193], v[60:63]
	v_mfma_f32_16x16x32_bf16 v[56:59], v[136:139], v[190:193], v[56:59]
	v_mfma_f32_16x16x32_bf16 v[44:47], v[128:131], v[198:201], v[44:47]
	v_mfma_f32_16x16x32_bf16 v[40:43], v[136:139], v[198:201], v[40:43]
	v_mfma_f32_16x16x32_bf16 v[28:31], v[128:131], v[206:209], v[28:31]
	v_mfma_f32_16x16x32_bf16 v[24:27], v[136:139], v[206:209], v[24:27]
	v_mfma_f32_16x16x32_bf16 v[12:15], v[128:131], v[214:217], v[12:15]
	v_mfma_f32_16x16x32_bf16 v[8:11], v[136:139], v[214:217], v[8:11]
	v_mfma_f32_16x16x32_bf16 v[60:63], v[132:135], v[194:197], v[60:63]
	v_mfma_f32_16x16x32_bf16 v[56:59], v[140:143], v[194:197], v[56:59]
	v_mfma_f32_16x16x32_bf16 v[44:47], v[132:135], v[202:205], v[44:47]
	v_mfma_f32_16x16x32_bf16 v[40:43], v[140:143], v[202:205], v[40:43]
	v_mfma_f32_16x16x32_bf16 v[28:31], v[132:135], v[210:213], v[28:31]
	v_mfma_f32_16x16x32_bf16 v[24:27], v[140:143], v[210:213], v[24:27]
	v_mfma_f32_16x16x32_bf16 v[12:15], v[132:135], v[224:227], v[12:15]
	v_mfma_f32_16x16x32_bf16 v[8:11], v[140:143], v[224:227], v[8:11]
	v_mfma_f32_16x16x32_bf16 v[52:55], v[166:169], v[190:193], v[52:55]
	v_mfma_f32_16x16x32_bf16 v[48:51], v[182:185], v[190:193], v[48:51]
	v_mfma_f32_16x16x32_bf16 v[36:39], v[166:169], v[198:201], v[36:39]
	v_mfma_f32_16x16x32_bf16 v[32:35], v[182:185], v[198:201], v[32:35]
	v_mfma_f32_16x16x32_bf16 v[20:23], v[166:169], v[206:209], v[20:23]
	v_mfma_f32_16x16x32_bf16 v[16:19], v[182:185], v[206:209], v[16:19]
	v_mfma_f32_16x16x32_bf16 v[4:7], v[166:169], v[214:217], v[4:7]
	v_mfma_f32_16x16x32_bf16 v[0:3], v[182:185], v[214:217], v[0:3]
	v_mfma_f32_16x16x32_bf16 v[52:55], v[170:173], v[194:197], v[52:55]
	v_mfma_f32_16x16x32_bf16 v[48:51], v[186:189], v[194:197], v[48:51]
	v_mfma_f32_16x16x32_bf16 v[36:39], v[170:173], v[202:205], v[36:39]
	v_mfma_f32_16x16x32_bf16 v[32:35], v[186:189], v[202:205], v[32:35]
	v_mfma_f32_16x16x32_bf16 v[20:23], v[170:173], v[210:213], v[20:23]
	v_mfma_f32_16x16x32_bf16 v[16:19], v[186:189], v[210:213], v[16:19]
	v_mfma_f32_16x16x32_bf16 v[4:7], v[170:173], v[224:227], v[4:7]
	v_mfma_f32_16x16x32_bf16 v[0:3], v[186:189], v[224:227], v[0:3]
	s_barrier
	s_setprio 0
	s_add_i32 s50, s50, 2
	s_add_u32 s40, s40, 0x100
	s_addc_u32 s41, s41, 0
	s_cmp_gt_u32 s50, 13
	s_mov_b64 s[6:7], s[8:9]
	s_cbranch_scc0 .LBB0_142
	v_readlane_b32 s6, v249, 60
	v_readlane_b32 s7, v249, 61
	s_and_b64 vcc, exec, s[6:7]
	s_cbranch_vccz .LBB0_145
	s_barrier

.LBB0_392:
	s_lshl_b32 s40, s65, 8
	v_readlane_b32 s72, v249, 0
	s_ashr_i32 s41, s40, 31
	v_readlane_b32 s84, v249, 12
	v_readlane_b32 s85, v249, 13
	s_lshl_b64 s[40:41], s[40:41], 10
	v_readlane_b32 s86, v249, 14
	v_readlane_b32 s87, v249, 15
	s_mov_b64 s[28:29], s[84:85]
	s_add_u32 s40, s28, s40
	s_addc_u32 s41, s29, s41
	s_and_b64 s[42:43], s[0:1], exec
	s_cselect_b32 s67, s41, s45
	s_cselect_b32 s72, s40, s44
	s_ashr_i32 s39, s38, 31
	s_lshl_b64 s[42:43], s[38:39], 18
	s_add_u32 s42, s10, s42
	s_addc_u32 s43, s11, s43
	s_and_b64 s[48:49], s[0:1], exec
	v_readlane_b32 s73, v249, 1
	v_readlane_b32 s74, v249, 2
	s_cselect_b32 s39, s43, s47
	s_cselect_b32 s50, s42, s46
	s_add_u32 s51, s46, 0x100
	s_addc_u32 s73, s47, 0
	s_mov_b32 s74, -2
	s_waitcnt vmcnt(0)
	s_waitcnt lgkmcnt(0)
	v_readlane_b32 s75, v249, 3
	v_readlane_b32 s76, v249, 4
	v_readlane_b32 s77, v249, 5
	v_readlane_b32 s78, v249, 6
	v_readlane_b32 s79, v249, 7
	v_readlane_b32 s80, v249, 8
	v_readlane_b32 s81, v249, 9
	v_readlane_b32 s82, v249, 10
	v_readlane_b32 s83, v249, 11
	s_mov_b64 s[30:31], s[86:87]
	ds_read_b128 v[144:147], v153
	ds_read_b128 v[156:159], v153 offset:1024
	ds_read_b128 v[160:163], v153 offset:2048
	ds_read_b128 v[164:167], v153 offset:3072
	ds_read_b128 v[168:171], v154
	ds_read_b128 v[172:175], v154 offset:1024
	ds_read_b128 v[176:179], v154 offset:2048
	ds_read_b128 v[180:183], v154 offset:3072
	s_add_u32 s46, s44, 0x100
	s_addc_u32 s47, s45, 0
	s_cmp_eq_u32 s74, 4
	s_cselect_b32 s77, s67, s47
	s_cselect_b32 s76, s72, s46
	s_cselect_b32 s49, s39, s73
	s_cselect_b32 s48, s50, s51
	v_lshl_add_u64 v[148:149], s[44:45], 0, v[136:137]
	s_add_i32 m0, s52, 0xc000
	ds_read_b128 v[184:187], v155
	ds_read_b128 v[188:191], v155 offset:1024
	ds_read_b128 v[192:195], v155 offset:2048
	ds_read_b128 v[196:199], v155 offset:3072
	ds_read_b128 v[200:203], v155 offset:4096
	ds_read_b128 v[204:207], v155 offset:5120
	ds_read_b128 v[208:211], v155 offset:6144
	ds_read_b128 v[212:215], v155 offset:7168
	global_load_lds_dwordx4 v[148:149], off
	s_add_i32 m0, s52, 0xe000
	v_lshl_add_u64 v[148:149], s[44:45], 0, v[138:139]
	global_load_lds_dwordx4 v[148:149], off
	s_setprio 1
	s_waitcnt vmcnt(8) lgkmcnt(0)
	s_barrier
	v_mfma_f32_16x16x32_bf16 v[124:127], v[144:147], v[184:187], 0
	v_mfma_f32_16x16x32_bf16 v[120:123], v[160:163], v[184:187], 0
	v_mfma_f32_16x16x32_bf16 v[108:111], v[144:147], v[192:195], 0
	v_mfma_f32_16x16x32_bf16 v[104:107], v[160:163], v[192:195], 0
	v_mfma_f32_16x16x32_bf16 v[92:95], v[144:147], v[200:203], 0
	v_mfma_f32_16x16x32_bf16 v[88:91], v[160:163], v[200:203], 0
	v_mfma_f32_16x16x32_bf16 v[76:79], v[144:147], v[208:211], 0
	v_mfma_f32_16x16x32_bf16 v[72:75], v[160:163], v[208:211], 0
	v_mfma_f32_16x16x32_bf16 v[124:127], v[156:159], v[188:191], v[124:127]
	v_mfma_f32_16x16x32_bf16 v[120:123], v[164:167], v[188:191], v[120:123]
	v_mfma_f32_16x16x32_bf16 v[108:111], v[156:159], v[196:199], v[108:111]
	v_mfma_f32_16x16x32_bf16 v[104:107], v[164:167], v[196:199], v[104:107]
	v_mfma_f32_16x16x32_bf16 v[92:95], v[156:159], v[204:207], v[92:95]
	v_mfma_f32_16x16x32_bf16 v[88:91], v[164:167], v[204:207], v[88:91]
	v_mfma_f32_16x16x32_bf16 v[76:79], v[156:159], v[212:215], v[76:79]
	v_mfma_f32_16x16x32_bf16 v[72:75], v[164:167], v[212:215], v[72:75]
	v_mfma_f32_16x16x32_bf16 v[116:119], v[168:171], v[184:187], 0
	v_mfma_f32_16x16x32_bf16 v[112:115], v[176:179], v[184:187], 0
	v_mfma_f32_16x16x32_bf16 v[100:103], v[168:171], v[192:195], 0
	v_mfma_f32_16x16x32_bf16 v[96:99], v[176:179], v[192:195], 0
	v_mfma_f32_16x16x32_bf16 v[84:87], v[168:171], v[200:203], 0
	v_mfma_f32_16x16x32_bf16 v[80:83], v[176:179], v[200:203], 0
	v_mfma_f32_16x16x32_bf16 v[68:71], v[168:171], v[208:211], 0
	v_mfma_f32_16x16x32_bf16 v[64:67], v[176:179], v[208:211], 0
	v_mfma_f32_16x16x32_bf16 v[116:119], v[172:175], v[188:191], v[116:119]
	v_mfma_f32_16x16x32_bf16 v[112:115], v[180:183], v[188:191], v[112:115]
	v_mfma_f32_16x16x32_bf16 v[100:103], v[172:175], v[196:199], v[100:103]
	v_mfma_f32_16x16x32_bf16 v[96:99], v[180:183], v[196:199], v[96:99]
	v_mfma_f32_16x16x32_bf16 v[84:87], v[172:175], v[204:207], v[84:87]
	v_mfma_f32_16x16x32_bf16 v[80:83], v[180:183], v[204:207], v[80:83]
	v_mfma_f32_16x16x32_bf16 v[68:71], v[172:175], v[212:215], v[68:71]
	v_mfma_f32_16x16x32_bf16 v[64:67], v[180:183], v[212:215], v[64:67]
	s_barrier
	s_setprio 0
	s_add_i32 s44, s61, s33
	v_lshl_add_u64 v[148:149], s[48:49], 0, v[132:133]
	s_mov_b32 m0, s44
	ds_read_b128 v[184:187], v155 offset:16384
	ds_read_b128 v[188:191], v155 offset:17408
	ds_read_b128 v[192:195], v155 offset:18432
	ds_read_b128 v[196:199], v155 offset:19456
	ds_read_b128 v[200:203], v155 offset:20480
	ds_read_b128 v[204:207], v155 offset:21504
	ds_read_b128 v[208:211], v155 offset:22528
	ds_read_b128 v[212:215], v155 offset:23552
	global_load_lds_dwordx4 v[148:149], off
	s_add_i32 m0, s44, 0x2000
	s_add_u32 s44, s48, 0x20000
	v_lshl_add_u64 v[216:217], s[48:49], 0, v[128:129]
	s_addc_u32 s45, s49, 0
	s_add_i32 s68, s62, s33
	global_load_lds_dwordx4 v[216:217], off
	v_lshl_add_u64 v[220:221], s[44:45], 0, v[132:133]
	s_mov_b32 m0, s68
	v_lshl_add_u64 v[224:225], s[76:77], 0, v[130:131]
	global_load_lds_dwordx4 v[220:221], off
	v_lshl_add_u64 v[220:221], s[44:45], 0, v[128:129]
	s_add_i32 m0, s68, 0x2000
	v_lshl_add_u64 v[226:227], v[224:225], 0, s[8:9]
	global_load_lds_dwordx4 v[220:221], off
	s_mov_b32 m0, s52
	v_lshl_add_u64 v[220:221], s[76:77], 0, v[134:135]
	global_load_lds_dwordx4 v[220:221], off
	s_mov_b32 m0, s53
	s_nop 0
	global_load_lds_dwordx4 v[226:227], off
	s_setprio 1
	s_waitcnt vmcnt(8) lgkmcnt(0)
	s_barrier
	v_mfma_f32_16x16x32_bf16 v[60:63], v[144:147], v[184:187], 0
	v_mfma_f32_16x16x32_bf16 v[56:59], v[160:163], v[184:187], 0
	v_mfma_f32_16x16x32_bf16 v[44:47], v[144:147], v[192:195], 0
	v_mfma_f32_16x16x32_bf16 v[40:43], v[160:163], v[192:195], 0
	v_mfma_f32_16x16x32_bf16 v[28:31], v[144:147], v[200:203], 0
	v_mfma_f32_16x16x32_bf16 v[24:27], v[160:163], v[200:203], 0
	v_mfma_f32_16x16x32_bf16 v[12:15], v[144:147], v[208:211], 0
	v_mfma_f32_16x16x32_bf16 v[8:11], v[160:163], v[208:211], 0
	v_mfma_f32_16x16x32_bf16 v[60:63], v[156:159], v[188:191], v[60:63]
	v_mfma_f32_16x16x32_bf16 v[56:59], v[164:167], v[188:191], v[56:59]
	v_mfma_f32_16x16x32_bf16 v[44:47], v[156:159], v[196:199], v[44:47]
	v_mfma_f32_16x16x32_bf16 v[40:43], v[164:167], v[196:199], v[40:43]
	v_mfma_f32_16x16x32_bf16 v[28:31], v[156:159], v[204:207], v[28:31]
	v_mfma_f32_16x16x32_bf16 v[24:27], v[164:167], v[204:207], v[24:27]
	v_mfma_f32_16x16x32_bf16 v[12:15], v[156:159], v[212:215], v[12:15]
	v_mfma_f32_16x16x32_bf16 v[8:11], v[164:167], v[212:215], v[8:11]
	v_mfma_f32_16x16x32_bf16 v[52:55], v[168:171], v[184:187], 0
	v_mfma_f32_16x16x32_bf16 v[48:51], v[176:179], v[184:187], 0
	v_mfma_f32_16x16x32_bf16 v[36:39], v[168:171], v[192:195], 0
	v_mfma_f32_16x16x32_bf16 v[32:35], v[176:179], v[192:195], 0
	v_mfma_f32_16x16x32_bf16 v[20:23], v[168:171], v[200:203], 0
	v_mfma_f32_16x16x32_bf16 v[16:19], v[176:179], v[200:203], 0
	v_mfma_f32_16x16x32_bf16 v[4:7], v[168:171], v[208:211], 0
	v_mfma_f32_16x16x32_bf16 v[0:3], v[176:179], v[208:211], 0
	v_mfma_f32_16x16x32_bf16 v[52:55], v[172:175], v[188:191], v[52:55]
	v_mfma_f32_16x16x32_bf16 v[48:51], v[180:183], v[188:191], v[48:51]
	v_mfma_f32_16x16x32_bf16 v[36:39], v[172:175], v[196:199], v[36:39]
	v_mfma_f32_16x16x32_bf16 v[32:35], v[180:183], v[196:199], v[32:35]
	v_mfma_f32_16x16x32_bf16 v[20:23], v[172:175], v[204:207], v[20:23]
	v_mfma_f32_16x16x32_bf16 v[16:19], v[180:183], v[204:207], v[16:19]
	v_mfma_f32_16x16x32_bf16 v[4:7], v[172:175], v[212:215], v[4:7]
	v_mfma_f32_16x16x32_bf16 v[0:3], v[180:183], v[212:215], v[0:3]
	s_barrier
	s_setprio 0
	s_add_i32 s44, 0, 0x18000
	s_add_i32 s68, 0, 0x1c000
	v_add_u32_e32 v164, s44, v151
	v_add_u32_e32 v180, s68, v151
	ds_read_b128 v[144:147], v164
	ds_read_b128 v[156:159], v164 offset:1024
	ds_read_b128 v[160:163], v164 offset:2048
	ds_read_b128 v[164:167], v164 offset:3072
	ds_read_b128 v[168:171], v180
	ds_read_b128 v[172:175], v180 offset:1024
	ds_read_b128 v[176:179], v180 offset:2048
	ds_read_b128 v[180:183], v180 offset:3072
	s_mov_b32 m0, s54
	v_lshl_add_u64 v[226:227], v[220:221], 0, s[6:7]
	ds_read_b128 v[184:187], v155 offset:32768
	ds_read_b128 v[188:191], v155 offset:33792
	ds_read_b128 v[192:195], v155 offset:34816
	ds_read_b128 v[196:199], v155 offset:35840
	ds_read_b128 v[200:203], v155 offset:36864
	ds_read_b128 v[204:207], v155 offset:37888
	ds_read_b128 v[208:211], v155 offset:38912
	ds_read_b128 v[212:215], v155 offset:39936
	global_load_lds_dwordx4 v[226:227], off
	s_mov_b32 m0, s55
	v_lshl_add_u64 v[226:227], v[224:225], 0, s[12:13]
	global_load_lds_dwordx4 v[226:227], off
	s_setprio 1
	s_waitcnt vmcnt(8) lgkmcnt(0)
	s_barrier
	v_mfma_f32_16x16x32_bf16 v[124:127], v[144:147], v[184:187], v[124:127]
	v_mfma_f32_16x16x32_bf16 v[120:123], v[160:163], v[184:187], v[120:123]
	v_mfma_f32_16x16x32_bf16 v[108:111], v[144:147], v[192:195], v[108:111]
	v_mfma_f32_16x16x32_bf16 v[104:107], v[160:163], v[192:195], v[104:107]
	v_mfma_f32_16x16x32_bf16 v[92:95], v[144:147], v[200:203], v[92:95]
	v_mfma_f32_16x16x32_bf16 v[88:91], v[160:163], v[200:203], v[88:91]
	v_mfma_f32_16x16x32_bf16 v[76:79], v[144:147], v[208:211], v[76:79]
	v_mfma_f32_16x16x32_bf16 v[72:75], v[160:163], v[208:211], v[72:75]
	v_mfma_f32_16x16x32_bf16 v[124:127], v[156:159], v[188:191], v[124:127]
	v_mfma_f32_16x16x32_bf16 v[120:123], v[164:167], v[188:191], v[120:123]
	v_mfma_f32_16x16x32_bf16 v[108:111], v[156:159], v[196:199], v[108:111]
	v_mfma_f32_16x16x32_bf16 v[104:107], v[164:167], v[196:199], v[104:107]
	v_mfma_f32_16x16x32_bf16 v[92:95], v[156:159], v[204:207], v[92:95]
	v_mfma_f32_16x16x32_bf16 v[88:91], v[164:167], v[204:207], v[88:91]
	v_mfma_f32_16x16x32_bf16 v[76:79], v[156:159], v[212:215], v[76:79]
	v_mfma_f32_16x16x32_bf16 v[72:75], v[164:167], v[212:215], v[72:75]
	v_mfma_f32_16x16x32_bf16 v[116:119], v[168:171], v[184:187], v[116:119]
	v_mfma_f32_16x16x32_bf16 v[112:115], v[176:179], v[184:187], v[112:115]
	v_mfma_f32_16x16x32_bf16 v[100:103], v[168:171], v[192:195], v[100:103]
	v_mfma_f32_16x16x32_bf16 v[96:99], v[176:179], v[192:195], v[96:99]
	v_mfma_f32_16x16x32_bf16 v[84:87], v[168:171], v[200:203], v[84:87]
	v_mfma_f32_16x16x32_bf16 v[80:83], v[176:179], v[200:203], v[80:83]
	v_mfma_f32_16x16x32_bf16 v[68:71], v[168:171], v[208:211], v[68:71]
	v_mfma_f32_16x16x32_bf16 v[64:67], v[176:179], v[208:211], v[64:67]
	v_mfma_f32_16x16x32_bf16 v[116:119], v[172:175], v[188:191], v[116:119]
	v_mfma_f32_16x16x32_bf16 v[112:115], v[180:183], v[188:191], v[112:115]
	v_mfma_f32_16x16x32_bf16 v[100:103], v[172:175], v[196:199], v[100:103]
	v_mfma_f32_16x16x32_bf16 v[96:99], v[180:183], v[196:199], v[96:99]
	v_mfma_f32_16x16x32_bf16 v[84:87], v[172:175], v[204:207], v[84:87]
	v_mfma_f32_16x16x32_bf16 v[80:83], v[180:183], v[204:207], v[80:83]
	v_mfma_f32_16x16x32_bf16 v[68:71], v[172:175], v[212:215], v[68:71]
	v_mfma_f32_16x16x32_bf16 v[64:67], v[180:183], v[212:215], v[64:67]
	s_barrier
	s_setprio 0
	s_add_i32 s44, s44, s33
	v_lshl_add_u64 v[148:149], v[148:149], 0, s[22:23]
	s_mov_b32 m0, s44
	ds_read_b128 v[184:187], v155 offset:49152
	ds_read_b128 v[188:191], v155 offset:50176
	ds_read_b128 v[192:195], v155 offset:51200
	ds_read_b128 v[196:199], v155 offset:52224
	ds_read_b128 v[200:203], v155 offset:53248
	ds_read_b128 v[204:207], v155 offset:54272
	ds_read_b128 v[208:211], v155 offset:55296
	ds_read_b128 v[212:215], v155 offset:56320
	global_load_lds_dwordx4 v[148:149], off
	s_add_i32 m0, s44, 0x2000
	s_add_u32 s44, s48, 0x20080
	v_lshl_add_u64 v[148:149], v[216:217], 0, s[22:23]
	s_addc_u32 s45, s49, 0
	s_add_i32 s48, s68, s33
	global_load_lds_dwordx4 v[148:149], off
	s_mov_b32 m0, s48
	v_lshl_add_u64 v[148:149], s[44:45], 0, v[132:133]
	global_load_lds_dwordx4 v[148:149], off
	s_add_i32 m0, s48, 0x2000
	v_lshl_add_u64 v[148:149], s[44:45], 0, v[128:129]
	global_load_lds_dwordx4 v[148:149], off
	s_mov_b32 m0, s57
	v_lshl_add_u64 v[148:149], v[220:221], 0, s[22:23]
	global_load_lds_dwordx4 v[148:149], off
	s_mov_b32 m0, s58
	v_lshl_add_u64 v[148:149], v[224:225], 0, s[24:25]
	global_load_lds_dwordx4 v[148:149], off
	s_setprio 1
	s_waitcnt vmcnt(8) lgkmcnt(0)
	s_barrier
	v_mfma_f32_16x16x32_bf16 v[60:63], v[144:147], v[184:187], v[60:63]
	v_mfma_f32_16x16x32_bf16 v[56:59], v[160:163], v[184:187], v[56:59]
	v_mfma_f32_16x16x32_bf16 v[44:47], v[144:147], v[192:195], v[44:47]
	v_mfma_f32_16x16x32_bf16 v[40:43], v[160:163], v[192:195], v[40:43]
	v_mfma_f32_16x16x32_bf16 v[28:31], v[144:147], v[200:203], v[28:31]
	v_mfma_f32_16x16x32_bf16 v[24:27], v[160:163], v[200:203], v[24:27]
	v_mfma_f32_16x16x32_bf16 v[12:15], v[144:147], v[208:211], v[12:15]
	v_mfma_f32_16x16x32_bf16 v[8:11], v[160:163], v[208:211], v[8:11]
	v_mfma_f32_16x16x32_bf16 v[60:63], v[156:159], v[188:191], v[60:63]
	v_mfma_f32_16x16x32_bf16 v[56:59], v[164:167], v[188:191], v[56:59]
	v_mfma_f32_16x16x32_bf16 v[44:47], v[156:159], v[196:199], v[44:47]
	v_mfma_f32_16x16x32_bf16 v[40:43], v[164:167], v[196:199], v[40:43]
	v_mfma_f32_16x16x32_bf16 v[28:31], v[156:159], v[204:207], v[28:31]
	v_mfma_f32_16x16x32_bf16 v[24:27], v[164:167], v[204:207], v[24:27]
	v_mfma_f32_16x16x32_bf16 v[12:15], v[156:159], v[212:215], v[12:15]
	v_mfma_f32_16x16x32_bf16 v[8:11], v[164:167], v[212:215], v[8:11]
	v_mfma_f32_16x16x32_bf16 v[52:55], v[168:171], v[184:187], v[52:55]
	v_mfma_f32_16x16x32_bf16 v[48:51], v[176:179], v[184:187], v[48:51]
	v_mfma_f32_16x16x32_bf16 v[36:39], v[168:171], v[192:195], v[36:39]
	v_mfma_f32_16x16x32_bf16 v[32:35], v[176:179], v[192:195], v[32:35]
	v_mfma_f32_16x16x32_bf16 v[20:23], v[168:171], v[200:203], v[20:23]
	v_mfma_f32_16x16x32_bf16 v[16:19], v[176:179], v[200:203], v[16:19]
	v_mfma_f32_16x16x32_bf16 v[4:7], v[168:171], v[208:211], v[4:7]
	v_mfma_f32_16x16x32_bf16 v[0:3], v[176:179], v[208:211], v[0:3]
	v_mfma_f32_16x16x32_bf16 v[52:55], v[172:175], v[188:191], v[52:55]
	v_mfma_f32_16x16x32_bf16 v[48:51], v[180:183], v[188:191], v[48:51]
	v_mfma_f32_16x16x32_bf16 v[36:39], v[172:175], v[196:199], v[36:39]
	v_mfma_f32_16x16x32_bf16 v[32:35], v[180:183], v[196:199], v[32:35]
	v_mfma_f32_16x16x32_bf16 v[20:23], v[172:175], v[204:207], v[20:23]
	v_mfma_f32_16x16x32_bf16 v[16:19], v[180:183], v[204:207], v[16:19]
	v_mfma_f32_16x16x32_bf16 v[4:7], v[172:175], v[212:215], v[4:7]
	v_mfma_f32_16x16x32_bf16 v[0:3], v[180:183], v[212:215], v[0:3]
	s_barrier
	s_setprio 0
	s_add_i32 s74, s74, 2
	s_add_u32 s51, s51, 0x100
	s_addc_u32 s73, s73, 0
	s_cmp_gt_u32 s74, 5
	s_mov_b64 s[44:45], s[46:47]
.LBB0_393:
	ds_read_b128 v[144:147], v153
	ds_read_b128 v[156:159], v153 offset:1024
	ds_read_b128 v[160:163], v153 offset:2048
	ds_read_b128 v[164:167], v153 offset:3072
	ds_read_b128 v[168:171], v154
	ds_read_b128 v[172:175], v154 offset:1024
	ds_read_b128 v[176:179], v154 offset:2048
	ds_read_b128 v[180:183], v154 offset:3072
	s_add_u32 s46, s44, 0x100
	s_addc_u32 s47, s45, 0
	s_cmp_eq_u32 s74, 4
	s_cselect_b32 s77, s67, s47
	s_cselect_b32 s76, s72, s46
	s_cselect_b32 s49, s39, s73
	s_cselect_b32 s48, s50, s51
	v_lshl_add_u64 v[148:149], s[44:45], 0, v[136:137]
	s_add_i32 m0, s52, 0xc000
	ds_read_b128 v[184:187], v155
	ds_read_b128 v[188:191], v155 offset:1024
	ds_read_b128 v[192:195], v155 offset:2048
	ds_read_b128 v[196:199], v155 offset:3072
	ds_read_b128 v[200:203], v155 offset:4096
	ds_read_b128 v[204:207], v155 offset:5120
	ds_read_b128 v[208:211], v155 offset:6144
	ds_read_b128 v[212:215], v155 offset:7168
	global_load_lds_dwordx4 v[148:149], off
	s_add_i32 m0, s52, 0xe000
	v_lshl_add_u64 v[148:149], s[44:45], 0, v[138:139]
	global_load_lds_dwordx4 v[148:149], off
	s_setprio 1
	s_waitcnt vmcnt(8) lgkmcnt(0)
	s_barrier
	v_mfma_f32_16x16x32_bf16 v[124:127], v[144:147], v[184:187], v[124:127]
	v_mfma_f32_16x16x32_bf16 v[120:123], v[160:163], v[184:187], v[120:123]
	v_mfma_f32_16x16x32_bf16 v[108:111], v[144:147], v[192:195], v[108:111]
	v_mfma_f32_16x16x32_bf16 v[104:107], v[160:163], v[192:195], v[104:107]
	v_mfma_f32_16x16x32_bf16 v[92:95], v[144:147], v[200:203], v[92:95]
	v_mfma_f32_16x16x32_bf16 v[88:91], v[160:163], v[200:203], v[88:91]
	v_mfma_f32_16x16x32_bf16 v[76:79], v[144:147], v[208:211], v[76:79]
	v_mfma_f32_16x16x32_bf16 v[72:75], v[160:163], v[208:211], v[72:75]
	v_mfma_f32_16x16x32_bf16 v[124:127], v[156:159], v[188:191], v[124:127]
	v_mfma_f32_16x16x32_bf16 v[120:123], v[164:167], v[188:191], v[120:123]
	v_mfma_f32_16x16x32_bf16 v[108:111], v[156:159], v[196:199], v[108:111]
	v_mfma_f32_16x16x32_bf16 v[104:107], v[164:167], v[196:199], v[104:107]
	v_mfma_f32_16x16x32_bf16 v[92:95], v[156:159], v[204:207], v[92:95]
	v_mfma_f32_16x16x32_bf16 v[88:91], v[164:167], v[204:207], v[88:91]
	v_mfma_f32_16x16x32_bf16 v[76:79], v[156:159], v[212:215], v[76:79]
	v_mfma_f32_16x16x32_bf16 v[72:75], v[164:167], v[212:215], v[72:75]
	v_mfma_f32_16x16x32_bf16 v[116:119], v[168:171], v[184:187], v[116:119]
	v_mfma_f32_16x16x32_bf16 v[112:115], v[176:179], v[184:187], v[112:115]
	v_mfma_f32_16x16x32_bf16 v[100:103], v[168:171], v[192:195], v[100:103]
	v_mfma_f32_16x16x32_bf16 v[96:99], v[176:179], v[192:195], v[96:99]
	v_mfma_f32_16x16x32_bf16 v[84:87], v[168:171], v[200:203], v[84:87]
	v_mfma_f32_16x16x32_bf16 v[80:83], v[176:179], v[200:203], v[80:83]
	v_mfma_f32_16x16x32_bf16 v[68:71], v[168:171], v[208:211], v[68:71]
	v_mfma_f32_16x16x32_bf16 v[64:67], v[176:179], v[208:211], v[64:67]
	v_mfma_f32_16x16x32_bf16 v[116:119], v[172:175], v[188:191], v[116:119]
	v_mfma_f32_16x16x32_bf16 v[112:115], v[180:183], v[188:191], v[112:115]
	v_mfma_f32_16x16x32_bf16 v[100:103], v[172:175], v[196:199], v[100:103]
	v_mfma_f32_16x16x32_bf16 v[96:99], v[180:183], v[196:199], v[96:99]
	v_mfma_f32_16x16x32_bf16 v[84:87], v[172:175], v[204:207], v[84:87]
	v_mfma_f32_16x16x32_bf16 v[80:83], v[180:183], v[204:207], v[80:83]
	v_mfma_f32_16x16x32_bf16 v[68:71], v[172:175], v[212:215], v[68:71]
	v_mfma_f32_16x16x32_bf16 v[64:67], v[180:183], v[212:215], v[64:67]
	s_barrier
	s_setprio 0
	s_add_i32 s44, s61, s33
	v_lshl_add_u64 v[148:149], s[48:49], 0, v[132:133]
	s_mov_b32 m0, s44
	ds_read_b128 v[184:187], v155 offset:16384
	ds_read_b128 v[188:191], v155 offset:17408
	ds_read_b128 v[192:195], v155 offset:18432
	ds_read_b128 v[196:199], v155 offset:19456
	ds_read_b128 v[200:203], v155 offset:20480
	ds_read_b128 v[204:207], v155 offset:21504
	ds_read_b128 v[208:211], v155 offset:22528
	ds_read_b128 v[212:215], v155 offset:23552
	global_load_lds_dwordx4 v[148:149], off
	s_add_i32 m0, s44, 0x2000
	s_add_u32 s44, s48, 0x20000
	v_lshl_add_u64 v[216:217], s[48:49], 0, v[128:129]
	s_addc_u32 s45, s49, 0
	s_add_i32 s68, s62, s33
	global_load_lds_dwordx4 v[216:217], off
	v_lshl_add_u64 v[220:221], s[44:45], 0, v[132:133]
	s_mov_b32 m0, s68
	v_lshl_add_u64 v[224:225], s[76:77], 0, v[130:131]
	global_load_lds_dwordx4 v[220:221], off
	v_lshl_add_u64 v[220:221], s[44:45], 0, v[128:129]
	s_add_i32 m0, s68, 0x2000
	v_lshl_add_u64 v[226:227], v[224:225], 0, s[8:9]
	global_load_lds_dwordx4 v[220:221], off
	s_mov_b32 m0, s52
	v_lshl_add_u64 v[220:221], s[76:77], 0, v[134:135]
	global_load_lds_dwordx4 v[220:221], off
	s_mov_b32 m0, s53
	s_nop 0
	global_load_lds_dwordx4 v[226:227], off
	s_setprio 1
	s_waitcnt vmcnt(8) lgkmcnt(0)
	s_barrier
	v_mfma_f32_16x16x32_bf16 v[60:63], v[144:147], v[184:187], v[60:63]
	v_mfma_f32_16x16x32_bf16 v[56:59], v[160:163], v[184:187], v[56:59]
	v_mfma_f32_16x16x32_bf16 v[44:47], v[144:147], v[192:195], v[44:47]
	v_mfma_f32_16x16x32_bf16 v[40:43], v[160:163], v[192:195], v[40:43]
	v_mfma_f32_16x16x32_bf16 v[28:31], v[144:147], v[200:203], v[28:31]
	v_mfma_f32_16x16x32_bf16 v[24:27], v[160:163], v[200:203], v[24:27]
	v_mfma_f32_16x16x32_bf16 v[12:15], v[144:147], v[208:211], v[12:15]
	v_mfma_f32_16x16x32_bf16 v[8:11], v[160:163], v[208:211], v[8:11]
	v_mfma_f32_16x16x32_bf16 v[60:63], v[156:159], v[188:191], v[60:63]
	v_mfma_f32_16x16x32_bf16 v[56:59], v[164:167], v[188:191], v[56:59]
	v_mfma_f32_16x16x32_bf16 v[44:47], v[156:159], v[196:199], v[44:47]
	v_mfma_f32_16x16x32_bf16 v[40:43], v[164:167], v[196:199], v[40:43]
	v_mfma_f32_16x16x32_bf16 v[28:31], v[156:159], v[204:207], v[28:31]
	v_mfma_f32_16x16x32_bf16 v[24:27], v[164:167], v[204:207], v[24:27]
	v_mfma_f32_16x16x32_bf16 v[12:15], v[156:159], v[212:215], v[12:15]
	v_mfma_f32_16x16x32_bf16 v[8:11], v[164:167], v[212:215], v[8:11]
	v_mfma_f32_16x16x32_bf16 v[52:55], v[168:171], v[184:187], v[52:55]
	v_mfma_f32_16x16x32_bf16 v[48:51], v[176:179], v[184:187], v[48:51]
	v_mfma_f32_16x16x32_bf16 v[36:39], v[168:171], v[192:195], v[36:39]
	v_mfma_f32_16x16x32_bf16 v[32:35], v[176:179], v[192:195], v[32:35]
	v_mfma_f32_16x16x32_bf16 v[20:23], v[168:171], v[200:203], v[20:23]
	v_mfma_f32_16x16x32_bf16 v[16:19], v[176:179], v[200:203], v[16:19]
	v_mfma_f32_16x16x32_bf16 v[4:7], v[168:171], v[208:211], v[4:7]
	v_mfma_f32_16x16x32_bf16 v[0:3], v[176:179], v[208:211], v[0:3]
	v_mfma_f32_16x16x32_bf16 v[52:55], v[172:175], v[188:191], v[52:55]
	v_mfma_f32_16x16x32_bf16 v[48:51], v[180:183], v[188:191], v[48:51]
	v_mfma_f32_16x16x32_bf16 v[36:39], v[172:175], v[196:199], v[36:39]
	v_mfma_f32_16x16x32_bf16 v[32:35], v[180:183], v[196:199], v[32:35]
	v_mfma_f32_16x16x32_bf16 v[20:23], v[172:175], v[204:207], v[20:23]
	v_mfma_f32_16x16x32_bf16 v[16:19], v[180:183], v[204:207], v[16:19]
	v_mfma_f32_16x16x32_bf16 v[4:7], v[172:175], v[212:215], v[4:7]
	v_mfma_f32_16x16x32_bf16 v[0:3], v[180:183], v[212:215], v[0:3]
	s_barrier
	s_setprio 0
	s_add_i32 s44, 0, 0x18000
	s_add_i32 s68, 0, 0x1c000
	v_add_u32_e32 v164, s44, v151
	v_add_u32_e32 v180, s68, v151
	ds_read_b128 v[144:147], v164
	ds_read_b128 v[156:159], v164 offset:1024
	ds_read_b128 v[160:163], v164 offset:2048
	ds_read_b128 v[164:167], v164 offset:3072
	ds_read_b128 v[168:171], v180
	ds_read_b128 v[172:175], v180 offset:1024
	ds_read_b128 v[176:179], v180 offset:2048
	ds_read_b128 v[180:183], v180 offset:3072
	s_mov_b32 m0, s54
	v_lshl_add_u64 v[226:227], v[220:221], 0, s[6:7]
	ds_read_b128 v[184:187], v155 offset:32768
	ds_read_b128 v[188:191], v155 offset:33792
	ds_read_b128 v[192:195], v155 offset:34816
	ds_read_b128 v[196:199], v155 offset:35840
	ds_read_b128 v[200:203], v155 offset:36864
	ds_read_b128 v[204:207], v155 offset:37888
	ds_read_b128 v[208:211], v155 offset:38912
	ds_read_b128 v[212:215], v155 offset:39936
	global_load_lds_dwordx4 v[226:227], off
	s_mov_b32 m0, s55
	v_lshl_add_u64 v[226:227], v[224:225], 0, s[12:13]
	global_load_lds_dwordx4 v[226:227], off
	s_setprio 1
	s_waitcnt vmcnt(8) lgkmcnt(0)
	s_barrier
	v_mfma_f32_16x16x32_bf16 v[124:127], v[144:147], v[184:187], v[124:127]
	v_mfma_f32_16x16x32_bf16 v[120:123], v[160:163], v[184:187], v[120:123]
	v_mfma_f32_16x16x32_bf16 v[108:111], v[144:147], v[192:195], v[108:111]
	v_mfma_f32_16x16x32_bf16 v[104:107], v[160:163], v[192:195], v[104:107]
	v_mfma_f32_16x16x32_bf16 v[92:95], v[144:147], v[200:203], v[92:95]
	v_mfma_f32_16x16x32_bf16 v[88:91], v[160:163], v[200:203], v[88:91]
	v_mfma_f32_16x16x32_bf16 v[76:79], v[144:147], v[208:211], v[76:79]
	v_mfma_f32_16x16x32_bf16 v[72:75], v[160:163], v[208:211], v[72:75]
	v_mfma_f32_16x16x32_bf16 v[124:127], v[156:159], v[188:191], v[124:127]
	v_mfma_f32_16x16x32_bf16 v[120:123], v[164:167], v[188:191], v[120:123]
	v_mfma_f32_16x16x32_bf16 v[108:111], v[156:159], v[196:199], v[108:111]
	v_mfma_f32_16x16x32_bf16 v[104:107], v[164:167], v[196:199], v[104:107]
	v_mfma_f32_16x16x32_bf16 v[92:95], v[156:159], v[204:207], v[92:95]
	v_mfma_f32_16x16x32_bf16 v[88:91], v[164:167], v[204:207], v[88:91]
	v_mfma_f32_16x16x32_bf16 v[76:79], v[156:159], v[212:215], v[76:79]
	v_mfma_f32_16x16x32_bf16 v[72:75], v[164:167], v[212:215], v[72:75]
	v_mfma_f32_16x16x32_bf16 v[116:119], v[168:171], v[184:187], v[116:119]
	v_mfma_f32_16x16x32_bf16 v[112:115], v[176:179], v[184:187], v[112:115]
	v_mfma_f32_16x16x32_bf16 v[100:103], v[168:171], v[192:195], v[100:103]
	v_mfma_f32_16x16x32_bf16 v[96:99], v[176:179], v[192:195], v[96:99]
	v_mfma_f32_16x16x32_bf16 v[84:87], v[168:171], v[200:203], v[84:87]
	v_mfma_f32_16x16x32_bf16 v[80:83], v[176:179], v[200:203], v[80:83]
	v_mfma_f32_16x16x32_bf16 v[68:71], v[168:171], v[208:211], v[68:71]
	v_mfma_f32_16x16x32_bf16 v[64:67], v[176:179], v[208:211], v[64:67]
	v_mfma_f32_16x16x32_bf16 v[116:119], v[172:175], v[188:191], v[116:119]
	v_mfma_f32_16x16x32_bf16 v[112:115], v[180:183], v[188:191], v[112:115]
	v_mfma_f32_16x16x32_bf16 v[100:103], v[172:175], v[196:199], v[100:103]
	v_mfma_f32_16x16x32_bf16 v[96:99], v[180:183], v[196:199], v[96:99]
	v_mfma_f32_16x16x32_bf16 v[84:87], v[172:175], v[204:207], v[84:87]
	v_mfma_f32_16x16x32_bf16 v[80:83], v[180:183], v[204:207], v[80:83]
	v_mfma_f32_16x16x32_bf16 v[68:71], v[172:175], v[212:215], v[68:71]
	v_mfma_f32_16x16x32_bf16 v[64:67], v[180:183], v[212:215], v[64:67]
	s_barrier
	s_setprio 0
	s_add_i32 s44, s44, s33
	v_lshl_add_u64 v[148:149], v[148:149], 0, s[22:23]
	s_mov_b32 m0, s44
	ds_read_b128 v[184:187], v155 offset:49152
	ds_read_b128 v[188:191], v155 offset:50176
	ds_read_b128 v[192:195], v155 offset:51200
	ds_read_b128 v[196:199], v155 offset:52224
	ds_read_b128 v[200:203], v155 offset:53248
	ds_read_b128 v[204:207], v155 offset:54272
	ds_read_b128 v[208:211], v155 offset:55296
	ds_read_b128 v[212:215], v155 offset:56320
	global_load_lds_dwordx4 v[148:149], off
	s_add_i32 m0, s44, 0x2000
	s_add_u32 s44, s48, 0x20080
	v_lshl_add_u64 v[148:149], v[216:217], 0, s[22:23]
	s_addc_u32 s45, s49, 0
	s_add_i32 s48, s68, s33
	global_load_lds_dwordx4 v[148:149], off
	s_mov_b32 m0, s48
	v_lshl_add_u64 v[148:149], s[44:45], 0, v[132:133]
	global_load_lds_dwordx4 v[148:149], off
	s_add_i32 m0, s48, 0x2000
	v_lshl_add_u64 v[148:149], s[44:45], 0, v[128:129]
	global_load_lds_dwordx4 v[148:149], off
	s_mov_b32 m0, s57
	v_lshl_add_u64 v[148:149], v[220:221], 0, s[22:23]
	global_load_lds_dwordx4 v[148:149], off
	s_mov_b32 m0, s58
	v_lshl_add_u64 v[148:149], v[224:225], 0, s[24:25]
	global_load_lds_dwordx4 v[148:149], off
	s_setprio 1
	s_waitcnt vmcnt(8) lgkmcnt(0)
	s_barrier
	v_mfma_f32_16x16x32_bf16 v[60:63], v[144:147], v[184:187], v[60:63]
	v_mfma_f32_16x16x32_bf16 v[56:59], v[160:163], v[184:187], v[56:59]
	v_mfma_f32_16x16x32_bf16 v[44:47], v[144:147], v[192:195], v[44:47]
	v_mfma_f32_16x16x32_bf16 v[40:43], v[160:163], v[192:195], v[40:43]
	v_mfma_f32_16x16x32_bf16 v[28:31], v[144:147], v[200:203], v[28:31]
	v_mfma_f32_16x16x32_bf16 v[24:27], v[160:163], v[200:203], v[24:27]
	v_mfma_f32_16x16x32_bf16 v[12:15], v[144:147], v[208:211], v[12:15]
	v_mfma_f32_16x16x32_bf16 v[8:11], v[160:163], v[208:211], v[8:11]
	v_mfma_f32_16x16x32_bf16 v[60:63], v[156:159], v[188:191], v[60:63]
	v_mfma_f32_16x16x32_bf16 v[56:59], v[164:167], v[188:191], v[56:59]
	v_mfma_f32_16x16x32_bf16 v[44:47], v[156:159], v[196:199], v[44:47]
	v_mfma_f32_16x16x32_bf16 v[40:43], v[164:167], v[196:199], v[40:43]
	v_mfma_f32_16x16x32_bf16 v[28:31], v[156:159], v[204:207], v[28:31]
	v_mfma_f32_16x16x32_bf16 v[24:27], v[164:167], v[204:207], v[24:27]
	v_mfma_f32_16x16x32_bf16 v[12:15], v[156:159], v[212:215], v[12:15]
	v_mfma_f32_16x16x32_bf16 v[8:11], v[164:167], v[212:215], v[8:11]
	v_mfma_f32_16x16x32_bf16 v[52:55], v[168:171], v[184:187], v[52:55]
	v_mfma_f32_16x16x32_bf16 v[48:51], v[176:179], v[184:187], v[48:51]
	v_mfma_f32_16x16x32_bf16 v[36:39], v[168:171], v[192:195], v[36:39]
	v_mfma_f32_16x16x32_bf16 v[32:35], v[176:179], v[192:195], v[32:35]
	v_mfma_f32_16x16x32_bf16 v[20:23], v[168:171], v[200:203], v[20:23]
	v_mfma_f32_16x16x32_bf16 v[16:19], v[176:179], v[200:203], v[16:19]
	v_mfma_f32_16x16x32_bf16 v[4:7], v[168:171], v[208:211], v[4:7]
	v_mfma_f32_16x16x32_bf16 v[0:3], v[176:179], v[208:211], v[0:3]
	v_mfma_f32_16x16x32_bf16 v[52:55], v[172:175], v[188:191], v[52:55]
	v_mfma_f32_16x16x32_bf16 v[48:51], v[180:183], v[188:191], v[48:51]
	v_mfma_f32_16x16x32_bf16 v[36:39], v[172:175], v[196:199], v[36:39]
	v_mfma_f32_16x16x32_bf16 v[32:35], v[180:183], v[196:199], v[32:35]
	v_mfma_f32_16x16x32_bf16 v[20:23], v[172:175], v[204:207], v[20:23]
	v_mfma_f32_16x16x32_bf16 v[16:19], v[180:183], v[204:207], v[16:19]
	v_mfma_f32_16x16x32_bf16 v[4:7], v[172:175], v[212:215], v[4:7]
	v_mfma_f32_16x16x32_bf16 v[0:3], v[180:183], v[212:215], v[0:3]
	s_barrier
	s_setprio 0
	s_add_i32 s74, s74, 2
	s_add_u32 s51, s51, 0x100
	s_addc_u32 s73, s73, 0
	s_cmp_gt_u32 s74, 5
	s_mov_b64 s[44:45], s[46:47]
	s_cbranch_scc0 .LBB0_393
	s_and_b64 vcc, exec, s[36:37]
	s_cbranch_vccz .LBB0_396
	s_barrier

.LBB0_465:
	s_lshl_b32 s42, s73, 8
	s_ashr_i32 s43, s42, 31
	s_lshl_b64 s[42:43], s[42:43], 11
	s_add_u32 s42, s10, s42
	s_addc_u32 s43, s11, s43
	s_and_b64 s[44:45], s[4:5], exec
	s_cselect_b32 s47, s43, s49
	s_cselect_b32 s74, s42, s48
	s_ashr_i32 s41, s40, 31
	s_lshl_b64 s[44:45], s[40:41], 19
	s_add_u32 s44, s33, s44
	s_addc_u32 s45, s34, s45
	s_and_b64 s[50:51], s[4:5], exec
	s_cselect_b32 s41, s45, s53
	s_cselect_b32 s50, s44, s52
	s_add_u32 s51, s52, 0x100
	s_addc_u32 s75, s53, 0
	s_mov_b32 s76, -2
	s_waitcnt lgkmcnt(0)
	s_waitcnt vmcnt(0)
	s_waitcnt lgkmcnt(0)
	ds_read_b128 v[144:147], v151
	ds_read_b128 v[156:159], v151 offset:1024
	ds_read_b128 v[160:163], v151 offset:2048
	ds_read_b128 v[164:167], v151 offset:3072
	ds_read_b128 v[168:171], v152
	ds_read_b128 v[172:175], v152 offset:1024
	ds_read_b128 v[176:179], v152 offset:2048
	ds_read_b128 v[180:183], v152 offset:3072
	s_add_u32 s52, s48, 0x100
	s_addc_u32 s53, s49, 0
	s_cmp_eq_u32 s76, 12
	s_cselect_b32 s79, s47, s53
	s_cselect_b32 s78, s74, s52
	s_cselect_b32 s55, s41, s75
	s_cselect_b32 s54, s50, s51
	v_lshl_add_u64 v[216:217], s[48:49], 0, v[136:137]
	s_add_i32 m0, s56, 0xc000
	ds_read_b128 v[184:187], v153
	ds_read_b128 v[188:191], v153 offset:1024
	ds_read_b128 v[192:195], v153 offset:2048
	ds_read_b128 v[196:199], v153 offset:3072
	ds_read_b128 v[200:203], v153 offset:4096
	ds_read_b128 v[204:207], v153 offset:5120
	ds_read_b128 v[208:211], v153 offset:6144
	ds_read_b128 v[212:215], v153 offset:7168
	global_load_lds_dwordx4 v[216:217], off
	s_add_i32 m0, s56, 0xe000
	v_lshl_add_u64 v[216:217], s[48:49], 0, v[138:139]
	global_load_lds_dwordx4 v[216:217], off
	s_setprio 1
	s_waitcnt vmcnt(8) lgkmcnt(0)
	s_barrier
	v_mfma_f32_16x16x32_bf16 v[124:127], v[144:147], v[184:187], 0
	v_mfma_f32_16x16x32_bf16 v[120:123], v[160:163], v[184:187], 0
	v_mfma_f32_16x16x32_bf16 v[108:111], v[144:147], v[192:195], 0
	v_mfma_f32_16x16x32_bf16 v[104:107], v[160:163], v[192:195], 0
	v_mfma_f32_16x16x32_bf16 v[92:95], v[144:147], v[200:203], 0
	v_mfma_f32_16x16x32_bf16 v[88:91], v[160:163], v[200:203], 0
	v_mfma_f32_16x16x32_bf16 v[76:79], v[144:147], v[208:211], 0
	v_mfma_f32_16x16x32_bf16 v[72:75], v[160:163], v[208:211], 0
	v_mfma_f32_16x16x32_bf16 v[124:127], v[156:159], v[188:191], v[124:127]
	v_mfma_f32_16x16x32_bf16 v[120:123], v[164:167], v[188:191], v[120:123]
	v_mfma_f32_16x16x32_bf16 v[108:111], v[156:159], v[196:199], v[108:111]
	v_mfma_f32_16x16x32_bf16 v[104:107], v[164:167], v[196:199], v[104:107]
	v_mfma_f32_16x16x32_bf16 v[92:95], v[156:159], v[204:207], v[92:95]
	v_mfma_f32_16x16x32_bf16 v[88:91], v[164:167], v[204:207], v[88:91]
	v_mfma_f32_16x16x32_bf16 v[76:79], v[156:159], v[212:215], v[76:79]
	v_mfma_f32_16x16x32_bf16 v[72:75], v[164:167], v[212:215], v[72:75]
	v_mfma_f32_16x16x32_bf16 v[116:119], v[168:171], v[184:187], 0
	v_mfma_f32_16x16x32_bf16 v[112:115], v[176:179], v[184:187], 0
	v_mfma_f32_16x16x32_bf16 v[100:103], v[168:171], v[192:195], 0
	v_mfma_f32_16x16x32_bf16 v[96:99], v[176:179], v[192:195], 0
	v_mfma_f32_16x16x32_bf16 v[84:87], v[168:171], v[200:203], 0
	v_mfma_f32_16x16x32_bf16 v[80:83], v[176:179], v[200:203], 0
	v_mfma_f32_16x16x32_bf16 v[68:71], v[168:171], v[208:211], 0
	v_mfma_f32_16x16x32_bf16 v[64:67], v[176:179], v[208:211], 0
	v_mfma_f32_16x16x32_bf16 v[116:119], v[172:175], v[188:191], v[116:119]
	v_mfma_f32_16x16x32_bf16 v[112:115], v[180:183], v[188:191], v[112:115]
	v_mfma_f32_16x16x32_bf16 v[100:103], v[172:175], v[196:199], v[100:103]
	v_mfma_f32_16x16x32_bf16 v[96:99], v[180:183], v[196:199], v[96:99]
	v_mfma_f32_16x16x32_bf16 v[84:87], v[172:175], v[204:207], v[84:87]
	v_mfma_f32_16x16x32_bf16 v[80:83], v[180:183], v[204:207], v[80:83]
	v_mfma_f32_16x16x32_bf16 v[68:71], v[172:175], v[212:215], v[68:71]
	v_mfma_f32_16x16x32_bf16 v[64:67], v[180:183], v[212:215], v[64:67]
	s_barrier
	s_setprio 0
	s_add_i32 s48, s67, s35
	v_lshl_add_u64 v[216:217], s[54:55], 0, v[130:131]
	s_mov_b32 m0, s48
	ds_read_b128 v[184:187], v153 offset:16384
	ds_read_b128 v[188:191], v153 offset:17408
	ds_read_b128 v[192:195], v153 offset:18432
	ds_read_b128 v[196:199], v153 offset:19456
	ds_read_b128 v[200:203], v153 offset:20480
	ds_read_b128 v[204:207], v153 offset:21504
	ds_read_b128 v[208:211], v153 offset:22528
	ds_read_b128 v[212:215], v153 offset:23552
	global_load_lds_dwordx4 v[216:217], off
	s_add_i32 m0, s48, 0x2000
	s_add_u32 s48, s54, 0x40000
	v_lshl_add_u64 v[220:221], s[54:55], 0, v[134:135]
	s_addc_u32 s49, s55, 0
	s_add_i32 s68, s72, s35
	global_load_lds_dwordx4 v[220:221], off
	v_lshl_add_u64 v[224:225], s[48:49], 0, v[130:131]
	s_mov_b32 m0, s68
	v_lshl_add_u64 v[226:227], s[78:79], 0, v[132:133]
	global_load_lds_dwordx4 v[224:225], off
	v_lshl_add_u64 v[224:225], s[48:49], 0, v[134:135]
	s_add_i32 m0, s68, 0x2000
	v_lshl_add_u64 v[228:229], v[226:227], 0, s[12:13]
	global_load_lds_dwordx4 v[224:225], off
	s_mov_b32 m0, s56
	v_lshl_add_u64 v[224:225], s[78:79], 0, v[128:129]
	global_load_lds_dwordx4 v[224:225], off
	s_mov_b32 m0, s57
	s_nop 0
	global_load_lds_dwordx4 v[228:229], off
	s_setprio 1
	s_waitcnt vmcnt(8) lgkmcnt(0)
	s_barrier
	v_mfma_f32_16x16x32_bf16 v[60:63], v[144:147], v[184:187], 0
	v_mfma_f32_16x16x32_bf16 v[56:59], v[160:163], v[184:187], 0
	v_mfma_f32_16x16x32_bf16 v[44:47], v[144:147], v[192:195], 0
	v_mfma_f32_16x16x32_bf16 v[40:43], v[160:163], v[192:195], 0
	v_mfma_f32_16x16x32_bf16 v[28:31], v[144:147], v[200:203], 0
	v_mfma_f32_16x16x32_bf16 v[24:27], v[160:163], v[200:203], 0
	v_mfma_f32_16x16x32_bf16 v[12:15], v[144:147], v[208:211], 0
	v_mfma_f32_16x16x32_bf16 v[8:11], v[160:163], v[208:211], 0
	v_mfma_f32_16x16x32_bf16 v[60:63], v[156:159], v[188:191], v[60:63]
	v_mfma_f32_16x16x32_bf16 v[56:59], v[164:167], v[188:191], v[56:59]
	v_mfma_f32_16x16x32_bf16 v[44:47], v[156:159], v[196:199], v[44:47]
	v_mfma_f32_16x16x32_bf16 v[40:43], v[164:167], v[196:199], v[40:43]
	v_mfma_f32_16x16x32_bf16 v[28:31], v[156:159], v[204:207], v[28:31]
	v_mfma_f32_16x16x32_bf16 v[24:27], v[164:167], v[204:207], v[24:27]
	v_mfma_f32_16x16x32_bf16 v[12:15], v[156:159], v[212:215], v[12:15]
	v_mfma_f32_16x16x32_bf16 v[8:11], v[164:167], v[212:215], v[8:11]
	v_mfma_f32_16x16x32_bf16 v[52:55], v[168:171], v[184:187], 0
	v_mfma_f32_16x16x32_bf16 v[48:51], v[176:179], v[184:187], 0
	v_mfma_f32_16x16x32_bf16 v[36:39], v[168:171], v[192:195], 0
	v_mfma_f32_16x16x32_bf16 v[32:35], v[176:179], v[192:195], 0
	v_mfma_f32_16x16x32_bf16 v[20:23], v[168:171], v[200:203], 0
	v_mfma_f32_16x16x32_bf16 v[16:19], v[176:179], v[200:203], 0
	v_mfma_f32_16x16x32_bf16 v[4:7], v[168:171], v[208:211], 0
	v_mfma_f32_16x16x32_bf16 v[0:3], v[176:179], v[208:211], 0
	v_mfma_f32_16x16x32_bf16 v[52:55], v[172:175], v[188:191], v[52:55]
	v_mfma_f32_16x16x32_bf16 v[48:51], v[180:183], v[188:191], v[48:51]
	v_mfma_f32_16x16x32_bf16 v[36:39], v[172:175], v[196:199], v[36:39]
	v_mfma_f32_16x16x32_bf16 v[32:35], v[180:183], v[196:199], v[32:35]
	v_mfma_f32_16x16x32_bf16 v[20:23], v[172:175], v[204:207], v[20:23]
	v_mfma_f32_16x16x32_bf16 v[16:19], v[180:183], v[204:207], v[16:19]
	v_mfma_f32_16x16x32_bf16 v[4:7], v[172:175], v[212:215], v[4:7]
	v_mfma_f32_16x16x32_bf16 v[0:3], v[180:183], v[212:215], v[0:3]
	s_barrier
	s_setprio 0
	s_add_i32 s48, 0, 0x18000
	v_add_u32_e32 v155, s48, v149
	s_add_i32 s68, 0, 0x1c000
	ds_read_b128 v[144:147], v155
	ds_read_b128 v[156:159], v155 offset:1024
	ds_read_b128 v[160:163], v155 offset:2048
	ds_read_b128 v[164:167], v155 offset:3072
	v_add_u32_e32 v155, s68, v149
	ds_read_b128 v[168:171], v155
	ds_read_b128 v[172:175], v155 offset:1024
	ds_read_b128 v[176:179], v155 offset:2048
	ds_read_b128 v[180:183], v155 offset:3072
	s_mov_b32 m0, s58
	v_lshl_add_u64 v[228:229], v[224:225], 0, s[8:9]
	ds_read_b128 v[184:187], v153 offset:32768
	ds_read_b128 v[188:191], v153 offset:33792
	ds_read_b128 v[192:195], v153 offset:34816
	ds_read_b128 v[196:199], v153 offset:35840
	ds_read_b128 v[200:203], v153 offset:36864
	ds_read_b128 v[204:207], v153 offset:37888
	ds_read_b128 v[208:211], v153 offset:38912
	ds_read_b128 v[212:215], v153 offset:39936
	global_load_lds_dwordx4 v[228:229], off
	s_mov_b32 m0, s59
	v_lshl_add_u64 v[228:229], v[226:227], 0, s[14:15]
	global_load_lds_dwordx4 v[228:229], off
	s_setprio 1
	s_waitcnt vmcnt(8) lgkmcnt(0)
	s_barrier
	v_mfma_f32_16x16x32_bf16 v[124:127], v[144:147], v[184:187], v[124:127]
	v_mfma_f32_16x16x32_bf16 v[120:123], v[160:163], v[184:187], v[120:123]
	v_mfma_f32_16x16x32_bf16 v[108:111], v[144:147], v[192:195], v[108:111]
	v_mfma_f32_16x16x32_bf16 v[104:107], v[160:163], v[192:195], v[104:107]
	v_mfma_f32_16x16x32_bf16 v[92:95], v[144:147], v[200:203], v[92:95]
	v_mfma_f32_16x16x32_bf16 v[88:91], v[160:163], v[200:203], v[88:91]
	v_mfma_f32_16x16x32_bf16 v[76:79], v[144:147], v[208:211], v[76:79]
	v_mfma_f32_16x16x32_bf16 v[72:75], v[160:163], v[208:211], v[72:75]
	v_mfma_f32_16x16x32_bf16 v[124:127], v[156:159], v[188:191], v[124:127]
	v_mfma_f32_16x16x32_bf16 v[120:123], v[164:167], v[188:191], v[120:123]
	v_mfma_f32_16x16x32_bf16 v[108:111], v[156:159], v[196:199], v[108:111]
	v_mfma_f32_16x16x32_bf16 v[104:107], v[164:167], v[196:199], v[104:107]
	v_mfma_f32_16x16x32_bf16 v[92:95], v[156:159], v[204:207], v[92:95]
	v_mfma_f32_16x16x32_bf16 v[88:91], v[164:167], v[204:207], v[88:91]
	v_mfma_f32_16x16x32_bf16 v[76:79], v[156:159], v[212:215], v[76:79]
	v_mfma_f32_16x16x32_bf16 v[72:75], v[164:167], v[212:215], v[72:75]
	v_mfma_f32_16x16x32_bf16 v[116:119], v[168:171], v[184:187], v[116:119]
	v_mfma_f32_16x16x32_bf16 v[112:115], v[176:179], v[184:187], v[112:115]
	v_mfma_f32_16x16x32_bf16 v[100:103], v[168:171], v[192:195], v[100:103]
	v_mfma_f32_16x16x32_bf16 v[96:99], v[176:179], v[192:195], v[96:99]
	v_mfma_f32_16x16x32_bf16 v[84:87], v[168:171], v[200:203], v[84:87]
	v_mfma_f32_16x16x32_bf16 v[80:83], v[176:179], v[200:203], v[80:83]
	v_mfma_f32_16x16x32_bf16 v[68:71], v[168:171], v[208:211], v[68:71]
	v_mfma_f32_16x16x32_bf16 v[64:67], v[176:179], v[208:211], v[64:67]
	v_mfma_f32_16x16x32_bf16 v[116:119], v[172:175], v[188:191], v[116:119]
	v_mfma_f32_16x16x32_bf16 v[112:115], v[180:183], v[188:191], v[112:115]
	v_mfma_f32_16x16x32_bf16 v[100:103], v[172:175], v[196:199], v[100:103]
	v_mfma_f32_16x16x32_bf16 v[96:99], v[180:183], v[196:199], v[96:99]
	v_mfma_f32_16x16x32_bf16 v[84:87], v[172:175], v[204:207], v[84:87]
	v_mfma_f32_16x16x32_bf16 v[80:83], v[180:183], v[204:207], v[80:83]
	v_mfma_f32_16x16x32_bf16 v[68:71], v[172:175], v[212:215], v[68:71]
	v_mfma_f32_16x16x32_bf16 v[64:67], v[180:183], v[212:215], v[64:67]
	s_barrier
	s_setprio 0
	s_add_i32 s48, s48, s35
	v_lshl_add_u64 v[216:217], v[216:217], 0, s[24:25]
	s_mov_b32 m0, s48
	ds_read_b128 v[184:187], v153 offset:49152
	ds_read_b128 v[188:191], v153 offset:50176
	ds_read_b128 v[192:195], v153 offset:51200
	ds_read_b128 v[196:199], v153 offset:52224
	ds_read_b128 v[200:203], v153 offset:53248
	ds_read_b128 v[204:207], v153 offset:54272
	ds_read_b128 v[208:211], v153 offset:55296
	ds_read_b128 v[212:215], v153 offset:56320
	global_load_lds_dwordx4 v[216:217], off
	s_add_i32 m0, s48, 0x2000
	s_add_u32 s48, s54, 0x40080
	v_lshl_add_u64 v[216:217], v[220:221], 0, s[24:25]
	s_addc_u32 s49, s55, 0
	s_add_i32 s54, s68, s35
	global_load_lds_dwordx4 v[216:217], off
	s_mov_b32 m0, s54
	v_lshl_add_u64 v[216:217], s[48:49], 0, v[130:131]
	global_load_lds_dwordx4 v[216:217], off
	s_add_i32 m0, s54, 0x2000
	v_lshl_add_u64 v[216:217], s[48:49], 0, v[134:135]
	global_load_lds_dwordx4 v[216:217], off
	s_mov_b32 m0, s61
	v_lshl_add_u64 v[216:217], v[224:225], 0, s[24:25]
	global_load_lds_dwordx4 v[216:217], off
	s_mov_b32 m0, s62
	v_lshl_add_u64 v[216:217], v[226:227], 0, s[36:37]
	global_load_lds_dwordx4 v[216:217], off
	s_setprio 1
	s_waitcnt vmcnt(8) lgkmcnt(0)
	s_barrier
	v_mfma_f32_16x16x32_bf16 v[60:63], v[144:147], v[184:187], v[60:63]
	v_mfma_f32_16x16x32_bf16 v[56:59], v[160:163], v[184:187], v[56:59]
	v_mfma_f32_16x16x32_bf16 v[44:47], v[144:147], v[192:195], v[44:47]
	v_mfma_f32_16x16x32_bf16 v[40:43], v[160:163], v[192:195], v[40:43]
	v_mfma_f32_16x16x32_bf16 v[28:31], v[144:147], v[200:203], v[28:31]
	v_mfma_f32_16x16x32_bf16 v[24:27], v[160:163], v[200:203], v[24:27]
	v_mfma_f32_16x16x32_bf16 v[12:15], v[144:147], v[208:211], v[12:15]
	v_mfma_f32_16x16x32_bf16 v[8:11], v[160:163], v[208:211], v[8:11]
	v_mfma_f32_16x16x32_bf16 v[60:63], v[156:159], v[188:191], v[60:63]
	v_mfma_f32_16x16x32_bf16 v[56:59], v[164:167], v[188:191], v[56:59]
	v_mfma_f32_16x16x32_bf16 v[44:47], v[156:159], v[196:199], v[44:47]
	v_mfma_f32_16x16x32_bf16 v[40:43], v[164:167], v[196:199], v[40:43]
	v_mfma_f32_16x16x32_bf16 v[28:31], v[156:159], v[204:207], v[28:31]
	v_mfma_f32_16x16x32_bf16 v[24:27], v[164:167], v[204:207], v[24:27]
	v_mfma_f32_16x16x32_bf16 v[12:15], v[156:159], v[212:215], v[12:15]
	v_mfma_f32_16x16x32_bf16 v[8:11], v[164:167], v[212:215], v[8:11]
	v_mfma_f32_16x16x32_bf16 v[52:55], v[168:171], v[184:187], v[52:55]
	v_mfma_f32_16x16x32_bf16 v[48:51], v[176:179], v[184:187], v[48:51]
	v_mfma_f32_16x16x32_bf16 v[36:39], v[168:171], v[192:195], v[36:39]
	v_mfma_f32_16x16x32_bf16 v[32:35], v[176:179], v[192:195], v[32:35]
	v_mfma_f32_16x16x32_bf16 v[20:23], v[168:171], v[200:203], v[20:23]
	v_mfma_f32_16x16x32_bf16 v[16:19], v[176:179], v[200:203], v[16:19]
	v_mfma_f32_16x16x32_bf16 v[4:7], v[168:171], v[208:211], v[4:7]
	v_mfma_f32_16x16x32_bf16 v[0:3], v[176:179], v[208:211], v[0:3]
	v_mfma_f32_16x16x32_bf16 v[52:55], v[172:175], v[188:191], v[52:55]
	v_mfma_f32_16x16x32_bf16 v[48:51], v[180:183], v[188:191], v[48:51]
	v_mfma_f32_16x16x32_bf16 v[36:39], v[172:175], v[196:199], v[36:39]
	v_mfma_f32_16x16x32_bf16 v[32:35], v[180:183], v[196:199], v[32:35]
	v_mfma_f32_16x16x32_bf16 v[20:23], v[172:175], v[204:207], v[20:23]
	v_mfma_f32_16x16x32_bf16 v[16:19], v[180:183], v[204:207], v[16:19]
	v_mfma_f32_16x16x32_bf16 v[4:7], v[172:175], v[212:215], v[4:7]
	v_mfma_f32_16x16x32_bf16 v[0:3], v[180:183], v[212:215], v[0:3]
	s_barrier
	s_setprio 0
	s_add_i32 s76, s76, 2
	s_add_u32 s51, s51, 0x100
	s_addc_u32 s75, s75, 0
	s_cmp_gt_u32 s76, 13
	s_mov_b64 s[48:49], s[52:53]
.LBB0_466:
	ds_read_b128 v[144:147], v151
	ds_read_b128 v[156:159], v151 offset:1024
	ds_read_b128 v[160:163], v151 offset:2048
	ds_read_b128 v[164:167], v151 offset:3072
	ds_read_b128 v[168:171], v152
	ds_read_b128 v[172:175], v152 offset:1024
	ds_read_b128 v[176:179], v152 offset:2048
	ds_read_b128 v[180:183], v152 offset:3072
	s_add_u32 s52, s48, 0x100
	s_addc_u32 s53, s49, 0
	s_cmp_eq_u32 s76, 12
	s_cselect_b32 s79, s47, s53
	s_cselect_b32 s78, s74, s52
	s_cselect_b32 s55, s41, s75
	s_cselect_b32 s54, s50, s51
	v_lshl_add_u64 v[216:217], s[48:49], 0, v[136:137]
	s_add_i32 m0, s56, 0xc000
	ds_read_b128 v[184:187], v153
	ds_read_b128 v[188:191], v153 offset:1024
	ds_read_b128 v[192:195], v153 offset:2048
	ds_read_b128 v[196:199], v153 offset:3072
	ds_read_b128 v[200:203], v153 offset:4096
	ds_read_b128 v[204:207], v153 offset:5120
	ds_read_b128 v[208:211], v153 offset:6144
	ds_read_b128 v[212:215], v153 offset:7168
	global_load_lds_dwordx4 v[216:217], off
	s_add_i32 m0, s56, 0xe000
	v_lshl_add_u64 v[216:217], s[48:49], 0, v[138:139]
	global_load_lds_dwordx4 v[216:217], off
	s_setprio 1
	s_waitcnt vmcnt(8) lgkmcnt(0)
	s_barrier
	v_mfma_f32_16x16x32_bf16 v[124:127], v[144:147], v[184:187], v[124:127]
	v_mfma_f32_16x16x32_bf16 v[120:123], v[160:163], v[184:187], v[120:123]
	v_mfma_f32_16x16x32_bf16 v[108:111], v[144:147], v[192:195], v[108:111]
	v_mfma_f32_16x16x32_bf16 v[104:107], v[160:163], v[192:195], v[104:107]
	v_mfma_f32_16x16x32_bf16 v[92:95], v[144:147], v[200:203], v[92:95]
	v_mfma_f32_16x16x32_bf16 v[88:91], v[160:163], v[200:203], v[88:91]
	v_mfma_f32_16x16x32_bf16 v[76:79], v[144:147], v[208:211], v[76:79]
	v_mfma_f32_16x16x32_bf16 v[72:75], v[160:163], v[208:211], v[72:75]
	v_mfma_f32_16x16x32_bf16 v[124:127], v[156:159], v[188:191], v[124:127]
	v_mfma_f32_16x16x32_bf16 v[120:123], v[164:167], v[188:191], v[120:123]
	v_mfma_f32_16x16x32_bf16 v[108:111], v[156:159], v[196:199], v[108:111]
	v_mfma_f32_16x16x32_bf16 v[104:107], v[164:167], v[196:199], v[104:107]
	v_mfma_f32_16x16x32_bf16 v[92:95], v[156:159], v[204:207], v[92:95]
	v_mfma_f32_16x16x32_bf16 v[88:91], v[164:167], v[204:207], v[88:91]
	v_mfma_f32_16x16x32_bf16 v[76:79], v[156:159], v[212:215], v[76:79]
	v_mfma_f32_16x16x32_bf16 v[72:75], v[164:167], v[212:215], v[72:75]
	v_mfma_f32_16x16x32_bf16 v[116:119], v[168:171], v[184:187], v[116:119]
	v_mfma_f32_16x16x32_bf16 v[112:115], v[176:179], v[184:187], v[112:115]
	v_mfma_f32_16x16x32_bf16 v[100:103], v[168:171], v[192:195], v[100:103]
	v_mfma_f32_16x16x32_bf16 v[96:99], v[176:179], v[192:195], v[96:99]
	v_mfma_f32_16x16x32_bf16 v[84:87], v[168:171], v[200:203], v[84:87]
	v_mfma_f32_16x16x32_bf16 v[80:83], v[176:179], v[200:203], v[80:83]
	v_mfma_f32_16x16x32_bf16 v[68:71], v[168:171], v[208:211], v[68:71]
	v_mfma_f32_16x16x32_bf16 v[64:67], v[176:179], v[208:211], v[64:67]
	v_mfma_f32_16x16x32_bf16 v[116:119], v[172:175], v[188:191], v[116:119]
	v_mfma_f32_16x16x32_bf16 v[112:115], v[180:183], v[188:191], v[112:115]
	v_mfma_f32_16x16x32_bf16 v[100:103], v[172:175], v[196:199], v[100:103]
	v_mfma_f32_16x16x32_bf16 v[96:99], v[180:183], v[196:199], v[96:99]
	v_mfma_f32_16x16x32_bf16 v[84:87], v[172:175], v[204:207], v[84:87]
	v_mfma_f32_16x16x32_bf16 v[80:83], v[180:183], v[204:207], v[80:83]
	v_mfma_f32_16x16x32_bf16 v[68:71], v[172:175], v[212:215], v[68:71]
	v_mfma_f32_16x16x32_bf16 v[64:67], v[180:183], v[212:215], v[64:67]
	s_barrier
	s_setprio 0
	s_add_i32 s48, s67, s35
	v_lshl_add_u64 v[216:217], s[54:55], 0, v[130:131]
	s_mov_b32 m0, s48
	ds_read_b128 v[184:187], v153 offset:16384
	ds_read_b128 v[188:191], v153 offset:17408
	ds_read_b128 v[192:195], v153 offset:18432
	ds_read_b128 v[196:199], v153 offset:19456
	ds_read_b128 v[200:203], v153 offset:20480
	ds_read_b128 v[204:207], v153 offset:21504
	ds_read_b128 v[208:211], v153 offset:22528
	ds_read_b128 v[212:215], v153 offset:23552
	global_load_lds_dwordx4 v[216:217], off
	s_add_i32 m0, s48, 0x2000
	s_add_u32 s48, s54, 0x40000
	v_lshl_add_u64 v[220:221], s[54:55], 0, v[134:135]
	s_addc_u32 s49, s55, 0
	s_add_i32 s68, s72, s35
	global_load_lds_dwordx4 v[220:221], off
	v_lshl_add_u64 v[224:225], s[48:49], 0, v[130:131]
	s_mov_b32 m0, s68
	v_lshl_add_u64 v[226:227], s[78:79], 0, v[132:133]
	global_load_lds_dwordx4 v[224:225], off
	v_lshl_add_u64 v[224:225], s[48:49], 0, v[134:135]
	s_add_i32 m0, s68, 0x2000
	v_lshl_add_u64 v[228:229], v[226:227], 0, s[12:13]
	global_load_lds_dwordx4 v[224:225], off
	s_mov_b32 m0, s56
	v_lshl_add_u64 v[224:225], s[78:79], 0, v[128:129]
	global_load_lds_dwordx4 v[224:225], off
	s_mov_b32 m0, s57
	s_nop 0
	global_load_lds_dwordx4 v[228:229], off
	s_setprio 1
	s_waitcnt vmcnt(8) lgkmcnt(0)
	s_barrier
	v_mfma_f32_16x16x32_bf16 v[60:63], v[144:147], v[184:187], v[60:63]
	v_mfma_f32_16x16x32_bf16 v[56:59], v[160:163], v[184:187], v[56:59]
	v_mfma_f32_16x16x32_bf16 v[44:47], v[144:147], v[192:195], v[44:47]
	v_mfma_f32_16x16x32_bf16 v[40:43], v[160:163], v[192:195], v[40:43]
	v_mfma_f32_16x16x32_bf16 v[28:31], v[144:147], v[200:203], v[28:31]
	v_mfma_f32_16x16x32_bf16 v[24:27], v[160:163], v[200:203], v[24:27]
	v_mfma_f32_16x16x32_bf16 v[12:15], v[144:147], v[208:211], v[12:15]
	v_mfma_f32_16x16x32_bf16 v[8:11], v[160:163], v[208:211], v[8:11]
	v_mfma_f32_16x16x32_bf16 v[60:63], v[156:159], v[188:191], v[60:63]
	v_mfma_f32_16x16x32_bf16 v[56:59], v[164:167], v[188:191], v[56:59]
	v_mfma_f32_16x16x32_bf16 v[44:47], v[156:159], v[196:199], v[44:47]
	v_mfma_f32_16x16x32_bf16 v[40:43], v[164:167], v[196:199], v[40:43]
	v_mfma_f32_16x16x32_bf16 v[28:31], v[156:159], v[204:207], v[28:31]
	v_mfma_f32_16x16x32_bf16 v[24:27], v[164:167], v[204:207], v[24:27]
	v_mfma_f32_16x16x32_bf16 v[12:15], v[156:159], v[212:215], v[12:15]
	v_mfma_f32_16x16x32_bf16 v[8:11], v[164:167], v[212:215], v[8:11]
	v_mfma_f32_16x16x32_bf16 v[52:55], v[168:171], v[184:187], v[52:55]
	v_mfma_f32_16x16x32_bf16 v[48:51], v[176:179], v[184:187], v[48:51]
	v_mfma_f32_16x16x32_bf16 v[36:39], v[168:171], v[192:195], v[36:39]
	v_mfma_f32_16x16x32_bf16 v[32:35], v[176:179], v[192:195], v[32:35]
	v_mfma_f32_16x16x32_bf16 v[20:23], v[168:171], v[200:203], v[20:23]
	v_mfma_f32_16x16x32_bf16 v[16:19], v[176:179], v[200:203], v[16:19]
	v_mfma_f32_16x16x32_bf16 v[4:7], v[168:171], v[208:211], v[4:7]
	v_mfma_f32_16x16x32_bf16 v[0:3], v[176:179], v[208:211], v[0:3]
	v_mfma_f32_16x16x32_bf16 v[52:55], v[172:175], v[188:191], v[52:55]
	v_mfma_f32_16x16x32_bf16 v[48:51], v[180:183], v[188:191], v[48:51]
	v_mfma_f32_16x16x32_bf16 v[36:39], v[172:175], v[196:199], v[36:39]
	v_mfma_f32_16x16x32_bf16 v[32:35], v[180:183], v[196:199], v[32:35]
	v_mfma_f32_16x16x32_bf16 v[20:23], v[172:175], v[204:207], v[20:23]
	v_mfma_f32_16x16x32_bf16 v[16:19], v[180:183], v[204:207], v[16:19]
	v_mfma_f32_16x16x32_bf16 v[4:7], v[172:175], v[212:215], v[4:7]
	v_mfma_f32_16x16x32_bf16 v[0:3], v[180:183], v[212:215], v[0:3]
	s_barrier
	s_setprio 0
	s_add_i32 s48, 0, 0x18000
	v_add_u32_e32 v155, s48, v149
	s_add_i32 s68, 0, 0x1c000
	ds_read_b128 v[144:147], v155
	ds_read_b128 v[156:159], v155 offset:1024
	ds_read_b128 v[160:163], v155 offset:2048
	ds_read_b128 v[164:167], v155 offset:3072
	v_add_u32_e32 v155, s68, v149
	ds_read_b128 v[168:171], v155
	ds_read_b128 v[172:175], v155 offset:1024
	ds_read_b128 v[176:179], v155 offset:2048
	ds_read_b128 v[180:183], v155 offset:3072
	s_mov_b32 m0, s58
	v_lshl_add_u64 v[228:229], v[224:225], 0, s[8:9]
	ds_read_b128 v[184:187], v153 offset:32768
	ds_read_b128 v[188:191], v153 offset:33792
	ds_read_b128 v[192:195], v153 offset:34816
	ds_read_b128 v[196:199], v153 offset:35840
	ds_read_b128 v[200:203], v153 offset:36864
	ds_read_b128 v[204:207], v153 offset:37888
	ds_read_b128 v[208:211], v153 offset:38912
	ds_read_b128 v[212:215], v153 offset:39936
	global_load_lds_dwordx4 v[228:229], off
	s_mov_b32 m0, s59
	v_lshl_add_u64 v[228:229], v[226:227], 0, s[14:15]
	global_load_lds_dwordx4 v[228:229], off
	s_setprio 1
	s_waitcnt vmcnt(8) lgkmcnt(0)
	s_barrier
	v_mfma_f32_16x16x32_bf16 v[124:127], v[144:147], v[184:187], v[124:127]
	v_mfma_f32_16x16x32_bf16 v[120:123], v[160:163], v[184:187], v[120:123]
	v_mfma_f32_16x16x32_bf16 v[108:111], v[144:147], v[192:195], v[108:111]
	v_mfma_f32_16x16x32_bf16 v[104:107], v[160:163], v[192:195], v[104:107]
	v_mfma_f32_16x16x32_bf16 v[92:95], v[144:147], v[200:203], v[92:95]
	v_mfma_f32_16x16x32_bf16 v[88:91], v[160:163], v[200:203], v[88:91]
	v_mfma_f32_16x16x32_bf16 v[76:79], v[144:147], v[208:211], v[76:79]
	v_mfma_f32_16x16x32_bf16 v[72:75], v[160:163], v[208:211], v[72:75]
	v_mfma_f32_16x16x32_bf16 v[124:127], v[156:159], v[188:191], v[124:127]
	v_mfma_f32_16x16x32_bf16 v[120:123], v[164:167], v[188:191], v[120:123]
	v_mfma_f32_16x16x32_bf16 v[108:111], v[156:159], v[196:199], v[108:111]
	v_mfma_f32_16x16x32_bf16 v[104:107], v[164:167], v[196:199], v[104:107]
	v_mfma_f32_16x16x32_bf16 v[92:95], v[156:159], v[204:207], v[92:95]
	v_mfma_f32_16x16x32_bf16 v[88:91], v[164:167], v[204:207], v[88:91]
	v_mfma_f32_16x16x32_bf16 v[76:79], v[156:159], v[212:215], v[76:79]
	v_mfma_f32_16x16x32_bf16 v[72:75], v[164:167], v[212:215], v[72:75]
	v_mfma_f32_16x16x32_bf16 v[116:119], v[168:171], v[184:187], v[116:119]
	v_mfma_f32_16x16x32_bf16 v[112:115], v[176:179], v[184:187], v[112:115]
	v_mfma_f32_16x16x32_bf16 v[100:103], v[168:171], v[192:195], v[100:103]
	v_mfma_f32_16x16x32_bf16 v[96:99], v[176:179], v[192:195], v[96:99]
	v_mfma_f32_16x16x32_bf16 v[84:87], v[168:171], v[200:203], v[84:87]
	v_mfma_f32_16x16x32_bf16 v[80:83], v[176:179], v[200:203], v[80:83]
	v_mfma_f32_16x16x32_bf16 v[68:71], v[168:171], v[208:211], v[68:71]
	v_mfma_f32_16x16x32_bf16 v[64:67], v[176:179], v[208:211], v[64:67]
	v_mfma_f32_16x16x32_bf16 v[116:119], v[172:175], v[188:191], v[116:119]
	v_mfma_f32_16x16x32_bf16 v[112:115], v[180:183], v[188:191], v[112:115]
	v_mfma_f32_16x16x32_bf16 v[100:103], v[172:175], v[196:199], v[100:103]
	v_mfma_f32_16x16x32_bf16 v[96:99], v[180:183], v[196:199], v[96:99]
	v_mfma_f32_16x16x32_bf16 v[84:87], v[172:175], v[204:207], v[84:87]
	v_mfma_f32_16x16x32_bf16 v[80:83], v[180:183], v[204:207], v[80:83]
	v_mfma_f32_16x16x32_bf16 v[68:71], v[172:175], v[212:215], v[68:71]
	v_mfma_f32_16x16x32_bf16 v[64:67], v[180:183], v[212:215], v[64:67]
	s_barrier
	s_setprio 0
	s_add_i32 s48, s48, s35
	v_lshl_add_u64 v[216:217], v[216:217], 0, s[24:25]
	s_mov_b32 m0, s48
	ds_read_b128 v[184:187], v153 offset:49152
	ds_read_b128 v[188:191], v153 offset:50176
	ds_read_b128 v[192:195], v153 offset:51200
	ds_read_b128 v[196:199], v153 offset:52224
	ds_read_b128 v[200:203], v153 offset:53248
	ds_read_b128 v[204:207], v153 offset:54272
	ds_read_b128 v[208:211], v153 offset:55296
	ds_read_b128 v[212:215], v153 offset:56320
	global_load_lds_dwordx4 v[216:217], off
	s_add_i32 m0, s48, 0x2000
	s_add_u32 s48, s54, 0x40080
	v_lshl_add_u64 v[216:217], v[220:221], 0, s[24:25]
	s_addc_u32 s49, s55, 0
	s_add_i32 s54, s68, s35
	global_load_lds_dwordx4 v[216:217], off
	s_mov_b32 m0, s54
	v_lshl_add_u64 v[216:217], s[48:49], 0, v[130:131]
	global_load_lds_dwordx4 v[216:217], off
	s_add_i32 m0, s54, 0x2000
	v_lshl_add_u64 v[216:217], s[48:49], 0, v[134:135]
	global_load_lds_dwordx4 v[216:217], off
	s_mov_b32 m0, s61
	v_lshl_add_u64 v[216:217], v[224:225], 0, s[24:25]
	global_load_lds_dwordx4 v[216:217], off
	s_mov_b32 m0, s62
	v_lshl_add_u64 v[216:217], v[226:227], 0, s[36:37]
	global_load_lds_dwordx4 v[216:217], off
	s_setprio 1
	s_waitcnt vmcnt(8) lgkmcnt(0)
	s_barrier
	v_mfma_f32_16x16x32_bf16 v[60:63], v[144:147], v[184:187], v[60:63]
	v_mfma_f32_16x16x32_bf16 v[56:59], v[160:163], v[184:187], v[56:59]
	v_mfma_f32_16x16x32_bf16 v[44:47], v[144:147], v[192:195], v[44:47]
	v_mfma_f32_16x16x32_bf16 v[40:43], v[160:163], v[192:195], v[40:43]
	v_mfma_f32_16x16x32_bf16 v[28:31], v[144:147], v[200:203], v[28:31]
	v_mfma_f32_16x16x32_bf16 v[24:27], v[160:163], v[200:203], v[24:27]
	v_mfma_f32_16x16x32_bf16 v[12:15], v[144:147], v[208:211], v[12:15]
	v_mfma_f32_16x16x32_bf16 v[8:11], v[160:163], v[208:211], v[8:11]
	v_mfma_f32_16x16x32_bf16 v[60:63], v[156:159], v[188:191], v[60:63]
	v_mfma_f32_16x16x32_bf16 v[56:59], v[164:167], v[188:191], v[56:59]
	v_mfma_f32_16x16x32_bf16 v[44:47], v[156:159], v[196:199], v[44:47]
	v_mfma_f32_16x16x32_bf16 v[40:43], v[164:167], v[196:199], v[40:43]
	v_mfma_f32_16x16x32_bf16 v[28:31], v[156:159], v[204:207], v[28:31]
	v_mfma_f32_16x16x32_bf16 v[24:27], v[164:167], v[204:207], v[24:27]
	v_mfma_f32_16x16x32_bf16 v[12:15], v[156:159], v[212:215], v[12:15]
	v_mfma_f32_16x16x32_bf16 v[8:11], v[164:167], v[212:215], v[8:11]
	v_mfma_f32_16x16x32_bf16 v[52:55], v[168:171], v[184:187], v[52:55]
	v_mfma_f32_16x16x32_bf16 v[48:51], v[176:179], v[184:187], v[48:51]
	v_mfma_f32_16x16x32_bf16 v[36:39], v[168:171], v[192:195], v[36:39]
	v_mfma_f32_16x16x32_bf16 v[32:35], v[176:179], v[192:195], v[32:35]
	v_mfma_f32_16x16x32_bf16 v[20:23], v[168:171], v[200:203], v[20:23]
	v_mfma_f32_16x16x32_bf16 v[16:19], v[176:179], v[200:203], v[16:19]
	v_mfma_f32_16x16x32_bf16 v[4:7], v[168:171], v[208:211], v[4:7]
	v_mfma_f32_16x16x32_bf16 v[0:3], v[176:179], v[208:211], v[0:3]
	v_mfma_f32_16x16x32_bf16 v[52:55], v[172:175], v[188:191], v[52:55]
	v_mfma_f32_16x16x32_bf16 v[48:51], v[180:183], v[188:191], v[48:51]
	v_mfma_f32_16x16x32_bf16 v[36:39], v[172:175], v[196:199], v[36:39]
	v_mfma_f32_16x16x32_bf16 v[32:35], v[180:183], v[196:199], v[32:35]
	v_mfma_f32_16x16x32_bf16 v[20:23], v[172:175], v[204:207], v[20:23]
	v_mfma_f32_16x16x32_bf16 v[16:19], v[180:183], v[204:207], v[16:19]
	v_mfma_f32_16x16x32_bf16 v[4:7], v[172:175], v[212:215], v[4:7]
	v_mfma_f32_16x16x32_bf16 v[0:3], v[180:183], v[212:215], v[0:3]
	s_barrier
	s_setprio 0
	s_add_i32 s76, s76, 2
	s_add_u32 s51, s51, 0x100
	s_addc_u32 s75, s75, 0
	s_cmp_gt_u32 s76, 13
	s_mov_b64 s[48:49], s[52:53]
	s_cbranch_scc0 .LBB0_466

.LBB0_564:
	s_ashr_i32 s77, s76, 31
	s_lshl_b64 s[50:51], s[76:77], 19
	s_add_u32 s82, s49, s50
	s_addc_u32 s83, s53, s51
	s_and_b64 s[0:1], s[0:1], exec
	s_cselect_b32 s13, s83, s89
	s_cselect_b32 s77, s82, s88
	v_lshl_add_u64 v[92:93], s[84:85], 0, v[168:169]
	s_add_u32 vcc_lo, s88, 0x100
	v_lshl_add_u64 v[130:131], v[92:93], 0, s[86:87]
	s_addc_u32 vcc_hi, s89, 0
	s_mov_b32 s50, -2
	s_mov_b64 s[0:1], 0
	s_waitcnt vmcnt(0)
	ds_read_b128 v[132:135], v207
	ds_read_b128 v[136:139], v207 offset:1024
	ds_read_b128 v[140:143], v207 offset:2048
	ds_read_b128 v[144:147], v207 offset:3072
	ds_read_b128 v[148:151], v208
	ds_read_b128 v[152:155], v208 offset:1024
	ds_read_b128 v[156:159], v208 offset:2048
	ds_read_b128 v[174:177], v208 offset:3072
	s_add_u32 s51, s84, s0
	s_addc_u32 s68, s85, s1
	s_add_u32 s51, s51, 0x100
	s_addc_u32 s68, s68, 0
	s_add_u32 s69, vcc_lo, s0
	s_addc_u32 s70, vcc_hi, s1
	s_cmpk_eq_i32 s0, 0x700
	s_cselect_b32 s91, s79, s68
	s_cselect_b32 s90, s78, s51
	s_cselect_b32 s51, s81, s87
	s_cselect_b32 s71, s80, s86
	s_cselect_b32 s89, s13, s70
	s_cselect_b32 s88, s77, s69
	v_lshl_add_u64 v[160:161], v[92:93], 0, s[0:1]
	s_add_i32 m0, s59, 0xc000
	ds_read_b128 v[194:197], v209
	ds_read_b128 v[198:201], v209 offset:1024
	ds_read_b128 v[212:215], v209 offset:2048
	ds_read_b128 v[224:227], v209 offset:3072
	ds_read_b128 v[228:231], v209 offset:4096
	ds_read_b128 v[232:235], v209 offset:5120
	ds_read_b128 v[236:239], v209 offset:6144
	ds_read_b128 v[240:243], v209 offset:7168
	global_load_lds_dwordx4 v[160:161], off
	s_add_i32 m0, s59, 0xe000
	v_lshl_add_u64 v[160:161], v[130:131], 0, s[0:1]
	global_load_lds_dwordx4 v[160:161], off
	s_setprio 1
	s_waitcnt vmcnt(8) lgkmcnt(0)
	s_barrier
	v_mfma_f32_16x16x32_bf16 v[126:129], v[132:135], v[194:197], 0
	v_mfma_f32_16x16x32_bf16 v[60:63], v[140:143], v[194:197], 0
	v_mfma_f32_16x16x32_bf16 v[118:121], v[132:135], v[212:215], 0
	v_mfma_f32_16x16x32_bf16 v[52:55], v[140:143], v[212:215], 0
	v_mfma_f32_16x16x32_bf16 v[110:113], v[132:135], v[228:231], 0
	v_mfma_f32_16x16x32_bf16 v[44:47], v[140:143], v[228:231], 0
	v_mfma_f32_16x16x32_bf16 v[94:97], v[132:135], v[236:239], 0
	v_mfma_f32_16x16x32_bf16 v[28:31], v[140:143], v[236:239], 0
	v_mfma_f32_16x16x32_bf16 v[126:129], v[136:139], v[198:201], v[126:129]
	v_mfma_f32_16x16x32_bf16 v[60:63], v[144:147], v[198:201], v[60:63]
	v_mfma_f32_16x16x32_bf16 v[118:121], v[136:139], v[224:227], v[118:121]
	v_mfma_f32_16x16x32_bf16 v[52:55], v[144:147], v[224:227], v[52:55]
	v_mfma_f32_16x16x32_bf16 v[110:113], v[136:139], v[232:235], v[110:113]
	v_mfma_f32_16x16x32_bf16 v[44:47], v[144:147], v[232:235], v[44:47]
	v_mfma_f32_16x16x32_bf16 v[94:97], v[136:139], v[240:243], v[94:97]
	v_mfma_f32_16x16x32_bf16 v[28:31], v[144:147], v[240:243], v[28:31]
	v_mfma_f32_16x16x32_bf16 v[122:125], v[148:151], v[194:197], 0
	v_mfma_f32_16x16x32_bf16 v[56:59], v[156:159], v[194:197], 0
	v_mfma_f32_16x16x32_bf16 v[114:117], v[148:151], v[212:215], 0
	v_mfma_f32_16x16x32_bf16 v[48:51], v[156:159], v[212:215], 0
	v_mfma_f32_16x16x32_bf16 v[102:105], v[148:151], v[228:231], 0
	v_mfma_f32_16x16x32_bf16 v[36:39], v[156:159], v[228:231], 0
	v_mfma_f32_16x16x32_bf16 v[88:91], v[148:151], v[236:239], 0
	v_mfma_f32_16x16x32_bf16 v[24:27], v[156:159], v[236:239], 0
	v_mfma_f32_16x16x32_bf16 v[122:125], v[152:155], v[198:201], v[122:125]
	v_mfma_f32_16x16x32_bf16 v[56:59], v[174:177], v[198:201], v[56:59]
	v_mfma_f32_16x16x32_bf16 v[114:117], v[152:155], v[224:227], v[114:117]
	v_mfma_f32_16x16x32_bf16 v[48:51], v[174:177], v[224:227], v[48:51]
	v_mfma_f32_16x16x32_bf16 v[102:105], v[152:155], v[232:235], v[102:105]
	v_mfma_f32_16x16x32_bf16 v[36:39], v[174:177], v[232:235], v[36:39]
	v_mfma_f32_16x16x32_bf16 v[88:91], v[152:155], v[240:243], v[88:91]
	v_mfma_f32_16x16x32_bf16 v[24:27], v[174:177], v[240:243], v[24:27]
	s_barrier
	s_setprio 0
	s_add_i32 s68, s95, s57
	v_lshl_add_u64 v[160:161], s[88:89], 0, v[164:165]
	s_mov_b32 m0, s68
	ds_read_b128 v[194:197], v209 offset:16384
	ds_read_b128 v[198:201], v209 offset:17408
	ds_read_b128 v[212:215], v209 offset:18432
	ds_read_b128 v[224:227], v209 offset:19456
	ds_read_b128 v[228:231], v209 offset:20480
	ds_read_b128 v[232:235], v209 offset:21504
	ds_read_b128 v[236:239], v209 offset:22528
	ds_read_b128 v[240:243], v209 offset:23552
	global_load_lds_dwordx4 v[160:161], off
	s_add_i32 m0, s68, 0x2000
	s_add_u32 s68, s88, 0x40000
	v_lshl_add_u64 v[216:217], s[88:89], 0, v[166:167]
	s_addc_u32 s69, s89, 0
	s_add_i32 s70, s96, s57
	global_load_lds_dwordx4 v[216:217], off
	s_mov_b32 m0, s70
	v_lshl_add_u64 v[220:221], s[68:69], 0, v[164:165]
	global_load_lds_dwordx4 v[220:221], off
	s_add_i32 m0, s70, 0x2000
	v_lshl_add_u64 v[220:221], s[68:69], 0, v[166:167]
	s_add_u32 s68, s90, s71
	global_load_lds_dwordx4 v[220:221], off
	v_lshl_add_u64 v[220:221], s[90:91], 0, v[162:163]
	s_mov_b32 m0, s59
	s_addc_u32 s69, s91, s51
	global_load_lds_dwordx4 v[220:221], off
	s_mov_b32 m0, s61
	v_lshl_add_u64 v[244:245], s[68:69], 0, v[162:163]
	global_load_lds_dwordx4 v[244:245], off
	s_setprio 1
	s_waitcnt vmcnt(8) lgkmcnt(0)
	s_barrier
	v_mfma_f32_16x16x32_bf16 v[84:87], v[132:135], v[194:197], 0
	v_mfma_f32_16x16x32_bf16 v[20:23], v[140:143], v[194:197], 0
	v_mfma_f32_16x16x32_bf16 v[76:79], v[132:135], v[212:215], 0
	v_mfma_f32_16x16x32_bf16 v[12:15], v[140:143], v[212:215], 0
	v_mfma_f32_16x16x32_bf16 v[68:71], v[132:135], v[228:231], 0
	v_mfma_f32_16x16x32_bf16 v[4:7], v[140:143], v[228:231], 0
	v_mfma_f32_16x16x32_bf16 v[106:109], v[132:135], v[236:239], 0
	v_mfma_f32_16x16x32_bf16 v[40:43], v[140:143], v[236:239], 0
	v_mfma_f32_16x16x32_bf16 v[84:87], v[136:139], v[198:201], v[84:87]
	v_mfma_f32_16x16x32_bf16 v[20:23], v[144:147], v[198:201], v[20:23]
	v_mfma_f32_16x16x32_bf16 v[76:79], v[136:139], v[224:227], v[76:79]
	v_mfma_f32_16x16x32_bf16 v[12:15], v[144:147], v[224:227], v[12:15]
	v_mfma_f32_16x16x32_bf16 v[68:71], v[136:139], v[232:235], v[68:71]
	v_mfma_f32_16x16x32_bf16 v[4:7], v[144:147], v[232:235], v[4:7]
	v_mfma_f32_16x16x32_bf16 v[106:109], v[136:139], v[240:243], v[106:109]
	v_mfma_f32_16x16x32_bf16 v[40:43], v[144:147], v[240:243], v[40:43]
	v_mfma_f32_16x16x32_bf16 v[80:83], v[148:151], v[194:197], 0
	v_mfma_f32_16x16x32_bf16 v[16:19], v[156:159], v[194:197], 0
	v_mfma_f32_16x16x32_bf16 v[72:75], v[148:151], v[212:215], 0
	v_mfma_f32_16x16x32_bf16 v[8:11], v[156:159], v[212:215], 0
	v_mfma_f32_16x16x32_bf16 v[64:67], v[148:151], v[228:231], 0
	v_mfma_f32_16x16x32_bf16 v[0:3], v[156:159], v[228:231], 0
	v_mfma_f32_16x16x32_bf16 v[98:101], v[148:151], v[236:239], 0
	v_mfma_f32_16x16x32_bf16 v[32:35], v[156:159], v[236:239], 0
	v_mfma_f32_16x16x32_bf16 v[80:83], v[152:155], v[198:201], v[80:83]
	v_mfma_f32_16x16x32_bf16 v[16:19], v[174:177], v[198:201], v[16:19]
	v_mfma_f32_16x16x32_bf16 v[72:75], v[152:155], v[224:227], v[72:75]
	v_mfma_f32_16x16x32_bf16 v[8:11], v[174:177], v[224:227], v[8:11]
	v_mfma_f32_16x16x32_bf16 v[64:67], v[152:155], v[232:235], v[64:67]
	v_mfma_f32_16x16x32_bf16 v[0:3], v[174:177], v[232:235], v[0:3]
	v_mfma_f32_16x16x32_bf16 v[98:101], v[152:155], v[240:243], v[98:101]
	v_mfma_f32_16x16x32_bf16 v[32:35], v[174:177], v[240:243], v[32:35]
	s_barrier
	s_setprio 0
	s_add_i32 s70, 0, 0x18000
	s_add_i32 s14, 0, 0x1c000
	v_add_u32_e32 v144, s70, v203
	v_add_u32_e32 v174, s14, v203
	ds_read_b128 v[132:135], v144
	ds_read_b128 v[136:139], v144 offset:1024
	ds_read_b128 v[140:143], v144 offset:2048
	ds_read_b128 v[144:147], v144 offset:3072
	ds_read_b128 v[148:151], v174
	ds_read_b128 v[152:155], v174 offset:1024
	ds_read_b128 v[156:159], v174 offset:2048
	ds_read_b128 v[174:177], v174 offset:3072
	s_add_u32 s68, s90, 0x2000
	s_addc_u32 s69, s91, 0
	v_lshl_add_u64 v[246:247], s[68:69], 0, v[162:163]
	s_add_u32 s68, s68, s71
	s_mov_b32 m0, s63
	s_addc_u32 s69, s69, s51
	ds_read_b128 v[194:197], v209 offset:32768
	ds_read_b128 v[198:201], v209 offset:33792
	ds_read_b128 v[212:215], v209 offset:34816
	ds_read_b128 v[224:227], v209 offset:35840
	ds_read_b128 v[228:231], v209 offset:36864
	ds_read_b128 v[232:235], v209 offset:37888
	ds_read_b128 v[236:239], v209 offset:38912
	ds_read_b128 v[240:243], v209 offset:39936
	global_load_lds_dwordx4 v[246:247], off
	s_mov_b32 m0, s67
	v_lshl_add_u64 v[246:247], s[68:69], 0, v[162:163]
	global_load_lds_dwordx4 v[246:247], off
	s_setprio 1
	s_waitcnt vmcnt(8) lgkmcnt(0)
	s_barrier
	v_mfma_f32_16x16x32_bf16 v[126:129], v[132:135], v[194:197], v[126:129]
	v_mfma_f32_16x16x32_bf16 v[60:63], v[140:143], v[194:197], v[60:63]
	v_mfma_f32_16x16x32_bf16 v[118:121], v[132:135], v[212:215], v[118:121]
	v_mfma_f32_16x16x32_bf16 v[52:55], v[140:143], v[212:215], v[52:55]
	v_mfma_f32_16x16x32_bf16 v[110:113], v[132:135], v[228:231], v[110:113]
	v_mfma_f32_16x16x32_bf16 v[44:47], v[140:143], v[228:231], v[44:47]
	v_mfma_f32_16x16x32_bf16 v[94:97], v[132:135], v[236:239], v[94:97]
	v_mfma_f32_16x16x32_bf16 v[28:31], v[140:143], v[236:239], v[28:31]
	v_mfma_f32_16x16x32_bf16 v[126:129], v[136:139], v[198:201], v[126:129]
	v_mfma_f32_16x16x32_bf16 v[60:63], v[144:147], v[198:201], v[60:63]
	v_mfma_f32_16x16x32_bf16 v[118:121], v[136:139], v[224:227], v[118:121]
	v_mfma_f32_16x16x32_bf16 v[52:55], v[144:147], v[224:227], v[52:55]
	v_mfma_f32_16x16x32_bf16 v[110:113], v[136:139], v[232:235], v[110:113]
	v_mfma_f32_16x16x32_bf16 v[44:47], v[144:147], v[232:235], v[44:47]
	v_mfma_f32_16x16x32_bf16 v[94:97], v[136:139], v[240:243], v[94:97]
	v_mfma_f32_16x16x32_bf16 v[28:31], v[144:147], v[240:243], v[28:31]
	v_mfma_f32_16x16x32_bf16 v[122:125], v[148:151], v[194:197], v[122:125]
	v_mfma_f32_16x16x32_bf16 v[56:59], v[156:159], v[194:197], v[56:59]
	v_mfma_f32_16x16x32_bf16 v[114:117], v[148:151], v[212:215], v[114:117]
	v_mfma_f32_16x16x32_bf16 v[48:51], v[156:159], v[212:215], v[48:51]
	v_mfma_f32_16x16x32_bf16 v[102:105], v[148:151], v[228:231], v[102:105]
	v_mfma_f32_16x16x32_bf16 v[36:39], v[156:159], v[228:231], v[36:39]
	v_mfma_f32_16x16x32_bf16 v[88:91], v[148:151], v[236:239], v[88:91]
	v_mfma_f32_16x16x32_bf16 v[24:27], v[156:159], v[236:239], v[24:27]
	v_mfma_f32_16x16x32_bf16 v[122:125], v[152:155], v[198:201], v[122:125]
	v_mfma_f32_16x16x32_bf16 v[56:59], v[174:177], v[198:201], v[56:59]
	v_mfma_f32_16x16x32_bf16 v[114:117], v[152:155], v[224:227], v[114:117]
	v_mfma_f32_16x16x32_bf16 v[48:51], v[174:177], v[224:227], v[48:51]
	v_mfma_f32_16x16x32_bf16 v[102:105], v[152:155], v[232:235], v[102:105]
	v_mfma_f32_16x16x32_bf16 v[36:39], v[174:177], v[232:235], v[36:39]
	v_mfma_f32_16x16x32_bf16 v[88:91], v[152:155], v[240:243], v[88:91]
	v_mfma_f32_16x16x32_bf16 v[24:27], v[174:177], v[240:243], v[24:27]
	s_barrier
	s_setprio 0
	s_add_i32 s15, s70, s57
	v_lshl_add_u64 v[160:161], v[160:161], 0, s[22:23]
	s_mov_b32 m0, s15
	ds_read_b128 v[194:197], v209 offset:49152
	ds_read_b128 v[198:201], v209 offset:50176
	ds_read_b128 v[212:215], v209 offset:51200
	ds_read_b128 v[224:227], v209 offset:52224
	ds_read_b128 v[228:231], v209 offset:53248
	ds_read_b128 v[232:235], v209 offset:54272
	ds_read_b128 v[236:239], v209 offset:55296
	ds_read_b128 v[240:243], v209 offset:56320
	global_load_lds_dwordx4 v[160:161], off
	s_add_i32 m0, s15, 0x2000
	s_add_u32 s68, s88, 0x40080
	v_lshl_add_u64 v[160:161], v[216:217], 0, s[22:23]
	s_addc_u32 s69, s89, 0
	s_add_i32 s14, s14, s57
	global_load_lds_dwordx4 v[160:161], off
	s_mov_b32 m0, s14
	v_lshl_add_u64 v[160:161], s[68:69], 0, v[164:165]
	global_load_lds_dwordx4 v[160:161], off
	s_add_i32 m0, s14, 0x2000
	v_lshl_add_u64 v[160:161], s[68:69], 0, v[166:167]
	global_load_lds_dwordx4 v[160:161], off
	s_mov_b32 m0, s75
	v_lshl_add_u64 v[160:161], v[220:221], 0, s[22:23]
	global_load_lds_dwordx4 v[160:161], off
	s_mov_b32 m0, s92
	v_lshl_add_u64 v[160:161], v[244:245], 0, s[22:23]
	global_load_lds_dwordx4 v[160:161], off
	s_setprio 1
	s_waitcnt vmcnt(8) lgkmcnt(0)
	s_barrier
	v_mfma_f32_16x16x32_bf16 v[84:87], v[132:135], v[194:197], v[84:87]
	v_mfma_f32_16x16x32_bf16 v[20:23], v[140:143], v[194:197], v[20:23]
	v_mfma_f32_16x16x32_bf16 v[76:79], v[132:135], v[212:215], v[76:79]
	v_mfma_f32_16x16x32_bf16 v[12:15], v[140:143], v[212:215], v[12:15]
	v_mfma_f32_16x16x32_bf16 v[68:71], v[132:135], v[228:231], v[68:71]
	v_mfma_f32_16x16x32_bf16 v[4:7], v[140:143], v[228:231], v[4:7]
	v_mfma_f32_16x16x32_bf16 v[106:109], v[132:135], v[236:239], v[106:109]
	v_mfma_f32_16x16x32_bf16 v[40:43], v[140:143], v[236:239], v[40:43]
	v_mfma_f32_16x16x32_bf16 v[84:87], v[136:139], v[198:201], v[84:87]
	v_mfma_f32_16x16x32_bf16 v[20:23], v[144:147], v[198:201], v[20:23]
	v_mfma_f32_16x16x32_bf16 v[76:79], v[136:139], v[224:227], v[76:79]
	v_mfma_f32_16x16x32_bf16 v[12:15], v[144:147], v[224:227], v[12:15]
	v_mfma_f32_16x16x32_bf16 v[68:71], v[136:139], v[232:235], v[68:71]
	v_mfma_f32_16x16x32_bf16 v[4:7], v[144:147], v[232:235], v[4:7]
	v_mfma_f32_16x16x32_bf16 v[106:109], v[136:139], v[240:243], v[106:109]
	v_mfma_f32_16x16x32_bf16 v[40:43], v[144:147], v[240:243], v[40:43]
	v_mfma_f32_16x16x32_bf16 v[80:83], v[148:151], v[194:197], v[80:83]
	v_mfma_f32_16x16x32_bf16 v[16:19], v[156:159], v[194:197], v[16:19]
	v_mfma_f32_16x16x32_bf16 v[72:75], v[148:151], v[212:215], v[72:75]
	v_mfma_f32_16x16x32_bf16 v[8:11], v[156:159], v[212:215], v[8:11]
	v_mfma_f32_16x16x32_bf16 v[64:67], v[148:151], v[228:231], v[64:67]
	v_mfma_f32_16x16x32_bf16 v[0:3], v[156:159], v[228:231], v[0:3]
	v_mfma_f32_16x16x32_bf16 v[98:101], v[148:151], v[236:239], v[98:101]
	v_mfma_f32_16x16x32_bf16 v[32:35], v[156:159], v[236:239], v[32:35]
	v_mfma_f32_16x16x32_bf16 v[80:83], v[152:155], v[198:201], v[80:83]
	v_mfma_f32_16x16x32_bf16 v[16:19], v[174:177], v[198:201], v[16:19]
	v_mfma_f32_16x16x32_bf16 v[72:75], v[152:155], v[224:227], v[72:75]
	v_mfma_f32_16x16x32_bf16 v[8:11], v[174:177], v[224:227], v[8:11]
	v_mfma_f32_16x16x32_bf16 v[64:67], v[152:155], v[232:235], v[64:67]
	v_mfma_f32_16x16x32_bf16 v[0:3], v[174:177], v[232:235], v[0:3]
	v_mfma_f32_16x16x32_bf16 v[98:101], v[152:155], v[240:243], v[98:101]
	v_mfma_f32_16x16x32_bf16 v[32:35], v[174:177], v[240:243], v[32:35]
	s_barrier
	s_setprio 0
	s_add_i32 s50, s50, 2
	s_add_u32 s0, s0, 0x100
	s_addc_u32 s1, s1, 0
	s_cmp_gt_u32 s50, 13
.LBB0_565:
	ds_read_b128 v[132:135], v207
	ds_read_b128 v[136:139], v207 offset:1024
	ds_read_b128 v[140:143], v207 offset:2048
	ds_read_b128 v[144:147], v207 offset:3072
	ds_read_b128 v[148:151], v208
	ds_read_b128 v[152:155], v208 offset:1024
	ds_read_b128 v[156:159], v208 offset:2048
	ds_read_b128 v[174:177], v208 offset:3072
	s_add_u32 s51, s84, s0
	s_addc_u32 s68, s85, s1
	s_add_u32 s51, s51, 0x100
	s_addc_u32 s68, s68, 0
	s_add_u32 s69, vcc_lo, s0
	s_addc_u32 s70, vcc_hi, s1
	s_cmpk_eq_i32 s0, 0x700
	s_cselect_b32 s91, s79, s68
	s_cselect_b32 s90, s78, s51
	s_cselect_b32 s51, s81, s87
	s_cselect_b32 s71, s80, s86
	s_cselect_b32 s89, s13, s70
	s_cselect_b32 s88, s77, s69
	v_lshl_add_u64 v[160:161], v[92:93], 0, s[0:1]
	s_add_i32 m0, s59, 0xc000
	ds_read_b128 v[194:197], v209
	ds_read_b128 v[198:201], v209 offset:1024
	ds_read_b128 v[212:215], v209 offset:2048
	ds_read_b128 v[224:227], v209 offset:3072
	ds_read_b128 v[228:231], v209 offset:4096
	ds_read_b128 v[232:235], v209 offset:5120
	ds_read_b128 v[236:239], v209 offset:6144
	ds_read_b128 v[240:243], v209 offset:7168
	global_load_lds_dwordx4 v[160:161], off
	s_add_i32 m0, s59, 0xe000
	v_lshl_add_u64 v[160:161], v[130:131], 0, s[0:1]
	global_load_lds_dwordx4 v[160:161], off
	s_setprio 1
	s_waitcnt vmcnt(8) lgkmcnt(0)
	s_barrier
	v_mfma_f32_16x16x32_bf16 v[126:129], v[132:135], v[194:197], v[126:129]
	v_mfma_f32_16x16x32_bf16 v[60:63], v[140:143], v[194:197], v[60:63]
	v_mfma_f32_16x16x32_bf16 v[118:121], v[132:135], v[212:215], v[118:121]
	v_mfma_f32_16x16x32_bf16 v[52:55], v[140:143], v[212:215], v[52:55]
	v_mfma_f32_16x16x32_bf16 v[110:113], v[132:135], v[228:231], v[110:113]
	v_mfma_f32_16x16x32_bf16 v[44:47], v[140:143], v[228:231], v[44:47]
	v_mfma_f32_16x16x32_bf16 v[94:97], v[132:135], v[236:239], v[94:97]
	v_mfma_f32_16x16x32_bf16 v[28:31], v[140:143], v[236:239], v[28:31]
	v_mfma_f32_16x16x32_bf16 v[126:129], v[136:139], v[198:201], v[126:129]
	v_mfma_f32_16x16x32_bf16 v[60:63], v[144:147], v[198:201], v[60:63]
	v_mfma_f32_16x16x32_bf16 v[118:121], v[136:139], v[224:227], v[118:121]
	v_mfma_f32_16x16x32_bf16 v[52:55], v[144:147], v[224:227], v[52:55]
	v_mfma_f32_16x16x32_bf16 v[110:113], v[136:139], v[232:235], v[110:113]
	v_mfma_f32_16x16x32_bf16 v[44:47], v[144:147], v[232:235], v[44:47]
	v_mfma_f32_16x16x32_bf16 v[94:97], v[136:139], v[240:243], v[94:97]
	v_mfma_f32_16x16x32_bf16 v[28:31], v[144:147], v[240:243], v[28:31]
	v_mfma_f32_16x16x32_bf16 v[122:125], v[148:151], v[194:197], v[122:125]
	v_mfma_f32_16x16x32_bf16 v[56:59], v[156:159], v[194:197], v[56:59]
	v_mfma_f32_16x16x32_bf16 v[114:117], v[148:151], v[212:215], v[114:117]
	v_mfma_f32_16x16x32_bf16 v[48:51], v[156:159], v[212:215], v[48:51]
	v_mfma_f32_16x16x32_bf16 v[102:105], v[148:151], v[228:231], v[102:105]
	v_mfma_f32_16x16x32_bf16 v[36:39], v[156:159], v[228:231], v[36:39]
	v_mfma_f32_16x16x32_bf16 v[88:91], v[148:151], v[236:239], v[88:91]
	v_mfma_f32_16x16x32_bf16 v[24:27], v[156:159], v[236:239], v[24:27]
	v_mfma_f32_16x16x32_bf16 v[122:125], v[152:155], v[198:201], v[122:125]
	v_mfma_f32_16x16x32_bf16 v[56:59], v[174:177], v[198:201], v[56:59]
	v_mfma_f32_16x16x32_bf16 v[114:117], v[152:155], v[224:227], v[114:117]
	v_mfma_f32_16x16x32_bf16 v[48:51], v[174:177], v[224:227], v[48:51]
	v_mfma_f32_16x16x32_bf16 v[102:105], v[152:155], v[232:235], v[102:105]
	v_mfma_f32_16x16x32_bf16 v[36:39], v[174:177], v[232:235], v[36:39]
	v_mfma_f32_16x16x32_bf16 v[88:91], v[152:155], v[240:243], v[88:91]
	v_mfma_f32_16x16x32_bf16 v[24:27], v[174:177], v[240:243], v[24:27]
	s_barrier
	s_setprio 0
	s_add_i32 s68, s95, s57
	v_lshl_add_u64 v[160:161], s[88:89], 0, v[164:165]
	s_mov_b32 m0, s68
	ds_read_b128 v[194:197], v209 offset:16384
	ds_read_b128 v[198:201], v209 offset:17408
	ds_read_b128 v[212:215], v209 offset:18432
	ds_read_b128 v[224:227], v209 offset:19456
	ds_read_b128 v[228:231], v209 offset:20480
	ds_read_b128 v[232:235], v209 offset:21504
	ds_read_b128 v[236:239], v209 offset:22528
	ds_read_b128 v[240:243], v209 offset:23552
	global_load_lds_dwordx4 v[160:161], off
	s_add_i32 m0, s68, 0x2000
	s_add_u32 s68, s88, 0x40000
	v_lshl_add_u64 v[216:217], s[88:89], 0, v[166:167]
	s_addc_u32 s69, s89, 0
	s_add_i32 s70, s96, s57
	global_load_lds_dwordx4 v[216:217], off
	s_mov_b32 m0, s70
	v_lshl_add_u64 v[220:221], s[68:69], 0, v[164:165]
	global_load_lds_dwordx4 v[220:221], off
	s_add_i32 m0, s70, 0x2000
	v_lshl_add_u64 v[220:221], s[68:69], 0, v[166:167]
	s_add_u32 s68, s90, s71
	global_load_lds_dwordx4 v[220:221], off
	v_lshl_add_u64 v[220:221], s[90:91], 0, v[162:163]
	s_mov_b32 m0, s59
	s_addc_u32 s69, s91, s51
	global_load_lds_dwordx4 v[220:221], off
	s_mov_b32 m0, s61
	v_lshl_add_u64 v[244:245], s[68:69], 0, v[162:163]
	global_load_lds_dwordx4 v[244:245], off
	s_setprio 1
	s_waitcnt vmcnt(8) lgkmcnt(0)
	s_barrier
	v_mfma_f32_16x16x32_bf16 v[84:87], v[132:135], v[194:197], v[84:87]
	v_mfma_f32_16x16x32_bf16 v[20:23], v[140:143], v[194:197], v[20:23]
	v_mfma_f32_16x16x32_bf16 v[76:79], v[132:135], v[212:215], v[76:79]
	v_mfma_f32_16x16x32_bf16 v[12:15], v[140:143], v[212:215], v[12:15]
	v_mfma_f32_16x16x32_bf16 v[68:71], v[132:135], v[228:231], v[68:71]
	v_mfma_f32_16x16x32_bf16 v[4:7], v[140:143], v[228:231], v[4:7]
	v_mfma_f32_16x16x32_bf16 v[106:109], v[132:135], v[236:239], v[106:109]
	v_mfma_f32_16x16x32_bf16 v[40:43], v[140:143], v[236:239], v[40:43]
	v_mfma_f32_16x16x32_bf16 v[84:87], v[136:139], v[198:201], v[84:87]
	v_mfma_f32_16x16x32_bf16 v[20:23], v[144:147], v[198:201], v[20:23]
	v_mfma_f32_16x16x32_bf16 v[76:79], v[136:139], v[224:227], v[76:79]
	v_mfma_f32_16x16x32_bf16 v[12:15], v[144:147], v[224:227], v[12:15]
	v_mfma_f32_16x16x32_bf16 v[68:71], v[136:139], v[232:235], v[68:71]
	v_mfma_f32_16x16x32_bf16 v[4:7], v[144:147], v[232:235], v[4:7]
	v_mfma_f32_16x16x32_bf16 v[106:109], v[136:139], v[240:243], v[106:109]
	v_mfma_f32_16x16x32_bf16 v[40:43], v[144:147], v[240:243], v[40:43]
	v_mfma_f32_16x16x32_bf16 v[80:83], v[148:151], v[194:197], v[80:83]
	v_mfma_f32_16x16x32_bf16 v[16:19], v[156:159], v[194:197], v[16:19]
	v_mfma_f32_16x16x32_bf16 v[72:75], v[148:151], v[212:215], v[72:75]
	v_mfma_f32_16x16x32_bf16 v[8:11], v[156:159], v[212:215], v[8:11]
	v_mfma_f32_16x16x32_bf16 v[64:67], v[148:151], v[228:231], v[64:67]
	v_mfma_f32_16x16x32_bf16 v[0:3], v[156:159], v[228:231], v[0:3]
	v_mfma_f32_16x16x32_bf16 v[98:101], v[148:151], v[236:239], v[98:101]
	v_mfma_f32_16x16x32_bf16 v[32:35], v[156:159], v[236:239], v[32:35]
	v_mfma_f32_16x16x32_bf16 v[80:83], v[152:155], v[198:201], v[80:83]
	v_mfma_f32_16x16x32_bf16 v[16:19], v[174:177], v[198:201], v[16:19]
	v_mfma_f32_16x16x32_bf16 v[72:75], v[152:155], v[224:227], v[72:75]
	v_mfma_f32_16x16x32_bf16 v[8:11], v[174:177], v[224:227], v[8:11]
	v_mfma_f32_16x16x32_bf16 v[64:67], v[152:155], v[232:235], v[64:67]
	v_mfma_f32_16x16x32_bf16 v[0:3], v[174:177], v[232:235], v[0:3]
	v_mfma_f32_16x16x32_bf16 v[98:101], v[152:155], v[240:243], v[98:101]
	v_mfma_f32_16x16x32_bf16 v[32:35], v[174:177], v[240:243], v[32:35]
	s_barrier
	s_setprio 0
	s_add_i32 s70, 0, 0x18000
	s_add_i32 s14, 0, 0x1c000
	v_add_u32_e32 v144, s70, v203
	v_add_u32_e32 v174, s14, v203
	ds_read_b128 v[132:135], v144
	ds_read_b128 v[136:139], v144 offset:1024
	ds_read_b128 v[140:143], v144 offset:2048
	ds_read_b128 v[144:147], v144 offset:3072
	ds_read_b128 v[148:151], v174
	ds_read_b128 v[152:155], v174 offset:1024
	ds_read_b128 v[156:159], v174 offset:2048
	ds_read_b128 v[174:177], v174 offset:3072
	s_add_u32 s68, s90, 0x2000
	s_addc_u32 s69, s91, 0
	v_lshl_add_u64 v[246:247], s[68:69], 0, v[162:163]
	s_add_u32 s68, s68, s71
	s_mov_b32 m0, s63
	s_addc_u32 s69, s69, s51
	ds_read_b128 v[194:197], v209 offset:32768
	ds_read_b128 v[198:201], v209 offset:33792
	ds_read_b128 v[212:215], v209 offset:34816
	ds_read_b128 v[224:227], v209 offset:35840
	ds_read_b128 v[228:231], v209 offset:36864
	ds_read_b128 v[232:235], v209 offset:37888
	ds_read_b128 v[236:239], v209 offset:38912
	ds_read_b128 v[240:243], v209 offset:39936
	global_load_lds_dwordx4 v[246:247], off
	s_mov_b32 m0, s67
	v_lshl_add_u64 v[246:247], s[68:69], 0, v[162:163]
	global_load_lds_dwordx4 v[246:247], off
	s_setprio 1
	s_waitcnt vmcnt(8) lgkmcnt(0)
	s_barrier
	v_mfma_f32_16x16x32_bf16 v[126:129], v[132:135], v[194:197], v[126:129]
	v_mfma_f32_16x16x32_bf16 v[60:63], v[140:143], v[194:197], v[60:63]
	v_mfma_f32_16x16x32_bf16 v[118:121], v[132:135], v[212:215], v[118:121]
	v_mfma_f32_16x16x32_bf16 v[52:55], v[140:143], v[212:215], v[52:55]
	v_mfma_f32_16x16x32_bf16 v[110:113], v[132:135], v[228:231], v[110:113]
	v_mfma_f32_16x16x32_bf16 v[44:47], v[140:143], v[228:231], v[44:47]
	v_mfma_f32_16x16x32_bf16 v[94:97], v[132:135], v[236:239], v[94:97]
	v_mfma_f32_16x16x32_bf16 v[28:31], v[140:143], v[236:239], v[28:31]
	v_mfma_f32_16x16x32_bf16 v[126:129], v[136:139], v[198:201], v[126:129]
	v_mfma_f32_16x16x32_bf16 v[60:63], v[144:147], v[198:201], v[60:63]
	v_mfma_f32_16x16x32_bf16 v[118:121], v[136:139], v[224:227], v[118:121]
	v_mfma_f32_16x16x32_bf16 v[52:55], v[144:147], v[224:227], v[52:55]
	v_mfma_f32_16x16x32_bf16 v[110:113], v[136:139], v[232:235], v[110:113]
	v_mfma_f32_16x16x32_bf16 v[44:47], v[144:147], v[232:235], v[44:47]
	v_mfma_f32_16x16x32_bf16 v[94:97], v[136:139], v[240:243], v[94:97]
	v_mfma_f32_16x16x32_bf16 v[28:31], v[144:147], v[240:243], v[28:31]
	v_mfma_f32_16x16x32_bf16 v[122:125], v[148:151], v[194:197], v[122:125]
	v_mfma_f32_16x16x32_bf16 v[56:59], v[156:159], v[194:197], v[56:59]
	v_mfma_f32_16x16x32_bf16 v[114:117], v[148:151], v[212:215], v[114:117]
	v_mfma_f32_16x16x32_bf16 v[48:51], v[156:159], v[212:215], v[48:51]
	v_mfma_f32_16x16x32_bf16 v[102:105], v[148:151], v[228:231], v[102:105]
	v_mfma_f32_16x16x32_bf16 v[36:39], v[156:159], v[228:231], v[36:39]
	v_mfma_f32_16x16x32_bf16 v[88:91], v[148:151], v[236:239], v[88:91]
	v_mfma_f32_16x16x32_bf16 v[24:27], v[156:159], v[236:239], v[24:27]
	v_mfma_f32_16x16x32_bf16 v[122:125], v[152:155], v[198:201], v[122:125]
	v_mfma_f32_16x16x32_bf16 v[56:59], v[174:177], v[198:201], v[56:59]
	v_mfma_f32_16x16x32_bf16 v[114:117], v[152:155], v[224:227], v[114:117]
	v_mfma_f32_16x16x32_bf16 v[48:51], v[174:177], v[224:227], v[48:51]
	v_mfma_f32_16x16x32_bf16 v[102:105], v[152:155], v[232:235], v[102:105]
	v_mfma_f32_16x16x32_bf16 v[36:39], v[174:177], v[232:235], v[36:39]
	v_mfma_f32_16x16x32_bf16 v[88:91], v[152:155], v[240:243], v[88:91]
	v_mfma_f32_16x16x32_bf16 v[24:27], v[174:177], v[240:243], v[24:27]
	s_barrier
	s_setprio 0
	s_add_i32 s15, s70, s57
	v_lshl_add_u64 v[160:161], v[160:161], 0, s[22:23]
	s_mov_b32 m0, s15
	ds_read_b128 v[194:197], v209 offset:49152
	ds_read_b128 v[198:201], v209 offset:50176
	ds_read_b128 v[212:215], v209 offset:51200
	ds_read_b128 v[224:227], v209 offset:52224
	ds_read_b128 v[228:231], v209 offset:53248
	ds_read_b128 v[232:235], v209 offset:54272
	ds_read_b128 v[236:239], v209 offset:55296
	ds_read_b128 v[240:243], v209 offset:56320
	global_load_lds_dwordx4 v[160:161], off
	s_add_i32 m0, s15, 0x2000
	s_add_u32 s68, s88, 0x40080
	v_lshl_add_u64 v[160:161], v[216:217], 0, s[22:23]
	s_addc_u32 s69, s89, 0
	s_add_i32 s14, s14, s57
	global_load_lds_dwordx4 v[160:161], off
	s_mov_b32 m0, s14
	v_lshl_add_u64 v[160:161], s[68:69], 0, v[164:165]
	global_load_lds_dwordx4 v[160:161], off
	s_add_i32 m0, s14, 0x2000
	v_lshl_add_u64 v[160:161], s[68:69], 0, v[166:167]
	global_load_lds_dwordx4 v[160:161], off
	s_mov_b32 m0, s75
	v_lshl_add_u64 v[160:161], v[220:221], 0, s[22:23]
	global_load_lds_dwordx4 v[160:161], off
	s_mov_b32 m0, s92
	v_lshl_add_u64 v[160:161], v[244:245], 0, s[22:23]
	global_load_lds_dwordx4 v[160:161], off
	s_setprio 1
	s_waitcnt vmcnt(8) lgkmcnt(0)
	s_barrier
	v_mfma_f32_16x16x32_bf16 v[84:87], v[132:135], v[194:197], v[84:87]
	v_mfma_f32_16x16x32_bf16 v[20:23], v[140:143], v[194:197], v[20:23]
	v_mfma_f32_16x16x32_bf16 v[76:79], v[132:135], v[212:215], v[76:79]
	v_mfma_f32_16x16x32_bf16 v[12:15], v[140:143], v[212:215], v[12:15]
	v_mfma_f32_16x16x32_bf16 v[68:71], v[132:135], v[228:231], v[68:71]
	v_mfma_f32_16x16x32_bf16 v[4:7], v[140:143], v[228:231], v[4:7]
	v_mfma_f32_16x16x32_bf16 v[106:109], v[132:135], v[236:239], v[106:109]
	v_mfma_f32_16x16x32_bf16 v[40:43], v[140:143], v[236:239], v[40:43]
	v_mfma_f32_16x16x32_bf16 v[84:87], v[136:139], v[198:201], v[84:87]
	v_mfma_f32_16x16x32_bf16 v[20:23], v[144:147], v[198:201], v[20:23]
	v_mfma_f32_16x16x32_bf16 v[76:79], v[136:139], v[224:227], v[76:79]
	v_mfma_f32_16x16x32_bf16 v[12:15], v[144:147], v[224:227], v[12:15]
	v_mfma_f32_16x16x32_bf16 v[68:71], v[136:139], v[232:235], v[68:71]
	v_mfma_f32_16x16x32_bf16 v[4:7], v[144:147], v[232:235], v[4:7]
	v_mfma_f32_16x16x32_bf16 v[106:109], v[136:139], v[240:243], v[106:109]
	v_mfma_f32_16x16x32_bf16 v[40:43], v[144:147], v[240:243], v[40:43]
	v_mfma_f32_16x16x32_bf16 v[80:83], v[148:151], v[194:197], v[80:83]
	v_mfma_f32_16x16x32_bf16 v[16:19], v[156:159], v[194:197], v[16:19]
	v_mfma_f32_16x16x32_bf16 v[72:75], v[148:151], v[212:215], v[72:75]
	v_mfma_f32_16x16x32_bf16 v[8:11], v[156:159], v[212:215], v[8:11]
	v_mfma_f32_16x16x32_bf16 v[64:67], v[148:151], v[228:231], v[64:67]
	v_mfma_f32_16x16x32_bf16 v[0:3], v[156:159], v[228:231], v[0:3]
	v_mfma_f32_16x16x32_bf16 v[98:101], v[148:151], v[236:239], v[98:101]
	v_mfma_f32_16x16x32_bf16 v[32:35], v[156:159], v[236:239], v[32:35]
	v_mfma_f32_16x16x32_bf16 v[80:83], v[152:155], v[198:201], v[80:83]
	v_mfma_f32_16x16x32_bf16 v[16:19], v[174:177], v[198:201], v[16:19]
	v_mfma_f32_16x16x32_bf16 v[72:75], v[152:155], v[224:227], v[72:75]
	v_mfma_f32_16x16x32_bf16 v[8:11], v[174:177], v[224:227], v[8:11]
	v_mfma_f32_16x16x32_bf16 v[64:67], v[152:155], v[232:235], v[64:67]
	v_mfma_f32_16x16x32_bf16 v[0:3], v[174:177], v[232:235], v[0:3]
	v_mfma_f32_16x16x32_bf16 v[98:101], v[152:155], v[240:243], v[98:101]
	v_mfma_f32_16x16x32_bf16 v[32:35], v[174:177], v[240:243], v[32:35]
	s_barrier
	s_setprio 0
	s_add_i32 s50, s50, 2
	s_add_u32 s0, s0, 0x100
	s_addc_u32 s1, s1, 0
	s_cmp_gt_u32 s50, 13
	s_cbranch_scc0 .LBB0_565

.LBB0_585:
	s_add_u32 s58, s46, s52
	s_addc_u32 s59, s47, s53
	s_add_u32 s56, s58, 0x100
	s_addc_u32 s57, s59, 0
	s_and_b64 s[54:55], s[50:51], exec
	s_cselect_b32 s54, s81, s56
	s_cselect_b32 s55, s13, s57
	s_add_u32 s52, s44, s52
	s_addc_u32 s53, s45, s53
	s_add_u32 s52, s52, 0x100
	ds_read_b128 v[148:151], v145
	ds_read_b128 v[152:155], v145 offset:1024
	ds_read_b128 v[156:159], v145 offset:2048
	ds_read_b128 v[160:163], v145 offset:3072
	ds_read_b128 v[164:167], v146
	ds_read_b128 v[168:171], v146 offset:1024
	ds_read_b128 v[172:175], v146 offset:2048
	ds_read_b128 v[176:179], v146 offset:3072
	s_addc_u32 s53, s53, 0
	s_and_b64 s[50:51], s[50:51], exec
	s_cselect_b32 s53, s39, s53
	s_cselect_b32 s52, s82, s52
	s_add_i32 s92, s75, s35
	s_add_i32 m0, s62, 0xc000
	s_add_i32 s93, s62, 0xe000
	s_add_i32 s89, s92, 0x2000
	s_add_u32 s56, s52, 0x10000
	s_addc_u32 s57, s53, 0
	s_add_i32 s88, 0, 0x18000
	s_add_i32 s91, s76, s35
	s_add_i32 s86, s88, s35
	s_add_i32 s90, s91, 0x2000
	s_add_i32 s87, 0, 0x1c000
	s_add_i32 s84, s86, 0x2000
	s_add_u32 s50, s52, 0x10080
	s_addc_u32 s51, s53, 0
	s_add_i32 s85, s87, s35
	s_add_i32 s83, s85, 0x2000
	v_lshl_add_u64 v[140:141], s[58:59], 0, v[134:135]
	v_lshl_add_u64 v[140:141], v[140:141], 0, s[68:69]
	ds_read_b128 v[180:183], v147
	ds_read_b128 v[184:187], v147 offset:1024
	ds_read_b128 v[188:191], v147 offset:2048
	ds_read_b128 v[192:195], v147 offset:3072
	ds_read_b128 v[196:199], v147 offset:4096
	ds_read_b128 v[200:203], v147 offset:5120
	ds_read_b128 v[204:207], v147 offset:6144
	ds_read_b128 v[208:211], v147 offset:7168
	global_load_lds_dwordx4 v[140:141], off
	v_lshl_add_u64 v[140:141], s[58:59], 0, v[130:131]
	s_mov_b64 s[58:59], 0x18080
	s_mov_b32 m0, s93
	v_lshl_add_u64 v[140:141], v[140:141], 0, s[58:59]
	global_load_lds_dwordx4 v[140:141], off
	s_setprio 1
	s_waitcnt vmcnt(8) lgkmcnt(0)
	s_barrier
	v_mfma_f32_16x16x32_bf16 v[124:127], v[148:151], v[180:183], v[124:127]
	v_mfma_f32_16x16x32_bf16 v[120:123], v[156:159], v[180:183], v[120:123]
	v_mfma_f32_16x16x32_bf16 v[112:115], v[148:151], v[188:191], v[112:115]
	v_mfma_f32_16x16x32_bf16 v[104:107], v[156:159], v[188:191], v[104:107]
	v_mfma_f32_16x16x32_bf16 v[96:99], v[148:151], v[196:199], v[96:99]
	v_mfma_f32_16x16x32_bf16 v[88:91], v[156:159], v[196:199], v[88:91]
	v_mfma_f32_16x16x32_bf16 v[80:83], v[148:151], v[204:207], v[80:83]
	v_mfma_f32_16x16x32_bf16 v[72:75], v[156:159], v[204:207], v[72:75]
	v_mfma_f32_16x16x32_bf16 v[124:127], v[152:155], v[184:187], v[124:127]
	v_mfma_f32_16x16x32_bf16 v[120:123], v[160:163], v[184:187], v[120:123]
	v_mfma_f32_16x16x32_bf16 v[112:115], v[152:155], v[192:195], v[112:115]
	v_mfma_f32_16x16x32_bf16 v[104:107], v[160:163], v[192:195], v[104:107]
	v_mfma_f32_16x16x32_bf16 v[96:99], v[152:155], v[200:203], v[96:99]
	v_mfma_f32_16x16x32_bf16 v[88:91], v[160:163], v[200:203], v[88:91]
	v_mfma_f32_16x16x32_bf16 v[80:83], v[152:155], v[208:211], v[80:83]
	v_mfma_f32_16x16x32_bf16 v[72:75], v[160:163], v[208:211], v[72:75]
	v_mfma_f32_16x16x32_bf16 v[116:119], v[164:167], v[180:183], v[116:119]
	v_mfma_f32_16x16x32_bf16 v[108:111], v[172:175], v[180:183], v[108:111]
	v_mfma_f32_16x16x32_bf16 v[100:103], v[164:167], v[188:191], v[100:103]
	v_mfma_f32_16x16x32_bf16 v[92:95], v[172:175], v[188:191], v[92:95]
	v_mfma_f32_16x16x32_bf16 v[84:87], v[164:167], v[196:199], v[84:87]
	v_mfma_f32_16x16x32_bf16 v[76:79], v[172:175], v[196:199], v[76:79]
	v_mfma_f32_16x16x32_bf16 v[68:71], v[164:167], v[204:207], v[68:71]
	v_mfma_f32_16x16x32_bf16 v[64:67], v[172:175], v[204:207], v[64:67]
	v_mfma_f32_16x16x32_bf16 v[116:119], v[168:171], v[184:187], v[116:119]
	v_mfma_f32_16x16x32_bf16 v[108:111], v[176:179], v[184:187], v[108:111]
	v_mfma_f32_16x16x32_bf16 v[100:103], v[168:171], v[192:195], v[100:103]
	v_mfma_f32_16x16x32_bf16 v[92:95], v[176:179], v[192:195], v[92:95]
	v_mfma_f32_16x16x32_bf16 v[84:87], v[168:171], v[200:203], v[84:87]
	v_mfma_f32_16x16x32_bf16 v[76:79], v[176:179], v[200:203], v[76:79]
	v_mfma_f32_16x16x32_bf16 v[68:71], v[168:171], v[208:211], v[68:71]
	v_mfma_f32_16x16x32_bf16 v[64:67], v[176:179], v[208:211], v[64:67]
	s_barrier
	s_setprio 0
	s_mov_b32 m0, s92
	v_lshl_add_u64 v[140:141], s[52:53], 0, v[132:133]
	ds_read_b128 v[180:183], v147 offset:16384
	ds_read_b128 v[184:187], v147 offset:17408
	ds_read_b128 v[188:191], v147 offset:18432
	ds_read_b128 v[192:195], v147 offset:19456
	ds_read_b128 v[196:199], v147 offset:20480
	ds_read_b128 v[200:203], v147 offset:21504
	ds_read_b128 v[204:207], v147 offset:22528
	ds_read_b128 v[208:211], v147 offset:23552
	global_load_lds_dwordx4 v[140:141], off
	v_lshl_add_u64 v[212:213], s[52:53], 0, v[128:129]
	s_mov_b32 m0, s89
	v_lshl_add_u64 v[214:215], s[56:57], 0, v[132:133]
	global_load_lds_dwordx4 v[212:213], off
	s_mov_b32 m0, s91
	v_lshl_add_u64 v[216:217], s[54:55], 0, v[130:131]
	global_load_lds_dwordx4 v[214:215], off
	v_lshl_add_u64 v[214:215], s[56:57], 0, v[128:129]
	s_mov_b32 m0, s90
	v_lshl_add_u64 v[220:221], v[216:217], 0, s[6:7]
	global_load_lds_dwordx4 v[214:215], off
	s_mov_b32 m0, s62
	v_lshl_add_u64 v[214:215], s[54:55], 0, v[134:135]
	global_load_lds_dwordx4 v[214:215], off
	s_mov_b32 m0, s63
	s_nop 0
	global_load_lds_dwordx4 v[220:221], off
	s_setprio 1
	s_waitcnt vmcnt(8) lgkmcnt(0)
	s_barrier
	v_mfma_f32_16x16x32_bf16 v[60:63], v[148:151], v[180:183], v[60:63]
	v_mfma_f32_16x16x32_bf16 v[56:59], v[156:159], v[180:183], v[56:59]
	v_mfma_f32_16x16x32_bf16 v[52:55], v[148:151], v[188:191], v[52:55]
	v_mfma_f32_16x16x32_bf16 v[44:47], v[156:159], v[188:191], v[44:47]
	v_mfma_f32_16x16x32_bf16 v[36:39], v[148:151], v[196:199], v[36:39]
	v_mfma_f32_16x16x32_bf16 v[28:31], v[156:159], v[196:199], v[28:31]
	v_mfma_f32_16x16x32_bf16 v[20:23], v[148:151], v[204:207], v[20:23]
	v_mfma_f32_16x16x32_bf16 v[12:15], v[156:159], v[204:207], v[12:15]
	v_mfma_f32_16x16x32_bf16 v[60:63], v[152:155], v[184:187], v[60:63]
	v_mfma_f32_16x16x32_bf16 v[56:59], v[160:163], v[184:187], v[56:59]
	v_mfma_f32_16x16x32_bf16 v[52:55], v[152:155], v[192:195], v[52:55]
	v_mfma_f32_16x16x32_bf16 v[44:47], v[160:163], v[192:195], v[44:47]
	v_mfma_f32_16x16x32_bf16 v[36:39], v[152:155], v[200:203], v[36:39]
	v_mfma_f32_16x16x32_bf16 v[28:31], v[160:163], v[200:203], v[28:31]
	v_mfma_f32_16x16x32_bf16 v[20:23], v[152:155], v[208:211], v[20:23]
	v_mfma_f32_16x16x32_bf16 v[12:15], v[160:163], v[208:211], v[12:15]
	v_mfma_f32_16x16x32_bf16 v[48:51], v[164:167], v[180:183], v[48:51]
	v_mfma_f32_16x16x32_bf16 v[40:43], v[172:175], v[180:183], v[40:43]
	v_mfma_f32_16x16x32_bf16 v[32:35], v[164:167], v[188:191], v[32:35]
	v_mfma_f32_16x16x32_bf16 v[24:27], v[172:175], v[188:191], v[24:27]
	v_mfma_f32_16x16x32_bf16 v[16:19], v[164:167], v[196:199], v[16:19]
	v_mfma_f32_16x16x32_bf16 v[8:11], v[172:175], v[196:199], v[8:11]
	v_mfma_f32_16x16x32_bf16 v[4:7], v[164:167], v[204:207], v[4:7]
	v_mfma_f32_16x16x32_bf16 v[0:3], v[172:175], v[204:207], v[0:3]
	v_mfma_f32_16x16x32_bf16 v[48:51], v[168:171], v[184:187], v[48:51]
	v_mfma_f32_16x16x32_bf16 v[40:43], v[176:179], v[184:187], v[40:43]
	v_mfma_f32_16x16x32_bf16 v[32:35], v[168:171], v[192:195], v[32:35]
	v_mfma_f32_16x16x32_bf16 v[24:27], v[176:179], v[192:195], v[24:27]
	v_mfma_f32_16x16x32_bf16 v[16:19], v[168:171], v[200:203], v[16:19]
	v_mfma_f32_16x16x32_bf16 v[8:11], v[176:179], v[200:203], v[8:11]
	v_mfma_f32_16x16x32_bf16 v[4:7], v[168:171], v[208:211], v[4:7]
	v_mfma_f32_16x16x32_bf16 v[0:3], v[176:179], v[208:211], v[0:3]
	s_barrier
	s_setprio 0
	v_add_u32_e32 v160, s88, v143
	v_add_u32_e32 v176, s87, v143
	ds_read_b128 v[148:151], v160
	ds_read_b128 v[152:155], v160 offset:1024
	ds_read_b128 v[156:159], v160 offset:2048
	ds_read_b128 v[160:163], v160 offset:3072
	ds_read_b128 v[164:167], v176
	ds_read_b128 v[168:171], v176 offset:1024
	ds_read_b128 v[172:175], v176 offset:2048
	ds_read_b128 v[176:179], v176 offset:3072
	s_mov_b32 m0, s64
	v_lshl_add_u64 v[220:221], v[214:215], 0, s[4:5]
	ds_read_b128 v[180:183], v147 offset:32768
	ds_read_b128 v[184:187], v147 offset:33792
	ds_read_b128 v[188:191], v147 offset:34816
	ds_read_b128 v[192:195], v147 offset:35840
	ds_read_b128 v[196:199], v147 offset:36864
	ds_read_b128 v[200:203], v147 offset:37888
	ds_read_b128 v[204:207], v147 offset:38912
	ds_read_b128 v[208:211], v147 offset:39936
	global_load_lds_dwordx4 v[220:221], off
	s_mov_b32 m0, s65
	v_lshl_add_u64 v[220:221], v[216:217], 0, s[8:9]
	global_load_lds_dwordx4 v[220:221], off
	s_setprio 1
	s_waitcnt vmcnt(8) lgkmcnt(0)
	s_barrier
	v_mfma_f32_16x16x32_bf16 v[124:127], v[148:151], v[180:183], v[124:127]
	v_mfma_f32_16x16x32_bf16 v[120:123], v[156:159], v[180:183], v[120:123]
	v_mfma_f32_16x16x32_bf16 v[112:115], v[148:151], v[188:191], v[112:115]
	v_mfma_f32_16x16x32_bf16 v[104:107], v[156:159], v[188:191], v[104:107]
	v_mfma_f32_16x16x32_bf16 v[96:99], v[148:151], v[196:199], v[96:99]
	v_mfma_f32_16x16x32_bf16 v[88:91], v[156:159], v[196:199], v[88:91]
	v_mfma_f32_16x16x32_bf16 v[80:83], v[148:151], v[204:207], v[80:83]
	v_mfma_f32_16x16x32_bf16 v[72:75], v[156:159], v[204:207], v[72:75]
	v_mfma_f32_16x16x32_bf16 v[124:127], v[152:155], v[184:187], v[124:127]
	v_mfma_f32_16x16x32_bf16 v[120:123], v[160:163], v[184:187], v[120:123]
	v_mfma_f32_16x16x32_bf16 v[112:115], v[152:155], v[192:195], v[112:115]
	v_mfma_f32_16x16x32_bf16 v[104:107], v[160:163], v[192:195], v[104:107]
	v_mfma_f32_16x16x32_bf16 v[96:99], v[152:155], v[200:203], v[96:99]
	v_mfma_f32_16x16x32_bf16 v[88:91], v[160:163], v[200:203], v[88:91]
	v_mfma_f32_16x16x32_bf16 v[80:83], v[152:155], v[208:211], v[80:83]
	v_mfma_f32_16x16x32_bf16 v[72:75], v[160:163], v[208:211], v[72:75]
	v_mfma_f32_16x16x32_bf16 v[116:119], v[164:167], v[180:183], v[116:119]
	v_mfma_f32_16x16x32_bf16 v[108:111], v[172:175], v[180:183], v[108:111]
	v_mfma_f32_16x16x32_bf16 v[100:103], v[164:167], v[188:191], v[100:103]
	v_mfma_f32_16x16x32_bf16 v[92:95], v[172:175], v[188:191], v[92:95]
	v_mfma_f32_16x16x32_bf16 v[84:87], v[164:167], v[196:199], v[84:87]
	v_mfma_f32_16x16x32_bf16 v[76:79], v[172:175], v[196:199], v[76:79]
	v_mfma_f32_16x16x32_bf16 v[68:71], v[164:167], v[204:207], v[68:71]
	v_mfma_f32_16x16x32_bf16 v[64:67], v[172:175], v[204:207], v[64:67]
	v_mfma_f32_16x16x32_bf16 v[116:119], v[168:171], v[184:187], v[116:119]
	v_mfma_f32_16x16x32_bf16 v[108:111], v[176:179], v[184:187], v[108:111]
	v_mfma_f32_16x16x32_bf16 v[100:103], v[168:171], v[192:195], v[100:103]
	v_mfma_f32_16x16x32_bf16 v[92:95], v[176:179], v[192:195], v[92:95]
	v_mfma_f32_16x16x32_bf16 v[84:87], v[168:171], v[200:203], v[84:87]
	v_mfma_f32_16x16x32_bf16 v[76:79], v[176:179], v[200:203], v[76:79]
	v_mfma_f32_16x16x32_bf16 v[68:71], v[168:171], v[208:211], v[68:71]
	v_mfma_f32_16x16x32_bf16 v[64:67], v[176:179], v[208:211], v[64:67]
	s_barrier
	s_setprio 0
	s_mov_b32 m0, s86
	v_lshl_add_u64 v[140:141], v[140:141], 0, s[18:19]
	ds_read_b128 v[180:183], v147 offset:49152
	ds_read_b128 v[184:187], v147 offset:50176
	ds_read_b128 v[188:191], v147 offset:51200
	ds_read_b128 v[192:195], v147 offset:52224
	ds_read_b128 v[196:199], v147 offset:53248
	ds_read_b128 v[200:203], v147 offset:54272
	ds_read_b128 v[204:207], v147 offset:55296
	ds_read_b128 v[208:211], v147 offset:56320
	global_load_lds_dwordx4 v[140:141], off
	s_mov_b32 m0, s84
	v_lshl_add_u64 v[140:141], v[212:213], 0, s[18:19]
	global_load_lds_dwordx4 v[140:141], off
	s_mov_b32 m0, s85
	v_lshl_add_u64 v[140:141], s[50:51], 0, v[132:133]
	global_load_lds_dwordx4 v[140:141], off
	s_mov_b32 m0, s83
	v_lshl_add_u64 v[140:141], s[50:51], 0, v[128:129]
	global_load_lds_dwordx4 v[140:141], off
	s_mov_b32 m0, s67
	v_lshl_add_u64 v[140:141], v[214:215], 0, s[18:19]
	global_load_lds_dwordx4 v[140:141], off
	s_mov_b32 m0, s72
	v_lshl_add_u64 v[140:141], v[216:217], 0, s[20:21]
	global_load_lds_dwordx4 v[140:141], off
	s_setprio 1
	s_waitcnt vmcnt(8) lgkmcnt(0)
	s_barrier
	v_mfma_f32_16x16x32_bf16 v[60:63], v[148:151], v[180:183], v[60:63]
	v_mfma_f32_16x16x32_bf16 v[56:59], v[156:159], v[180:183], v[56:59]
	v_mfma_f32_16x16x32_bf16 v[52:55], v[148:151], v[188:191], v[52:55]
	v_mfma_f32_16x16x32_bf16 v[44:47], v[156:159], v[188:191], v[44:47]
	v_mfma_f32_16x16x32_bf16 v[36:39], v[148:151], v[196:199], v[36:39]
	v_mfma_f32_16x16x32_bf16 v[28:31], v[156:159], v[196:199], v[28:31]
	v_mfma_f32_16x16x32_bf16 v[20:23], v[148:151], v[204:207], v[20:23]
	v_mfma_f32_16x16x32_bf16 v[12:15], v[156:159], v[204:207], v[12:15]
	v_mfma_f32_16x16x32_bf16 v[60:63], v[152:155], v[184:187], v[60:63]
	v_mfma_f32_16x16x32_bf16 v[56:59], v[160:163], v[184:187], v[56:59]
	v_mfma_f32_16x16x32_bf16 v[52:55], v[152:155], v[192:195], v[52:55]
	v_mfma_f32_16x16x32_bf16 v[44:47], v[160:163], v[192:195], v[44:47]
	v_mfma_f32_16x16x32_bf16 v[36:39], v[152:155], v[200:203], v[36:39]
	v_mfma_f32_16x16x32_bf16 v[28:31], v[160:163], v[200:203], v[28:31]
	v_mfma_f32_16x16x32_bf16 v[20:23], v[152:155], v[208:211], v[20:23]
	v_mfma_f32_16x16x32_bf16 v[12:15], v[160:163], v[208:211], v[12:15]
	v_mfma_f32_16x16x32_bf16 v[48:51], v[164:167], v[180:183], v[48:51]
	v_mfma_f32_16x16x32_bf16 v[40:43], v[172:175], v[180:183], v[40:43]
	v_mfma_f32_16x16x32_bf16 v[32:35], v[164:167], v[188:191], v[32:35]
	v_mfma_f32_16x16x32_bf16 v[24:27], v[172:175], v[188:191], v[24:27]
	v_mfma_f32_16x16x32_bf16 v[16:19], v[164:167], v[196:199], v[16:19]
	v_mfma_f32_16x16x32_bf16 v[8:11], v[172:175], v[196:199], v[8:11]
	v_mfma_f32_16x16x32_bf16 v[4:7], v[164:167], v[204:207], v[4:7]
	v_mfma_f32_16x16x32_bf16 v[0:3], v[172:175], v[204:207], v[0:3]
	v_mfma_f32_16x16x32_bf16 v[48:51], v[168:171], v[184:187], v[48:51]
	v_mfma_f32_16x16x32_bf16 v[40:43], v[176:179], v[184:187], v[40:43]
	v_mfma_f32_16x16x32_bf16 v[32:35], v[168:171], v[192:195], v[32:35]
	v_mfma_f32_16x16x32_bf16 v[24:27], v[176:179], v[192:195], v[24:27]
	v_mfma_f32_16x16x32_bf16 v[16:19], v[168:171], v[200:203], v[16:19]
	v_mfma_f32_16x16x32_bf16 v[8:11], v[176:179], v[200:203], v[8:11]
	v_mfma_f32_16x16x32_bf16 v[4:7], v[168:171], v[208:211], v[4:7]
	v_mfma_f32_16x16x32_bf16 v[0:3], v[176:179], v[208:211], v[0:3]
	s_barrier
	s_setprio 0
	s_andn2_b64 vcc, exec, s[48:49]
	s_mov_b64 s[50:51], -1
	s_mov_b64 s[48:49], 0
	s_mov_b64 s[52:53], 0x100
	s_cbranch_vccz .LBB0_585
	s_and_b64 vcc, exec, s[22:23]
	s_cbranch_vccz .LBB0_588
	s_barrier

.LBB0_661:
	s_add_u32 s64, s44, 0x100
	s_addc_u32 s65, s45, 0
	s_mov_b32 s66, -2
	s_waitcnt lgkmcnt(0)
	s_waitcnt vmcnt(0)
	ds_read_b128 v[144:147], v151
	ds_read_b128 v[156:159], v151 offset:1024
	ds_read_b128 v[160:163], v151 offset:2048
	ds_read_b128 v[164:167], v151 offset:3072
	ds_read_b128 v[168:171], v152
	ds_read_b128 v[172:175], v152 offset:1024
	ds_read_b128 v[176:179], v152 offset:2048
	ds_read_b128 v[180:183], v152 offset:3072
	s_add_u32 s44, s42, 0x100
	s_addc_u32 s45, s43, 0
	s_cmp_eq_u32 s66, 40
	s_cselect_b32 s69, s1, s45
	s_cselect_b32 s68, s0, s44
	s_cselect_b32 s47, s41, s65
	s_cselect_b32 s46, s40, s64
	v_lshl_add_u64 v[216:217], s[42:43], 0, v[136:137]
	s_add_i32 m0, s48, 0xc000
	ds_read_b128 v[184:187], v153
	ds_read_b128 v[188:191], v153 offset:1024
	ds_read_b128 v[192:195], v153 offset:2048
	ds_read_b128 v[196:199], v153 offset:3072
	ds_read_b128 v[200:203], v153 offset:4096
	ds_read_b128 v[204:207], v153 offset:5120
	ds_read_b128 v[208:211], v153 offset:6144
	ds_read_b128 v[212:215], v153 offset:7168
	global_load_lds_dwordx4 v[216:217], off
	s_add_i32 m0, s48, 0xe000
	v_lshl_add_u64 v[216:217], s[42:43], 0, v[138:139]
	global_load_lds_dwordx4 v[216:217], off
	s_setprio 1
	s_waitcnt vmcnt(8) lgkmcnt(0)
	s_barrier
	v_mfma_f32_16x16x32_bf16 v[124:127], v[144:147], v[184:187], 0
	v_mfma_f32_16x16x32_bf16 v[120:123], v[160:163], v[184:187], 0
	v_mfma_f32_16x16x32_bf16 v[108:111], v[144:147], v[192:195], 0
	v_mfma_f32_16x16x32_bf16 v[104:107], v[160:163], v[192:195], 0
	v_mfma_f32_16x16x32_bf16 v[92:95], v[144:147], v[200:203], 0
	v_mfma_f32_16x16x32_bf16 v[88:91], v[160:163], v[200:203], 0
	v_mfma_f32_16x16x32_bf16 v[76:79], v[144:147], v[208:211], 0
	v_mfma_f32_16x16x32_bf16 v[72:75], v[160:163], v[208:211], 0
	v_mfma_f32_16x16x32_bf16 v[124:127], v[156:159], v[188:191], v[124:127]
	v_mfma_f32_16x16x32_bf16 v[120:123], v[164:167], v[188:191], v[120:123]
	v_mfma_f32_16x16x32_bf16 v[108:111], v[156:159], v[196:199], v[108:111]
	v_mfma_f32_16x16x32_bf16 v[104:107], v[164:167], v[196:199], v[104:107]
	v_mfma_f32_16x16x32_bf16 v[92:95], v[156:159], v[204:207], v[92:95]
	v_mfma_f32_16x16x32_bf16 v[88:91], v[164:167], v[204:207], v[88:91]
	v_mfma_f32_16x16x32_bf16 v[76:79], v[156:159], v[212:215], v[76:79]
	v_mfma_f32_16x16x32_bf16 v[72:75], v[164:167], v[212:215], v[72:75]
	v_mfma_f32_16x16x32_bf16 v[116:119], v[168:171], v[184:187], 0
	v_mfma_f32_16x16x32_bf16 v[112:115], v[176:179], v[184:187], 0
	v_mfma_f32_16x16x32_bf16 v[100:103], v[168:171], v[192:195], 0
	v_mfma_f32_16x16x32_bf16 v[96:99], v[176:179], v[192:195], 0
	v_mfma_f32_16x16x32_bf16 v[84:87], v[168:171], v[200:203], 0
	v_mfma_f32_16x16x32_bf16 v[80:83], v[176:179], v[200:203], 0
	v_mfma_f32_16x16x32_bf16 v[68:71], v[168:171], v[208:211], 0
	v_mfma_f32_16x16x32_bf16 v[64:67], v[176:179], v[208:211], 0
	v_mfma_f32_16x16x32_bf16 v[116:119], v[172:175], v[188:191], v[116:119]
	v_mfma_f32_16x16x32_bf16 v[112:115], v[180:183], v[188:191], v[112:115]
	v_mfma_f32_16x16x32_bf16 v[100:103], v[172:175], v[196:199], v[100:103]
	v_mfma_f32_16x16x32_bf16 v[96:99], v[180:183], v[196:199], v[96:99]
	v_mfma_f32_16x16x32_bf16 v[84:87], v[172:175], v[204:207], v[84:87]
	v_mfma_f32_16x16x32_bf16 v[80:83], v[180:183], v[204:207], v[80:83]
	v_mfma_f32_16x16x32_bf16 v[68:71], v[172:175], v[212:215], v[68:71]
	v_mfma_f32_16x16x32_bf16 v[64:67], v[180:183], v[212:215], v[64:67]
	s_barrier
	s_setprio 0
	s_add_i32 s42, s59, s35
	v_lshl_add_u64 v[216:217], s[46:47], 0, v[130:131]
	s_mov_b32 m0, s42
	ds_read_b128 v[184:187], v153 offset:16384
	ds_read_b128 v[188:191], v153 offset:17408
	ds_read_b128 v[192:195], v153 offset:18432
	ds_read_b128 v[196:199], v153 offset:19456
	ds_read_b128 v[200:203], v153 offset:20480
	ds_read_b128 v[204:207], v153 offset:21504
	ds_read_b128 v[208:211], v153 offset:22528
	ds_read_b128 v[212:215], v153 offset:23552
	global_load_lds_dwordx4 v[216:217], off
	s_add_i32 m0, s42, 0x2000
	s_add_u32 s42, s46, 0xb0000
	v_lshl_add_u64 v[220:221], s[46:47], 0, v[134:135]
	s_addc_u32 s43, s47, 0
	s_add_i32 s67, s60, s35
	global_load_lds_dwordx4 v[220:221], off
	v_lshl_add_u64 v[224:225], s[42:43], 0, v[130:131]
	s_mov_b32 m0, s67
	v_lshl_add_u64 v[226:227], s[68:69], 0, v[132:133]
	global_load_lds_dwordx4 v[224:225], off
	v_lshl_add_u64 v[224:225], s[42:43], 0, v[134:135]
	s_add_i32 m0, s67, 0x2000
	v_lshl_add_u64 v[228:229], v[226:227], 0, s[14:15]
	global_load_lds_dwordx4 v[224:225], off
	s_mov_b32 m0, s48
	v_lshl_add_u64 v[224:225], s[68:69], 0, v[128:129]
	global_load_lds_dwordx4 v[224:225], off
	s_mov_b32 m0, s49
	s_nop 0
	global_load_lds_dwordx4 v[228:229], off
	s_setprio 1
	s_waitcnt vmcnt(8) lgkmcnt(0)
	s_barrier
	v_mfma_f32_16x16x32_bf16 v[60:63], v[144:147], v[184:187], 0
	v_mfma_f32_16x16x32_bf16 v[56:59], v[160:163], v[184:187], 0
	v_mfma_f32_16x16x32_bf16 v[44:47], v[144:147], v[192:195], 0
	v_mfma_f32_16x16x32_bf16 v[40:43], v[160:163], v[192:195], 0
	v_mfma_f32_16x16x32_bf16 v[28:31], v[144:147], v[200:203], 0
	v_mfma_f32_16x16x32_bf16 v[24:27], v[160:163], v[200:203], 0
	v_mfma_f32_16x16x32_bf16 v[12:15], v[144:147], v[208:211], 0
	v_mfma_f32_16x16x32_bf16 v[8:11], v[160:163], v[208:211], 0
	v_mfma_f32_16x16x32_bf16 v[60:63], v[156:159], v[188:191], v[60:63]
	v_mfma_f32_16x16x32_bf16 v[56:59], v[164:167], v[188:191], v[56:59]
	v_mfma_f32_16x16x32_bf16 v[44:47], v[156:159], v[196:199], v[44:47]
	v_mfma_f32_16x16x32_bf16 v[40:43], v[164:167], v[196:199], v[40:43]
	v_mfma_f32_16x16x32_bf16 v[28:31], v[156:159], v[204:207], v[28:31]
	v_mfma_f32_16x16x32_bf16 v[24:27], v[164:167], v[204:207], v[24:27]
	v_mfma_f32_16x16x32_bf16 v[12:15], v[156:159], v[212:215], v[12:15]
	v_mfma_f32_16x16x32_bf16 v[8:11], v[164:167], v[212:215], v[8:11]
	v_mfma_f32_16x16x32_bf16 v[52:55], v[168:171], v[184:187], 0
	v_mfma_f32_16x16x32_bf16 v[48:51], v[176:179], v[184:187], 0
	v_mfma_f32_16x16x32_bf16 v[36:39], v[168:171], v[192:195], 0
	v_mfma_f32_16x16x32_bf16 v[32:35], v[176:179], v[192:195], 0
	v_mfma_f32_16x16x32_bf16 v[20:23], v[168:171], v[200:203], 0
	v_mfma_f32_16x16x32_bf16 v[16:19], v[176:179], v[200:203], 0
	v_mfma_f32_16x16x32_bf16 v[4:7], v[168:171], v[208:211], 0
	v_mfma_f32_16x16x32_bf16 v[0:3], v[176:179], v[208:211], 0
	v_mfma_f32_16x16x32_bf16 v[52:55], v[172:175], v[188:191], v[52:55]
	v_mfma_f32_16x16x32_bf16 v[48:51], v[180:183], v[188:191], v[48:51]
	v_mfma_f32_16x16x32_bf16 v[36:39], v[172:175], v[196:199], v[36:39]
	v_mfma_f32_16x16x32_bf16 v[32:35], v[180:183], v[196:199], v[32:35]
	v_mfma_f32_16x16x32_bf16 v[20:23], v[172:175], v[204:207], v[20:23]
	v_mfma_f32_16x16x32_bf16 v[16:19], v[180:183], v[204:207], v[16:19]
	v_mfma_f32_16x16x32_bf16 v[4:7], v[172:175], v[212:215], v[4:7]
	v_mfma_f32_16x16x32_bf16 v[0:3], v[180:183], v[212:215], v[0:3]
	s_barrier
	s_setprio 0
	s_add_i32 s42, 0, 0x18000
	v_add_u32_e32 v155, s42, v149
	s_add_i32 s67, 0, 0x1c000
	ds_read_b128 v[144:147], v155
	ds_read_b128 v[156:159], v155 offset:1024
	ds_read_b128 v[160:163], v155 offset:2048
	ds_read_b128 v[164:167], v155 offset:3072
	v_add_u32_e32 v155, s67, v149
	ds_read_b128 v[168:171], v155
	ds_read_b128 v[172:175], v155 offset:1024
	ds_read_b128 v[176:179], v155 offset:2048
	ds_read_b128 v[180:183], v155 offset:3072
	s_mov_b32 m0, s50
	v_lshl_add_u64 v[228:229], v[224:225], 0, s[12:13]
	ds_read_b128 v[184:187], v153 offset:32768
	ds_read_b128 v[188:191], v153 offset:33792
	ds_read_b128 v[192:195], v153 offset:34816
	ds_read_b128 v[196:199], v153 offset:35840
	ds_read_b128 v[200:203], v153 offset:36864
	ds_read_b128 v[204:207], v153 offset:37888
	ds_read_b128 v[208:211], v153 offset:38912
	ds_read_b128 v[212:215], v153 offset:39936
	global_load_lds_dwordx4 v[228:229], off
	s_mov_b32 m0, s51
	v_lshl_add_u64 v[228:229], v[226:227], 0, s[16:17]
	global_load_lds_dwordx4 v[228:229], off
	s_setprio 1
	s_waitcnt vmcnt(8) lgkmcnt(0)
	s_barrier
	v_mfma_f32_16x16x32_bf16 v[124:127], v[144:147], v[184:187], v[124:127]
	v_mfma_f32_16x16x32_bf16 v[120:123], v[160:163], v[184:187], v[120:123]
	v_mfma_f32_16x16x32_bf16 v[108:111], v[144:147], v[192:195], v[108:111]
	v_mfma_f32_16x16x32_bf16 v[104:107], v[160:163], v[192:195], v[104:107]
	v_mfma_f32_16x16x32_bf16 v[92:95], v[144:147], v[200:203], v[92:95]
	v_mfma_f32_16x16x32_bf16 v[88:91], v[160:163], v[200:203], v[88:91]
	v_mfma_f32_16x16x32_bf16 v[76:79], v[144:147], v[208:211], v[76:79]
	v_mfma_f32_16x16x32_bf16 v[72:75], v[160:163], v[208:211], v[72:75]
	v_mfma_f32_16x16x32_bf16 v[124:127], v[156:159], v[188:191], v[124:127]
	v_mfma_f32_16x16x32_bf16 v[120:123], v[164:167], v[188:191], v[120:123]
	v_mfma_f32_16x16x32_bf16 v[108:111], v[156:159], v[196:199], v[108:111]
	v_mfma_f32_16x16x32_bf16 v[104:107], v[164:167], v[196:199], v[104:107]
	v_mfma_f32_16x16x32_bf16 v[92:95], v[156:159], v[204:207], v[92:95]
	v_mfma_f32_16x16x32_bf16 v[88:91], v[164:167], v[204:207], v[88:91]
	v_mfma_f32_16x16x32_bf16 v[76:79], v[156:159], v[212:215], v[76:79]
	v_mfma_f32_16x16x32_bf16 v[72:75], v[164:167], v[212:215], v[72:75]
	v_mfma_f32_16x16x32_bf16 v[116:119], v[168:171], v[184:187], v[116:119]
	v_mfma_f32_16x16x32_bf16 v[112:115], v[176:179], v[184:187], v[112:115]
	v_mfma_f32_16x16x32_bf16 v[100:103], v[168:171], v[192:195], v[100:103]
	v_mfma_f32_16x16x32_bf16 v[96:99], v[176:179], v[192:195], v[96:99]
	v_mfma_f32_16x16x32_bf16 v[84:87], v[168:171], v[200:203], v[84:87]
	v_mfma_f32_16x16x32_bf16 v[80:83], v[176:179], v[200:203], v[80:83]
	v_mfma_f32_16x16x32_bf16 v[68:71], v[168:171], v[208:211], v[68:71]
	v_mfma_f32_16x16x32_bf16 v[64:67], v[176:179], v[208:211], v[64:67]
	v_mfma_f32_16x16x32_bf16 v[116:119], v[172:175], v[188:191], v[116:119]
	v_mfma_f32_16x16x32_bf16 v[112:115], v[180:183], v[188:191], v[112:115]
	v_mfma_f32_16x16x32_bf16 v[100:103], v[172:175], v[196:199], v[100:103]
	v_mfma_f32_16x16x32_bf16 v[96:99], v[180:183], v[196:199], v[96:99]
	v_mfma_f32_16x16x32_bf16 v[84:87], v[172:175], v[204:207], v[84:87]
	v_mfma_f32_16x16x32_bf16 v[80:83], v[180:183], v[204:207], v[80:83]
	v_mfma_f32_16x16x32_bf16 v[68:71], v[172:175], v[212:215], v[68:71]
	v_mfma_f32_16x16x32_bf16 v[64:67], v[180:183], v[212:215], v[64:67]
	s_barrier
	s_setprio 0
	s_add_i32 s42, s42, s35
	v_lshl_add_u64 v[216:217], v[216:217], 0, s[24:25]
	s_mov_b32 m0, s42
	ds_read_b128 v[184:187], v153 offset:49152
	ds_read_b128 v[188:191], v153 offset:50176
	ds_read_b128 v[192:195], v153 offset:51200
	ds_read_b128 v[196:199], v153 offset:52224
	ds_read_b128 v[200:203], v153 offset:53248
	ds_read_b128 v[204:207], v153 offset:54272
	ds_read_b128 v[208:211], v153 offset:55296
	ds_read_b128 v[212:215], v153 offset:56320
	global_load_lds_dwordx4 v[216:217], off
	s_add_i32 m0, s42, 0x2000
	s_add_u32 s42, s46, 0xb0080
	v_lshl_add_u64 v[216:217], v[220:221], 0, s[24:25]
	s_addc_u32 s43, s47, 0
	s_add_i32 s46, s67, s35
	global_load_lds_dwordx4 v[216:217], off
	s_mov_b32 m0, s46
	v_lshl_add_u64 v[216:217], s[42:43], 0, v[130:131]
	global_load_lds_dwordx4 v[216:217], off
	s_add_i32 m0, s46, 0x2000
	v_lshl_add_u64 v[216:217], s[42:43], 0, v[134:135]
	global_load_lds_dwordx4 v[216:217], off
	s_mov_b32 m0, s53
	v_lshl_add_u64 v[216:217], v[224:225], 0, s[24:25]
	global_load_lds_dwordx4 v[216:217], off
	s_mov_b32 m0, s54
	v_lshl_add_u64 v[216:217], v[226:227], 0, s[36:37]
	global_load_lds_dwordx4 v[216:217], off
	s_setprio 1
	s_waitcnt vmcnt(8) lgkmcnt(0)
	s_barrier
	v_mfma_f32_16x16x32_bf16 v[60:63], v[144:147], v[184:187], v[60:63]
	v_mfma_f32_16x16x32_bf16 v[56:59], v[160:163], v[184:187], v[56:59]
	v_mfma_f32_16x16x32_bf16 v[44:47], v[144:147], v[192:195], v[44:47]
	v_mfma_f32_16x16x32_bf16 v[40:43], v[160:163], v[192:195], v[40:43]
	v_mfma_f32_16x16x32_bf16 v[28:31], v[144:147], v[200:203], v[28:31]
	v_mfma_f32_16x16x32_bf16 v[24:27], v[160:163], v[200:203], v[24:27]
	v_mfma_f32_16x16x32_bf16 v[12:15], v[144:147], v[208:211], v[12:15]
	v_mfma_f32_16x16x32_bf16 v[8:11], v[160:163], v[208:211], v[8:11]
	v_mfma_f32_16x16x32_bf16 v[60:63], v[156:159], v[188:191], v[60:63]
	v_mfma_f32_16x16x32_bf16 v[56:59], v[164:167], v[188:191], v[56:59]
	v_mfma_f32_16x16x32_bf16 v[44:47], v[156:159], v[196:199], v[44:47]
	v_mfma_f32_16x16x32_bf16 v[40:43], v[164:167], v[196:199], v[40:43]
	v_mfma_f32_16x16x32_bf16 v[28:31], v[156:159], v[204:207], v[28:31]
	v_mfma_f32_16x16x32_bf16 v[24:27], v[164:167], v[204:207], v[24:27]
	v_mfma_f32_16x16x32_bf16 v[12:15], v[156:159], v[212:215], v[12:15]
	v_mfma_f32_16x16x32_bf16 v[8:11], v[164:167], v[212:215], v[8:11]
	v_mfma_f32_16x16x32_bf16 v[52:55], v[168:171], v[184:187], v[52:55]
	v_mfma_f32_16x16x32_bf16 v[48:51], v[176:179], v[184:187], v[48:51]
	v_mfma_f32_16x16x32_bf16 v[36:39], v[168:171], v[192:195], v[36:39]
	v_mfma_f32_16x16x32_bf16 v[32:35], v[176:179], v[192:195], v[32:35]
	v_mfma_f32_16x16x32_bf16 v[20:23], v[168:171], v[200:203], v[20:23]
	v_mfma_f32_16x16x32_bf16 v[16:19], v[176:179], v[200:203], v[16:19]
	v_mfma_f32_16x16x32_bf16 v[4:7], v[168:171], v[208:211], v[4:7]
	v_mfma_f32_16x16x32_bf16 v[0:3], v[176:179], v[208:211], v[0:3]
	v_mfma_f32_16x16x32_bf16 v[52:55], v[172:175], v[188:191], v[52:55]
	v_mfma_f32_16x16x32_bf16 v[48:51], v[180:183], v[188:191], v[48:51]
	v_mfma_f32_16x16x32_bf16 v[36:39], v[172:175], v[196:199], v[36:39]
	v_mfma_f32_16x16x32_bf16 v[32:35], v[180:183], v[196:199], v[32:35]
	v_mfma_f32_16x16x32_bf16 v[20:23], v[172:175], v[204:207], v[20:23]
	v_mfma_f32_16x16x32_bf16 v[16:19], v[180:183], v[204:207], v[16:19]
	v_mfma_f32_16x16x32_bf16 v[4:7], v[172:175], v[212:215], v[4:7]
	v_mfma_f32_16x16x32_bf16 v[0:3], v[180:183], v[212:215], v[0:3]
	s_barrier
	s_setprio 0
	s_add_i32 s66, s66, 2
	s_add_u32 s64, s64, 0x100
	s_addc_u32 s65, s65, 0
	s_cmp_gt_u32 s66, 41
	s_mov_b64 s[42:43], s[44:45]
.LBB0_662:
	ds_read_b128 v[144:147], v151
	ds_read_b128 v[156:159], v151 offset:1024
	ds_read_b128 v[160:163], v151 offset:2048
	ds_read_b128 v[164:167], v151 offset:3072
	ds_read_b128 v[168:171], v152
	ds_read_b128 v[172:175], v152 offset:1024
	ds_read_b128 v[176:179], v152 offset:2048
	ds_read_b128 v[180:183], v152 offset:3072
	s_add_u32 s44, s42, 0x100
	s_addc_u32 s45, s43, 0
	s_cmp_eq_u32 s66, 40
	s_cselect_b32 s69, s1, s45
	s_cselect_b32 s68, s0, s44
	s_cselect_b32 s47, s41, s65
	s_cselect_b32 s46, s40, s64
	v_lshl_add_u64 v[216:217], s[42:43], 0, v[136:137]
	s_add_i32 m0, s48, 0xc000
	ds_read_b128 v[184:187], v153
	ds_read_b128 v[188:191], v153 offset:1024
	ds_read_b128 v[192:195], v153 offset:2048
	ds_read_b128 v[196:199], v153 offset:3072
	ds_read_b128 v[200:203], v153 offset:4096
	ds_read_b128 v[204:207], v153 offset:5120
	ds_read_b128 v[208:211], v153 offset:6144
	ds_read_b128 v[212:215], v153 offset:7168
	global_load_lds_dwordx4 v[216:217], off
	s_add_i32 m0, s48, 0xe000
	v_lshl_add_u64 v[216:217], s[42:43], 0, v[138:139]
	global_load_lds_dwordx4 v[216:217], off
	s_setprio 1
	s_waitcnt vmcnt(8) lgkmcnt(0)
	s_barrier
	v_mfma_f32_16x16x32_bf16 v[124:127], v[144:147], v[184:187], v[124:127]
	v_mfma_f32_16x16x32_bf16 v[120:123], v[160:163], v[184:187], v[120:123]
	v_mfma_f32_16x16x32_bf16 v[108:111], v[144:147], v[192:195], v[108:111]
	v_mfma_f32_16x16x32_bf16 v[104:107], v[160:163], v[192:195], v[104:107]
	v_mfma_f32_16x16x32_bf16 v[92:95], v[144:147], v[200:203], v[92:95]
	v_mfma_f32_16x16x32_bf16 v[88:91], v[160:163], v[200:203], v[88:91]
	v_mfma_f32_16x16x32_bf16 v[76:79], v[144:147], v[208:211], v[76:79]
	v_mfma_f32_16x16x32_bf16 v[72:75], v[160:163], v[208:211], v[72:75]
	v_mfma_f32_16x16x32_bf16 v[124:127], v[156:159], v[188:191], v[124:127]
	v_mfma_f32_16x16x32_bf16 v[120:123], v[164:167], v[188:191], v[120:123]
	v_mfma_f32_16x16x32_bf16 v[108:111], v[156:159], v[196:199], v[108:111]
	v_mfma_f32_16x16x32_bf16 v[104:107], v[164:167], v[196:199], v[104:107]
	v_mfma_f32_16x16x32_bf16 v[92:95], v[156:159], v[204:207], v[92:95]
	v_mfma_f32_16x16x32_bf16 v[88:91], v[164:167], v[204:207], v[88:91]
	v_mfma_f32_16x16x32_bf16 v[76:79], v[156:159], v[212:215], v[76:79]
	v_mfma_f32_16x16x32_bf16 v[72:75], v[164:167], v[212:215], v[72:75]
	v_mfma_f32_16x16x32_bf16 v[116:119], v[168:171], v[184:187], v[116:119]
	v_mfma_f32_16x16x32_bf16 v[112:115], v[176:179], v[184:187], v[112:115]
	v_mfma_f32_16x16x32_bf16 v[100:103], v[168:171], v[192:195], v[100:103]
	v_mfma_f32_16x16x32_bf16 v[96:99], v[176:179], v[192:195], v[96:99]
	v_mfma_f32_16x16x32_bf16 v[84:87], v[168:171], v[200:203], v[84:87]
	v_mfma_f32_16x16x32_bf16 v[80:83], v[176:179], v[200:203], v[80:83]
	v_mfma_f32_16x16x32_bf16 v[68:71], v[168:171], v[208:211], v[68:71]
	v_mfma_f32_16x16x32_bf16 v[64:67], v[176:179], v[208:211], v[64:67]
	v_mfma_f32_16x16x32_bf16 v[116:119], v[172:175], v[188:191], v[116:119]
	v_mfma_f32_16x16x32_bf16 v[112:115], v[180:183], v[188:191], v[112:115]
	v_mfma_f32_16x16x32_bf16 v[100:103], v[172:175], v[196:199], v[100:103]
	v_mfma_f32_16x16x32_bf16 v[96:99], v[180:183], v[196:199], v[96:99]
	v_mfma_f32_16x16x32_bf16 v[84:87], v[172:175], v[204:207], v[84:87]
	v_mfma_f32_16x16x32_bf16 v[80:83], v[180:183], v[204:207], v[80:83]
	v_mfma_f32_16x16x32_bf16 v[68:71], v[172:175], v[212:215], v[68:71]
	v_mfma_f32_16x16x32_bf16 v[64:67], v[180:183], v[212:215], v[64:67]
	s_barrier
	s_setprio 0
	s_add_i32 s42, s59, s35
	v_lshl_add_u64 v[216:217], s[46:47], 0, v[130:131]
	s_mov_b32 m0, s42
	ds_read_b128 v[184:187], v153 offset:16384
	ds_read_b128 v[188:191], v153 offset:17408
	ds_read_b128 v[192:195], v153 offset:18432
	ds_read_b128 v[196:199], v153 offset:19456
	ds_read_b128 v[200:203], v153 offset:20480
	ds_read_b128 v[204:207], v153 offset:21504
	ds_read_b128 v[208:211], v153 offset:22528
	ds_read_b128 v[212:215], v153 offset:23552
	global_load_lds_dwordx4 v[216:217], off
	s_add_i32 m0, s42, 0x2000
	s_add_u32 s42, s46, 0xb0000
	v_lshl_add_u64 v[220:221], s[46:47], 0, v[134:135]
	s_addc_u32 s43, s47, 0
	s_add_i32 s67, s60, s35
	global_load_lds_dwordx4 v[220:221], off
	v_lshl_add_u64 v[224:225], s[42:43], 0, v[130:131]
	s_mov_b32 m0, s67
	v_lshl_add_u64 v[226:227], s[68:69], 0, v[132:133]
	global_load_lds_dwordx4 v[224:225], off
	v_lshl_add_u64 v[224:225], s[42:43], 0, v[134:135]
	s_add_i32 m0, s67, 0x2000
	v_lshl_add_u64 v[228:229], v[226:227], 0, s[14:15]
	global_load_lds_dwordx4 v[224:225], off
	s_mov_b32 m0, s48
	v_lshl_add_u64 v[224:225], s[68:69], 0, v[128:129]
	global_load_lds_dwordx4 v[224:225], off
	s_mov_b32 m0, s49
	s_nop 0
	global_load_lds_dwordx4 v[228:229], off
	s_setprio 1
	s_waitcnt vmcnt(8) lgkmcnt(0)
	s_barrier
	v_mfma_f32_16x16x32_bf16 v[60:63], v[144:147], v[184:187], v[60:63]
	v_mfma_f32_16x16x32_bf16 v[56:59], v[160:163], v[184:187], v[56:59]
	v_mfma_f32_16x16x32_bf16 v[44:47], v[144:147], v[192:195], v[44:47]
	v_mfma_f32_16x16x32_bf16 v[40:43], v[160:163], v[192:195], v[40:43]
	v_mfma_f32_16x16x32_bf16 v[28:31], v[144:147], v[200:203], v[28:31]
	v_mfma_f32_16x16x32_bf16 v[24:27], v[160:163], v[200:203], v[24:27]
	v_mfma_f32_16x16x32_bf16 v[12:15], v[144:147], v[208:211], v[12:15]
	v_mfma_f32_16x16x32_bf16 v[8:11], v[160:163], v[208:211], v[8:11]
	v_mfma_f32_16x16x32_bf16 v[60:63], v[156:159], v[188:191], v[60:63]
	v_mfma_f32_16x16x32_bf16 v[56:59], v[164:167], v[188:191], v[56:59]
	v_mfma_f32_16x16x32_bf16 v[44:47], v[156:159], v[196:199], v[44:47]
	v_mfma_f32_16x16x32_bf16 v[40:43], v[164:167], v[196:199], v[40:43]
	v_mfma_f32_16x16x32_bf16 v[28:31], v[156:159], v[204:207], v[28:31]
	v_mfma_f32_16x16x32_bf16 v[24:27], v[164:167], v[204:207], v[24:27]
	v_mfma_f32_16x16x32_bf16 v[12:15], v[156:159], v[212:215], v[12:15]
	v_mfma_f32_16x16x32_bf16 v[8:11], v[164:167], v[212:215], v[8:11]
	v_mfma_f32_16x16x32_bf16 v[52:55], v[168:171], v[184:187], v[52:55]
	v_mfma_f32_16x16x32_bf16 v[48:51], v[176:179], v[184:187], v[48:51]
	v_mfma_f32_16x16x32_bf16 v[36:39], v[168:171], v[192:195], v[36:39]
	v_mfma_f32_16x16x32_bf16 v[32:35], v[176:179], v[192:195], v[32:35]
	v_mfma_f32_16x16x32_bf16 v[20:23], v[168:171], v[200:203], v[20:23]
	v_mfma_f32_16x16x32_bf16 v[16:19], v[176:179], v[200:203], v[16:19]
	v_mfma_f32_16x16x32_bf16 v[4:7], v[168:171], v[208:211], v[4:7]
	v_mfma_f32_16x16x32_bf16 v[0:3], v[176:179], v[208:211], v[0:3]
	v_mfma_f32_16x16x32_bf16 v[52:55], v[172:175], v[188:191], v[52:55]
	v_mfma_f32_16x16x32_bf16 v[48:51], v[180:183], v[188:191], v[48:51]
	v_mfma_f32_16x16x32_bf16 v[36:39], v[172:175], v[196:199], v[36:39]
	v_mfma_f32_16x16x32_bf16 v[32:35], v[180:183], v[196:199], v[32:35]
	v_mfma_f32_16x16x32_bf16 v[20:23], v[172:175], v[204:207], v[20:23]
	v_mfma_f32_16x16x32_bf16 v[16:19], v[180:183], v[204:207], v[16:19]
	v_mfma_f32_16x16x32_bf16 v[4:7], v[172:175], v[212:215], v[4:7]
	v_mfma_f32_16x16x32_bf16 v[0:3], v[180:183], v[212:215], v[0:3]
	s_barrier
	s_setprio 0
	s_add_i32 s42, 0, 0x18000
	v_add_u32_e32 v155, s42, v149
	s_add_i32 s67, 0, 0x1c000
	ds_read_b128 v[144:147], v155
	ds_read_b128 v[156:159], v155 offset:1024
	ds_read_b128 v[160:163], v155 offset:2048
	ds_read_b128 v[164:167], v155 offset:3072
	v_add_u32_e32 v155, s67, v149
	ds_read_b128 v[168:171], v155
	ds_read_b128 v[172:175], v155 offset:1024
	ds_read_b128 v[176:179], v155 offset:2048
	ds_read_b128 v[180:183], v155 offset:3072
	s_mov_b32 m0, s50
	v_lshl_add_u64 v[228:229], v[224:225], 0, s[12:13]
	ds_read_b128 v[184:187], v153 offset:32768
	ds_read_b128 v[188:191], v153 offset:33792
	ds_read_b128 v[192:195], v153 offset:34816
	ds_read_b128 v[196:199], v153 offset:35840
	ds_read_b128 v[200:203], v153 offset:36864
	ds_read_b128 v[204:207], v153 offset:37888
	ds_read_b128 v[208:211], v153 offset:38912
	ds_read_b128 v[212:215], v153 offset:39936
	global_load_lds_dwordx4 v[228:229], off
	s_mov_b32 m0, s51
	v_lshl_add_u64 v[228:229], v[226:227], 0, s[16:17]
	global_load_lds_dwordx4 v[228:229], off
	s_setprio 1
	s_waitcnt vmcnt(8) lgkmcnt(0)
	s_barrier
	v_mfma_f32_16x16x32_bf16 v[124:127], v[144:147], v[184:187], v[124:127]
	v_mfma_f32_16x16x32_bf16 v[120:123], v[160:163], v[184:187], v[120:123]
	v_mfma_f32_16x16x32_bf16 v[108:111], v[144:147], v[192:195], v[108:111]
	v_mfma_f32_16x16x32_bf16 v[104:107], v[160:163], v[192:195], v[104:107]
	v_mfma_f32_16x16x32_bf16 v[92:95], v[144:147], v[200:203], v[92:95]
	v_mfma_f32_16x16x32_bf16 v[88:91], v[160:163], v[200:203], v[88:91]
	v_mfma_f32_16x16x32_bf16 v[76:79], v[144:147], v[208:211], v[76:79]
	v_mfma_f32_16x16x32_bf16 v[72:75], v[160:163], v[208:211], v[72:75]
	v_mfma_f32_16x16x32_bf16 v[124:127], v[156:159], v[188:191], v[124:127]
	v_mfma_f32_16x16x32_bf16 v[120:123], v[164:167], v[188:191], v[120:123]
	v_mfma_f32_16x16x32_bf16 v[108:111], v[156:159], v[196:199], v[108:111]
	v_mfma_f32_16x16x32_bf16 v[104:107], v[164:167], v[196:199], v[104:107]
	v_mfma_f32_16x16x32_bf16 v[92:95], v[156:159], v[204:207], v[92:95]
	v_mfma_f32_16x16x32_bf16 v[88:91], v[164:167], v[204:207], v[88:91]
	v_mfma_f32_16x16x32_bf16 v[76:79], v[156:159], v[212:215], v[76:79]
	v_mfma_f32_16x16x32_bf16 v[72:75], v[164:167], v[212:215], v[72:75]
	v_mfma_f32_16x16x32_bf16 v[116:119], v[168:171], v[184:187], v[116:119]
	v_mfma_f32_16x16x32_bf16 v[112:115], v[176:179], v[184:187], v[112:115]
	v_mfma_f32_16x16x32_bf16 v[100:103], v[168:171], v[192:195], v[100:103]
	v_mfma_f32_16x16x32_bf16 v[96:99], v[176:179], v[192:195], v[96:99]
	v_mfma_f32_16x16x32_bf16 v[84:87], v[168:171], v[200:203], v[84:87]
	v_mfma_f32_16x16x32_bf16 v[80:83], v[176:179], v[200:203], v[80:83]
	v_mfma_f32_16x16x32_bf16 v[68:71], v[168:171], v[208:211], v[68:71]
	v_mfma_f32_16x16x32_bf16 v[64:67], v[176:179], v[208:211], v[64:67]
	v_mfma_f32_16x16x32_bf16 v[116:119], v[172:175], v[188:191], v[116:119]
	v_mfma_f32_16x16x32_bf16 v[112:115], v[180:183], v[188:191], v[112:115]
	v_mfma_f32_16x16x32_bf16 v[100:103], v[172:175], v[196:199], v[100:103]
	v_mfma_f32_16x16x32_bf16 v[96:99], v[180:183], v[196:199], v[96:99]
	v_mfma_f32_16x16x32_bf16 v[84:87], v[172:175], v[204:207], v[84:87]
	v_mfma_f32_16x16x32_bf16 v[80:83], v[180:183], v[204:207], v[80:83]
	v_mfma_f32_16x16x32_bf16 v[68:71], v[172:175], v[212:215], v[68:71]
	v_mfma_f32_16x16x32_bf16 v[64:67], v[180:183], v[212:215], v[64:67]
	s_barrier
	s_setprio 0
	s_add_i32 s42, s42, s35
	v_lshl_add_u64 v[216:217], v[216:217], 0, s[24:25]
	s_mov_b32 m0, s42
	ds_read_b128 v[184:187], v153 offset:49152
	ds_read_b128 v[188:191], v153 offset:50176
	ds_read_b128 v[192:195], v153 offset:51200
	ds_read_b128 v[196:199], v153 offset:52224
	ds_read_b128 v[200:203], v153 offset:53248
	ds_read_b128 v[204:207], v153 offset:54272
	ds_read_b128 v[208:211], v153 offset:55296
	ds_read_b128 v[212:215], v153 offset:56320
	global_load_lds_dwordx4 v[216:217], off
	s_add_i32 m0, s42, 0x2000
	s_add_u32 s42, s46, 0xb0080
	v_lshl_add_u64 v[216:217], v[220:221], 0, s[24:25]
	s_addc_u32 s43, s47, 0
	s_add_i32 s46, s67, s35
	global_load_lds_dwordx4 v[216:217], off
	s_mov_b32 m0, s46
	v_lshl_add_u64 v[216:217], s[42:43], 0, v[130:131]
	global_load_lds_dwordx4 v[216:217], off
	s_add_i32 m0, s46, 0x2000
	v_lshl_add_u64 v[216:217], s[42:43], 0, v[134:135]
	global_load_lds_dwordx4 v[216:217], off
	s_mov_b32 m0, s53
	v_lshl_add_u64 v[216:217], v[224:225], 0, s[24:25]
	global_load_lds_dwordx4 v[216:217], off
	s_mov_b32 m0, s54
	v_lshl_add_u64 v[216:217], v[226:227], 0, s[36:37]
	global_load_lds_dwordx4 v[216:217], off
	s_setprio 1
	s_waitcnt vmcnt(8) lgkmcnt(0)
	s_barrier
	v_mfma_f32_16x16x32_bf16 v[60:63], v[144:147], v[184:187], v[60:63]
	v_mfma_f32_16x16x32_bf16 v[56:59], v[160:163], v[184:187], v[56:59]
	v_mfma_f32_16x16x32_bf16 v[44:47], v[144:147], v[192:195], v[44:47]
	v_mfma_f32_16x16x32_bf16 v[40:43], v[160:163], v[192:195], v[40:43]
	v_mfma_f32_16x16x32_bf16 v[28:31], v[144:147], v[200:203], v[28:31]
	v_mfma_f32_16x16x32_bf16 v[24:27], v[160:163], v[200:203], v[24:27]
	v_mfma_f32_16x16x32_bf16 v[12:15], v[144:147], v[208:211], v[12:15]
	v_mfma_f32_16x16x32_bf16 v[8:11], v[160:163], v[208:211], v[8:11]
	v_mfma_f32_16x16x32_bf16 v[60:63], v[156:159], v[188:191], v[60:63]
	v_mfma_f32_16x16x32_bf16 v[56:59], v[164:167], v[188:191], v[56:59]
	v_mfma_f32_16x16x32_bf16 v[44:47], v[156:159], v[196:199], v[44:47]
	v_mfma_f32_16x16x32_bf16 v[40:43], v[164:167], v[196:199], v[40:43]
	v_mfma_f32_16x16x32_bf16 v[28:31], v[156:159], v[204:207], v[28:31]
	v_mfma_f32_16x16x32_bf16 v[24:27], v[164:167], v[204:207], v[24:27]
	v_mfma_f32_16x16x32_bf16 v[12:15], v[156:159], v[212:215], v[12:15]
	v_mfma_f32_16x16x32_bf16 v[8:11], v[164:167], v[212:215], v[8:11]
	v_mfma_f32_16x16x32_bf16 v[52:55], v[168:171], v[184:187], v[52:55]
	v_mfma_f32_16x16x32_bf16 v[48:51], v[176:179], v[184:187], v[48:51]
	v_mfma_f32_16x16x32_bf16 v[36:39], v[168:171], v[192:195], v[36:39]
	v_mfma_f32_16x16x32_bf16 v[32:35], v[176:179], v[192:195], v[32:35]
	v_mfma_f32_16x16x32_bf16 v[20:23], v[168:171], v[200:203], v[20:23]
	v_mfma_f32_16x16x32_bf16 v[16:19], v[176:179], v[200:203], v[16:19]
	v_mfma_f32_16x16x32_bf16 v[4:7], v[168:171], v[208:211], v[4:7]
	v_mfma_f32_16x16x32_bf16 v[0:3], v[176:179], v[208:211], v[0:3]
	v_mfma_f32_16x16x32_bf16 v[52:55], v[172:175], v[188:191], v[52:55]
	v_mfma_f32_16x16x32_bf16 v[48:51], v[180:183], v[188:191], v[48:51]
	v_mfma_f32_16x16x32_bf16 v[36:39], v[172:175], v[196:199], v[36:39]
	v_mfma_f32_16x16x32_bf16 v[32:35], v[180:183], v[196:199], v[32:35]
	v_mfma_f32_16x16x32_bf16 v[20:23], v[172:175], v[204:207], v[20:23]
	v_mfma_f32_16x16x32_bf16 v[16:19], v[180:183], v[204:207], v[16:19]
	v_mfma_f32_16x16x32_bf16 v[4:7], v[172:175], v[212:215], v[4:7]
	v_mfma_f32_16x16x32_bf16 v[0:3], v[180:183], v[212:215], v[0:3]
	s_barrier
	s_setprio 0
	s_add_i32 s66, s66, 2
	s_add_u32 s64, s64, 0x100
	s_addc_u32 s65, s65, 0
	s_cmp_gt_u32 s66, 41
	s_mov_b64 s[42:43], s[44:45]
	s_cbranch_scc0 .LBB0_662

.LBB0_750:
	s_lshl_b32 s38, s65, 8
	s_ashr_i32 s39, s38, 31
	s_lshl_b64 s[38:39], s[38:39], 11
	s_add_u32 s38, s8, s38
	s_addc_u32 s39, s9, s39
	s_and_b64 s[40:41], s[4:5], exec
	s_cselect_b32 s43, s39, s45
	s_cselect_b32 s67, s38, s44
	s_ashr_i32 s37, s36, 31
	s_lshl_b64 s[40:41], s[36:37], 19
	s_add_u32 s40, s3, s40
	s_addc_u32 s41, s33, s41
	s_and_b64 s[48:49], s[4:5], exec
	s_cselect_b32 s37, s41, s47
	s_cselect_b32 s68, s40, s46
	s_add_u32 s69, s46, 0x100
	s_addc_u32 s71, s47, 0
	s_mov_b32 s72, -2
	s_waitcnt vmcnt(0)
	ds_read_b128 v[144:147], v189
	ds_read_b128 v[148:151], v189 offset:1024
	ds_read_b128 v[152:155], v189 offset:2048
	ds_read_b128 v[156:159], v189 offset:3072
	ds_read_b128 v[160:163], v190
	ds_read_b128 v[164:167], v190 offset:1024
	ds_read_b128 v[168:171], v190 offset:2048
	ds_read_b128 v[172:175], v190 offset:3072
	s_add_u32 s46, s44, 0x100
	s_addc_u32 s47, s45, 0
	s_cmp_eq_u32 s72, 12
	s_cselect_b32 s75, s43, s47
	s_cselect_b32 s74, s67, s46
	s_cselect_b32 s49, s37, s71
	s_cselect_b32 s48, s68, s69
	v_lshl_add_u64 v[184:185], s[44:45], 0, v[136:137]
	s_add_i32 m0, s51, 0xc000
	ds_read_b128 v[176:179], v191
	ds_read_b128 v[180:183], v191 offset:1024
	ds_read_b128 v[194:197], v191 offset:2048
	ds_read_b128 v[198:201], v191 offset:3072
	ds_read_b128 v[202:205], v191 offset:4096
	ds_read_b128 v[206:209], v191 offset:5120
	ds_read_b128 v[210:213], v191 offset:6144
	ds_read_b128 v[214:217], v191 offset:7168
	global_load_lds_dwordx4 v[184:185], off
	s_add_i32 m0, s51, 0xe000
	v_lshl_add_u64 v[184:185], s[44:45], 0, v[138:139]
	global_load_lds_dwordx4 v[184:185], off
	s_setprio 1
	s_waitcnt vmcnt(8) lgkmcnt(0)
	s_barrier
	v_mfma_f32_16x16x32_bf16 v[124:127], v[144:147], v[176:179], 0
	v_mfma_f32_16x16x32_bf16 v[120:123], v[152:155], v[176:179], 0
	v_mfma_f32_16x16x32_bf16 v[108:111], v[144:147], v[194:197], 0
	v_mfma_f32_16x16x32_bf16 v[104:107], v[152:155], v[194:197], 0
	v_mfma_f32_16x16x32_bf16 v[92:95], v[144:147], v[202:205], 0
	v_mfma_f32_16x16x32_bf16 v[88:91], v[152:155], v[202:205], 0
	v_mfma_f32_16x16x32_bf16 v[76:79], v[144:147], v[210:213], 0
	v_mfma_f32_16x16x32_bf16 v[72:75], v[152:155], v[210:213], 0
	v_mfma_f32_16x16x32_bf16 v[124:127], v[148:151], v[180:183], v[124:127]
	v_mfma_f32_16x16x32_bf16 v[120:123], v[156:159], v[180:183], v[120:123]
	v_mfma_f32_16x16x32_bf16 v[108:111], v[148:151], v[198:201], v[108:111]
	v_mfma_f32_16x16x32_bf16 v[104:107], v[156:159], v[198:201], v[104:107]
	v_mfma_f32_16x16x32_bf16 v[92:95], v[148:151], v[206:209], v[92:95]
	v_mfma_f32_16x16x32_bf16 v[88:91], v[156:159], v[206:209], v[88:91]
	v_mfma_f32_16x16x32_bf16 v[76:79], v[148:151], v[214:217], v[76:79]
	v_mfma_f32_16x16x32_bf16 v[72:75], v[156:159], v[214:217], v[72:75]
	v_mfma_f32_16x16x32_bf16 v[116:119], v[160:163], v[176:179], 0
	v_mfma_f32_16x16x32_bf16 v[112:115], v[168:171], v[176:179], 0
	v_mfma_f32_16x16x32_bf16 v[100:103], v[160:163], v[194:197], 0
	v_mfma_f32_16x16x32_bf16 v[96:99], v[168:171], v[194:197], 0
	v_mfma_f32_16x16x32_bf16 v[84:87], v[160:163], v[202:205], 0
	v_mfma_f32_16x16x32_bf16 v[80:83], v[168:171], v[202:205], 0
	v_mfma_f32_16x16x32_bf16 v[68:71], v[160:163], v[210:213], 0
	v_mfma_f32_16x16x32_bf16 v[64:67], v[168:171], v[210:213], 0
	v_mfma_f32_16x16x32_bf16 v[116:119], v[164:167], v[180:183], v[116:119]
	v_mfma_f32_16x16x32_bf16 v[112:115], v[172:175], v[180:183], v[112:115]
	v_mfma_f32_16x16x32_bf16 v[100:103], v[164:167], v[198:201], v[100:103]
	v_mfma_f32_16x16x32_bf16 v[96:99], v[172:175], v[198:201], v[96:99]
	v_mfma_f32_16x16x32_bf16 v[84:87], v[164:167], v[206:209], v[84:87]
	v_mfma_f32_16x16x32_bf16 v[80:83], v[172:175], v[206:209], v[80:83]
	v_mfma_f32_16x16x32_bf16 v[68:71], v[164:167], v[214:217], v[68:71]
	v_mfma_f32_16x16x32_bf16 v[64:67], v[172:175], v[214:217], v[64:67]
	s_barrier
	s_setprio 0
	s_add_i32 s44, s63, s50
	v_lshl_add_u64 v[184:185], s[48:49], 0, v[130:131]
	s_mov_b32 m0, s44
	ds_read_b128 v[176:179], v191 offset:16384
	ds_read_b128 v[180:183], v191 offset:17408
	ds_read_b128 v[194:197], v191 offset:18432
	ds_read_b128 v[198:201], v191 offset:19456
	ds_read_b128 v[202:205], v191 offset:20480
	ds_read_b128 v[206:209], v191 offset:21504
	ds_read_b128 v[210:213], v191 offset:22528
	ds_read_b128 v[214:217], v191 offset:23552
	global_load_lds_dwordx4 v[184:185], off
	s_add_i32 m0, s44, 0x2000
	s_add_u32 s44, s48, 0x40000
	v_lshl_add_u64 v[218:219], s[48:49], 0, v[134:135]
	s_addc_u32 s45, s49, 0
	s_add_i32 s70, s64, s50
	global_load_lds_dwordx4 v[218:219], off
	v_lshl_add_u64 v[220:221], s[44:45], 0, v[130:131]
	s_mov_b32 m0, s70
	v_lshl_add_u64 v[222:223], s[74:75], 0, v[132:133]
	global_load_lds_dwordx4 v[220:221], off
	v_lshl_add_u64 v[220:221], s[44:45], 0, v[134:135]
	s_add_i32 m0, s70, 0x2000
	v_lshl_add_u64 v[224:225], v[222:223], 0, s[12:13]
	global_load_lds_dwordx4 v[220:221], off
	s_mov_b32 m0, s51
	v_lshl_add_u64 v[220:221], s[74:75], 0, v[128:129]
	global_load_lds_dwordx4 v[220:221], off
	s_mov_b32 m0, s52
	s_nop 0
	global_load_lds_dwordx4 v[224:225], off
	s_setprio 1
	s_waitcnt vmcnt(8) lgkmcnt(0)
	s_barrier
	v_mfma_f32_16x16x32_bf16 v[60:63], v[144:147], v[176:179], 0
	v_mfma_f32_16x16x32_bf16 v[56:59], v[152:155], v[176:179], 0
	v_mfma_f32_16x16x32_bf16 v[44:47], v[144:147], v[194:197], 0
	v_mfma_f32_16x16x32_bf16 v[40:43], v[152:155], v[194:197], 0
	v_mfma_f32_16x16x32_bf16 v[28:31], v[144:147], v[202:205], 0
	v_mfma_f32_16x16x32_bf16 v[24:27], v[152:155], v[202:205], 0
	v_mfma_f32_16x16x32_bf16 v[12:15], v[144:147], v[210:213], 0
	v_mfma_f32_16x16x32_bf16 v[8:11], v[152:155], v[210:213], 0
	v_mfma_f32_16x16x32_bf16 v[60:63], v[148:151], v[180:183], v[60:63]
	v_mfma_f32_16x16x32_bf16 v[56:59], v[156:159], v[180:183], v[56:59]
	v_mfma_f32_16x16x32_bf16 v[44:47], v[148:151], v[198:201], v[44:47]
	v_mfma_f32_16x16x32_bf16 v[40:43], v[156:159], v[198:201], v[40:43]
	v_mfma_f32_16x16x32_bf16 v[28:31], v[148:151], v[206:209], v[28:31]
	v_mfma_f32_16x16x32_bf16 v[24:27], v[156:159], v[206:209], v[24:27]
	v_mfma_f32_16x16x32_bf16 v[12:15], v[148:151], v[214:217], v[12:15]
	v_mfma_f32_16x16x32_bf16 v[8:11], v[156:159], v[214:217], v[8:11]
	v_mfma_f32_16x16x32_bf16 v[52:55], v[160:163], v[176:179], 0
	v_mfma_f32_16x16x32_bf16 v[48:51], v[168:171], v[176:179], 0
	v_mfma_f32_16x16x32_bf16 v[36:39], v[160:163], v[194:197], 0
	v_mfma_f32_16x16x32_bf16 v[32:35], v[168:171], v[194:197], 0
	v_mfma_f32_16x16x32_bf16 v[20:23], v[160:163], v[202:205], 0
	v_mfma_f32_16x16x32_bf16 v[16:19], v[168:171], v[202:205], 0
	v_mfma_f32_16x16x32_bf16 v[4:7], v[160:163], v[210:213], 0
	v_mfma_f32_16x16x32_bf16 v[0:3], v[168:171], v[210:213], 0
	v_mfma_f32_16x16x32_bf16 v[52:55], v[164:167], v[180:183], v[52:55]
	v_mfma_f32_16x16x32_bf16 v[48:51], v[172:175], v[180:183], v[48:51]
	v_mfma_f32_16x16x32_bf16 v[36:39], v[164:167], v[198:201], v[36:39]
	v_mfma_f32_16x16x32_bf16 v[32:35], v[172:175], v[198:201], v[32:35]
	v_mfma_f32_16x16x32_bf16 v[20:23], v[164:167], v[206:209], v[20:23]
	v_mfma_f32_16x16x32_bf16 v[16:19], v[172:175], v[206:209], v[16:19]
	v_mfma_f32_16x16x32_bf16 v[4:7], v[164:167], v[214:217], v[4:7]
	v_mfma_f32_16x16x32_bf16 v[0:3], v[172:175], v[214:217], v[0:3]
	s_barrier
	s_setprio 0
	s_add_i32 s44, 0, 0x18000
	s_add_i32 s70, 0, 0x1c000
	v_add_u32_e32 v156, s44, v187
	v_add_u32_e32 v172, s70, v187
	ds_read_b128 v[144:147], v156
	ds_read_b128 v[148:151], v156 offset:1024
	ds_read_b128 v[152:155], v156 offset:2048
	ds_read_b128 v[156:159], v156 offset:3072
	ds_read_b128 v[160:163], v172
	ds_read_b128 v[164:167], v172 offset:1024
	ds_read_b128 v[168:171], v172 offset:2048
	ds_read_b128 v[172:175], v172 offset:3072
	s_mov_b32 m0, s53
	v_lshl_add_u64 v[224:225], v[220:221], 0, s[10:11]
	ds_read_b128 v[176:179], v191 offset:32768
	ds_read_b128 v[180:183], v191 offset:33792
	ds_read_b128 v[194:197], v191 offset:34816
	ds_read_b128 v[198:201], v191 offset:35840
	ds_read_b128 v[202:205], v191 offset:36864
	ds_read_b128 v[206:209], v191 offset:37888
	ds_read_b128 v[210:213], v191 offset:38912
	ds_read_b128 v[214:217], v191 offset:39936
	global_load_lds_dwordx4 v[224:225], off
	s_mov_b32 m0, s54
	v_lshl_add_u64 v[224:225], v[222:223], 0, s[14:15]
	global_load_lds_dwordx4 v[224:225], off
	s_setprio 1
	s_waitcnt vmcnt(8) lgkmcnt(0)
	s_barrier
	v_mfma_f32_16x16x32_bf16 v[124:127], v[144:147], v[176:179], v[124:127]
	v_mfma_f32_16x16x32_bf16 v[120:123], v[152:155], v[176:179], v[120:123]
	v_mfma_f32_16x16x32_bf16 v[108:111], v[144:147], v[194:197], v[108:111]
	v_mfma_f32_16x16x32_bf16 v[104:107], v[152:155], v[194:197], v[104:107]
	v_mfma_f32_16x16x32_bf16 v[92:95], v[144:147], v[202:205], v[92:95]
	v_mfma_f32_16x16x32_bf16 v[88:91], v[152:155], v[202:205], v[88:91]
	v_mfma_f32_16x16x32_bf16 v[76:79], v[144:147], v[210:213], v[76:79]
	v_mfma_f32_16x16x32_bf16 v[72:75], v[152:155], v[210:213], v[72:75]
	v_mfma_f32_16x16x32_bf16 v[124:127], v[148:151], v[180:183], v[124:127]
	v_mfma_f32_16x16x32_bf16 v[120:123], v[156:159], v[180:183], v[120:123]
	v_mfma_f32_16x16x32_bf16 v[108:111], v[148:151], v[198:201], v[108:111]
	v_mfma_f32_16x16x32_bf16 v[104:107], v[156:159], v[198:201], v[104:107]
	v_mfma_f32_16x16x32_bf16 v[92:95], v[148:151], v[206:209], v[92:95]
	v_mfma_f32_16x16x32_bf16 v[88:91], v[156:159], v[206:209], v[88:91]
	v_mfma_f32_16x16x32_bf16 v[76:79], v[148:151], v[214:217], v[76:79]
	v_mfma_f32_16x16x32_bf16 v[72:75], v[156:159], v[214:217], v[72:75]
	v_mfma_f32_16x16x32_bf16 v[116:119], v[160:163], v[176:179], v[116:119]
	v_mfma_f32_16x16x32_bf16 v[112:115], v[168:171], v[176:179], v[112:115]
	v_mfma_f32_16x16x32_bf16 v[100:103], v[160:163], v[194:197], v[100:103]
	v_mfma_f32_16x16x32_bf16 v[96:99], v[168:171], v[194:197], v[96:99]
	v_mfma_f32_16x16x32_bf16 v[84:87], v[160:163], v[202:205], v[84:87]
	v_mfma_f32_16x16x32_bf16 v[80:83], v[168:171], v[202:205], v[80:83]
	v_mfma_f32_16x16x32_bf16 v[68:71], v[160:163], v[210:213], v[68:71]
	v_mfma_f32_16x16x32_bf16 v[64:67], v[168:171], v[210:213], v[64:67]
	v_mfma_f32_16x16x32_bf16 v[116:119], v[164:167], v[180:183], v[116:119]
	v_mfma_f32_16x16x32_bf16 v[112:115], v[172:175], v[180:183], v[112:115]
	v_mfma_f32_16x16x32_bf16 v[100:103], v[164:167], v[198:201], v[100:103]
	v_mfma_f32_16x16x32_bf16 v[96:99], v[172:175], v[198:201], v[96:99]
	v_mfma_f32_16x16x32_bf16 v[84:87], v[164:167], v[206:209], v[84:87]
	v_mfma_f32_16x16x32_bf16 v[80:83], v[172:175], v[206:209], v[80:83]
	v_mfma_f32_16x16x32_bf16 v[68:71], v[164:167], v[214:217], v[68:71]
	v_mfma_f32_16x16x32_bf16 v[64:67], v[172:175], v[214:217], v[64:67]
	s_barrier
	s_setprio 0
	s_add_i32 s44, s44, s50
	v_lshl_add_u64 v[184:185], v[184:185], 0, s[24:25]
	s_mov_b32 m0, s44
	ds_read_b128 v[176:179], v191 offset:49152
	ds_read_b128 v[180:183], v191 offset:50176
	ds_read_b128 v[194:197], v191 offset:51200
	ds_read_b128 v[198:201], v191 offset:52224
	ds_read_b128 v[202:205], v191 offset:53248
	ds_read_b128 v[206:209], v191 offset:54272
	ds_read_b128 v[210:213], v191 offset:55296
	ds_read_b128 v[214:217], v191 offset:56320
	global_load_lds_dwordx4 v[184:185], off
	s_add_i32 m0, s44, 0x2000
	s_add_u32 s44, s48, 0x40080
	v_lshl_add_u64 v[184:185], v[218:219], 0, s[24:25]
	s_addc_u32 s45, s49, 0
	s_add_i32 s48, s70, s50
	global_load_lds_dwordx4 v[184:185], off
	s_mov_b32 m0, s48
	v_lshl_add_u64 v[184:185], s[44:45], 0, v[130:131]
	global_load_lds_dwordx4 v[184:185], off
	s_add_i32 m0, s48, 0x2000
	v_lshl_add_u64 v[184:185], s[44:45], 0, v[134:135]
	global_load_lds_dwordx4 v[184:185], off
	s_mov_b32 m0, s58
	v_lshl_add_u64 v[184:185], v[220:221], 0, s[24:25]
	global_load_lds_dwordx4 v[184:185], off
	s_mov_b32 m0, s59
	v_lshl_add_u64 v[184:185], v[222:223], 0, s[30:31]
	global_load_lds_dwordx4 v[184:185], off
	s_setprio 1
	s_waitcnt vmcnt(8) lgkmcnt(0)
	s_barrier
	v_mfma_f32_16x16x32_bf16 v[60:63], v[144:147], v[176:179], v[60:63]
	v_mfma_f32_16x16x32_bf16 v[56:59], v[152:155], v[176:179], v[56:59]
	v_mfma_f32_16x16x32_bf16 v[44:47], v[144:147], v[194:197], v[44:47]
	v_mfma_f32_16x16x32_bf16 v[40:43], v[152:155], v[194:197], v[40:43]
	v_mfma_f32_16x16x32_bf16 v[28:31], v[144:147], v[202:205], v[28:31]
	v_mfma_f32_16x16x32_bf16 v[24:27], v[152:155], v[202:205], v[24:27]
	v_mfma_f32_16x16x32_bf16 v[12:15], v[144:147], v[210:213], v[12:15]
	v_mfma_f32_16x16x32_bf16 v[8:11], v[152:155], v[210:213], v[8:11]
	v_mfma_f32_16x16x32_bf16 v[60:63], v[148:151], v[180:183], v[60:63]
	v_mfma_f32_16x16x32_bf16 v[56:59], v[156:159], v[180:183], v[56:59]
	v_mfma_f32_16x16x32_bf16 v[44:47], v[148:151], v[198:201], v[44:47]
	v_mfma_f32_16x16x32_bf16 v[40:43], v[156:159], v[198:201], v[40:43]
	v_mfma_f32_16x16x32_bf16 v[28:31], v[148:151], v[206:209], v[28:31]
	v_mfma_f32_16x16x32_bf16 v[24:27], v[156:159], v[206:209], v[24:27]
	v_mfma_f32_16x16x32_bf16 v[12:15], v[148:151], v[214:217], v[12:15]
	v_mfma_f32_16x16x32_bf16 v[8:11], v[156:159], v[214:217], v[8:11]
	v_mfma_f32_16x16x32_bf16 v[52:55], v[160:163], v[176:179], v[52:55]
	v_mfma_f32_16x16x32_bf16 v[48:51], v[168:171], v[176:179], v[48:51]
	v_mfma_f32_16x16x32_bf16 v[36:39], v[160:163], v[194:197], v[36:39]
	v_mfma_f32_16x16x32_bf16 v[32:35], v[168:171], v[194:197], v[32:35]
	v_mfma_f32_16x16x32_bf16 v[20:23], v[160:163], v[202:205], v[20:23]
	v_mfma_f32_16x16x32_bf16 v[16:19], v[168:171], v[202:205], v[16:19]
	v_mfma_f32_16x16x32_bf16 v[4:7], v[160:163], v[210:213], v[4:7]
	v_mfma_f32_16x16x32_bf16 v[0:3], v[168:171], v[210:213], v[0:3]
	v_mfma_f32_16x16x32_bf16 v[52:55], v[164:167], v[180:183], v[52:55]
	v_mfma_f32_16x16x32_bf16 v[48:51], v[172:175], v[180:183], v[48:51]
	v_mfma_f32_16x16x32_bf16 v[36:39], v[164:167], v[198:201], v[36:39]
	v_mfma_f32_16x16x32_bf16 v[32:35], v[172:175], v[198:201], v[32:35]
	v_mfma_f32_16x16x32_bf16 v[20:23], v[164:167], v[206:209], v[20:23]
	v_mfma_f32_16x16x32_bf16 v[16:19], v[172:175], v[206:209], v[16:19]
	v_mfma_f32_16x16x32_bf16 v[4:7], v[164:167], v[214:217], v[4:7]
	v_mfma_f32_16x16x32_bf16 v[0:3], v[172:175], v[214:217], v[0:3]
	s_barrier
	s_setprio 0
	s_add_i32 s72, s72, 2
	s_add_u32 s69, s69, 0x100
	s_addc_u32 s71, s71, 0
	s_cmp_gt_u32 s72, 13
	s_mov_b64 s[44:45], s[46:47]
.LBB0_751:
	ds_read_b128 v[144:147], v189
	ds_read_b128 v[148:151], v189 offset:1024
	ds_read_b128 v[152:155], v189 offset:2048
	ds_read_b128 v[156:159], v189 offset:3072
	ds_read_b128 v[160:163], v190
	ds_read_b128 v[164:167], v190 offset:1024
	ds_read_b128 v[168:171], v190 offset:2048
	ds_read_b128 v[172:175], v190 offset:3072
	s_add_u32 s46, s44, 0x100
	s_addc_u32 s47, s45, 0
	s_cmp_eq_u32 s72, 12
	s_cselect_b32 s75, s43, s47
	s_cselect_b32 s74, s67, s46
	s_cselect_b32 s49, s37, s71
	s_cselect_b32 s48, s68, s69
	v_lshl_add_u64 v[184:185], s[44:45], 0, v[136:137]
	s_add_i32 m0, s51, 0xc000
	ds_read_b128 v[176:179], v191
	ds_read_b128 v[180:183], v191 offset:1024
	ds_read_b128 v[194:197], v191 offset:2048
	ds_read_b128 v[198:201], v191 offset:3072
	ds_read_b128 v[202:205], v191 offset:4096
	ds_read_b128 v[206:209], v191 offset:5120
	ds_read_b128 v[210:213], v191 offset:6144
	ds_read_b128 v[214:217], v191 offset:7168
	global_load_lds_dwordx4 v[184:185], off
	s_add_i32 m0, s51, 0xe000
	v_lshl_add_u64 v[184:185], s[44:45], 0, v[138:139]
	global_load_lds_dwordx4 v[184:185], off
	s_setprio 1
	s_waitcnt vmcnt(8) lgkmcnt(0)
	s_barrier
	v_mfma_f32_16x16x32_bf16 v[124:127], v[144:147], v[176:179], v[124:127]
	v_mfma_f32_16x16x32_bf16 v[120:123], v[152:155], v[176:179], v[120:123]
	v_mfma_f32_16x16x32_bf16 v[108:111], v[144:147], v[194:197], v[108:111]
	v_mfma_f32_16x16x32_bf16 v[104:107], v[152:155], v[194:197], v[104:107]
	v_mfma_f32_16x16x32_bf16 v[92:95], v[144:147], v[202:205], v[92:95]
	v_mfma_f32_16x16x32_bf16 v[88:91], v[152:155], v[202:205], v[88:91]
	v_mfma_f32_16x16x32_bf16 v[76:79], v[144:147], v[210:213], v[76:79]
	v_mfma_f32_16x16x32_bf16 v[72:75], v[152:155], v[210:213], v[72:75]
	v_mfma_f32_16x16x32_bf16 v[124:127], v[148:151], v[180:183], v[124:127]
	v_mfma_f32_16x16x32_bf16 v[120:123], v[156:159], v[180:183], v[120:123]
	v_mfma_f32_16x16x32_bf16 v[108:111], v[148:151], v[198:201], v[108:111]
	v_mfma_f32_16x16x32_bf16 v[104:107], v[156:159], v[198:201], v[104:107]
	v_mfma_f32_16x16x32_bf16 v[92:95], v[148:151], v[206:209], v[92:95]
	v_mfma_f32_16x16x32_bf16 v[88:91], v[156:159], v[206:209], v[88:91]
	v_mfma_f32_16x16x32_bf16 v[76:79], v[148:151], v[214:217], v[76:79]
	v_mfma_f32_16x16x32_bf16 v[72:75], v[156:159], v[214:217], v[72:75]
	v_mfma_f32_16x16x32_bf16 v[116:119], v[160:163], v[176:179], v[116:119]
	v_mfma_f32_16x16x32_bf16 v[112:115], v[168:171], v[176:179], v[112:115]
	v_mfma_f32_16x16x32_bf16 v[100:103], v[160:163], v[194:197], v[100:103]
	v_mfma_f32_16x16x32_bf16 v[96:99], v[168:171], v[194:197], v[96:99]
	v_mfma_f32_16x16x32_bf16 v[84:87], v[160:163], v[202:205], v[84:87]
	v_mfma_f32_16x16x32_bf16 v[80:83], v[168:171], v[202:205], v[80:83]
	v_mfma_f32_16x16x32_bf16 v[68:71], v[160:163], v[210:213], v[68:71]
	v_mfma_f32_16x16x32_bf16 v[64:67], v[168:171], v[210:213], v[64:67]
	v_mfma_f32_16x16x32_bf16 v[116:119], v[164:167], v[180:183], v[116:119]
	v_mfma_f32_16x16x32_bf16 v[112:115], v[172:175], v[180:183], v[112:115]
	v_mfma_f32_16x16x32_bf16 v[100:103], v[164:167], v[198:201], v[100:103]
	v_mfma_f32_16x16x32_bf16 v[96:99], v[172:175], v[198:201], v[96:99]
	v_mfma_f32_16x16x32_bf16 v[84:87], v[164:167], v[206:209], v[84:87]
	v_mfma_f32_16x16x32_bf16 v[80:83], v[172:175], v[206:209], v[80:83]
	v_mfma_f32_16x16x32_bf16 v[68:71], v[164:167], v[214:217], v[68:71]
	v_mfma_f32_16x16x32_bf16 v[64:67], v[172:175], v[214:217], v[64:67]
	s_barrier
	s_setprio 0
	s_add_i32 s44, s63, s50
	v_lshl_add_u64 v[184:185], s[48:49], 0, v[130:131]
	s_mov_b32 m0, s44
	ds_read_b128 v[176:179], v191 offset:16384
	ds_read_b128 v[180:183], v191 offset:17408
	ds_read_b128 v[194:197], v191 offset:18432
	ds_read_b128 v[198:201], v191 offset:19456
	ds_read_b128 v[202:205], v191 offset:20480
	ds_read_b128 v[206:209], v191 offset:21504
	ds_read_b128 v[210:213], v191 offset:22528
	ds_read_b128 v[214:217], v191 offset:23552
	global_load_lds_dwordx4 v[184:185], off
	s_add_i32 m0, s44, 0x2000
	s_add_u32 s44, s48, 0x40000
	v_lshl_add_u64 v[218:219], s[48:49], 0, v[134:135]
	s_addc_u32 s45, s49, 0
	s_add_i32 s70, s64, s50
	global_load_lds_dwordx4 v[218:219], off
	v_lshl_add_u64 v[220:221], s[44:45], 0, v[130:131]
	s_mov_b32 m0, s70
	v_lshl_add_u64 v[222:223], s[74:75], 0, v[132:133]
	global_load_lds_dwordx4 v[220:221], off
	v_lshl_add_u64 v[220:221], s[44:45], 0, v[134:135]
	s_add_i32 m0, s70, 0x2000
	v_lshl_add_u64 v[224:225], v[222:223], 0, s[12:13]
	global_load_lds_dwordx4 v[220:221], off
	s_mov_b32 m0, s51
	v_lshl_add_u64 v[220:221], s[74:75], 0, v[128:129]
	global_load_lds_dwordx4 v[220:221], off
	s_mov_b32 m0, s52
	s_nop 0
	global_load_lds_dwordx4 v[224:225], off
	s_setprio 1
	s_waitcnt vmcnt(8) lgkmcnt(0)
	s_barrier
	v_mfma_f32_16x16x32_bf16 v[60:63], v[144:147], v[176:179], v[60:63]
	v_mfma_f32_16x16x32_bf16 v[56:59], v[152:155], v[176:179], v[56:59]
	v_mfma_f32_16x16x32_bf16 v[44:47], v[144:147], v[194:197], v[44:47]
	v_mfma_f32_16x16x32_bf16 v[40:43], v[152:155], v[194:197], v[40:43]
	v_mfma_f32_16x16x32_bf16 v[28:31], v[144:147], v[202:205], v[28:31]
	v_mfma_f32_16x16x32_bf16 v[24:27], v[152:155], v[202:205], v[24:27]
	v_mfma_f32_16x16x32_bf16 v[12:15], v[144:147], v[210:213], v[12:15]
	v_mfma_f32_16x16x32_bf16 v[8:11], v[152:155], v[210:213], v[8:11]
	v_mfma_f32_16x16x32_bf16 v[60:63], v[148:151], v[180:183], v[60:63]
	v_mfma_f32_16x16x32_bf16 v[56:59], v[156:159], v[180:183], v[56:59]
	v_mfma_f32_16x16x32_bf16 v[44:47], v[148:151], v[198:201], v[44:47]
	v_mfma_f32_16x16x32_bf16 v[40:43], v[156:159], v[198:201], v[40:43]
	v_mfma_f32_16x16x32_bf16 v[28:31], v[148:151], v[206:209], v[28:31]
	v_mfma_f32_16x16x32_bf16 v[24:27], v[156:159], v[206:209], v[24:27]
	v_mfma_f32_16x16x32_bf16 v[12:15], v[148:151], v[214:217], v[12:15]
	v_mfma_f32_16x16x32_bf16 v[8:11], v[156:159], v[214:217], v[8:11]
	v_mfma_f32_16x16x32_bf16 v[52:55], v[160:163], v[176:179], v[52:55]
	v_mfma_f32_16x16x32_bf16 v[48:51], v[168:171], v[176:179], v[48:51]
	v_mfma_f32_16x16x32_bf16 v[36:39], v[160:163], v[194:197], v[36:39]
	v_mfma_f32_16x16x32_bf16 v[32:35], v[168:171], v[194:197], v[32:35]
	v_mfma_f32_16x16x32_bf16 v[20:23], v[160:163], v[202:205], v[20:23]
	v_mfma_f32_16x16x32_bf16 v[16:19], v[168:171], v[202:205], v[16:19]
	v_mfma_f32_16x16x32_bf16 v[4:7], v[160:163], v[210:213], v[4:7]
	v_mfma_f32_16x16x32_bf16 v[0:3], v[168:171], v[210:213], v[0:3]
	v_mfma_f32_16x16x32_bf16 v[52:55], v[164:167], v[180:183], v[52:55]
	v_mfma_f32_16x16x32_bf16 v[48:51], v[172:175], v[180:183], v[48:51]
	v_mfma_f32_16x16x32_bf16 v[36:39], v[164:167], v[198:201], v[36:39]
	v_mfma_f32_16x16x32_bf16 v[32:35], v[172:175], v[198:201], v[32:35]
	v_mfma_f32_16x16x32_bf16 v[20:23], v[164:167], v[206:209], v[20:23]
	v_mfma_f32_16x16x32_bf16 v[16:19], v[172:175], v[206:209], v[16:19]
	v_mfma_f32_16x16x32_bf16 v[4:7], v[164:167], v[214:217], v[4:7]
	v_mfma_f32_16x16x32_bf16 v[0:3], v[172:175], v[214:217], v[0:3]
	s_barrier
	s_setprio 0
	s_add_i32 s44, 0, 0x18000
	s_add_i32 s70, 0, 0x1c000
	v_add_u32_e32 v156, s44, v187
	v_add_u32_e32 v172, s70, v187
	ds_read_b128 v[144:147], v156
	ds_read_b128 v[148:151], v156 offset:1024
	ds_read_b128 v[152:155], v156 offset:2048
	ds_read_b128 v[156:159], v156 offset:3072
	ds_read_b128 v[160:163], v172
	ds_read_b128 v[164:167], v172 offset:1024
	ds_read_b128 v[168:171], v172 offset:2048
	ds_read_b128 v[172:175], v172 offset:3072
	s_mov_b32 m0, s53
	v_lshl_add_u64 v[224:225], v[220:221], 0, s[10:11]
	ds_read_b128 v[176:179], v191 offset:32768
	ds_read_b128 v[180:183], v191 offset:33792
	ds_read_b128 v[194:197], v191 offset:34816
	ds_read_b128 v[198:201], v191 offset:35840
	ds_read_b128 v[202:205], v191 offset:36864
	ds_read_b128 v[206:209], v191 offset:37888
	ds_read_b128 v[210:213], v191 offset:38912
	ds_read_b128 v[214:217], v191 offset:39936
	global_load_lds_dwordx4 v[224:225], off
	s_mov_b32 m0, s54
	v_lshl_add_u64 v[224:225], v[222:223], 0, s[14:15]
	global_load_lds_dwordx4 v[224:225], off
	s_setprio 1
	s_waitcnt vmcnt(8) lgkmcnt(0)
	s_barrier
	v_mfma_f32_16x16x32_bf16 v[124:127], v[144:147], v[176:179], v[124:127]
	v_mfma_f32_16x16x32_bf16 v[120:123], v[152:155], v[176:179], v[120:123]
	v_mfma_f32_16x16x32_bf16 v[108:111], v[144:147], v[194:197], v[108:111]
	v_mfma_f32_16x16x32_bf16 v[104:107], v[152:155], v[194:197], v[104:107]
	v_mfma_f32_16x16x32_bf16 v[92:95], v[144:147], v[202:205], v[92:95]
	v_mfma_f32_16x16x32_bf16 v[88:91], v[152:155], v[202:205], v[88:91]
	v_mfma_f32_16x16x32_bf16 v[76:79], v[144:147], v[210:213], v[76:79]
	v_mfma_f32_16x16x32_bf16 v[72:75], v[152:155], v[210:213], v[72:75]
	v_mfma_f32_16x16x32_bf16 v[124:127], v[148:151], v[180:183], v[124:127]
	v_mfma_f32_16x16x32_bf16 v[120:123], v[156:159], v[180:183], v[120:123]
	v_mfma_f32_16x16x32_bf16 v[108:111], v[148:151], v[198:201], v[108:111]
	v_mfma_f32_16x16x32_bf16 v[104:107], v[156:159], v[198:201], v[104:107]
	v_mfma_f32_16x16x32_bf16 v[92:95], v[148:151], v[206:209], v[92:95]
	v_mfma_f32_16x16x32_bf16 v[88:91], v[156:159], v[206:209], v[88:91]
	v_mfma_f32_16x16x32_bf16 v[76:79], v[148:151], v[214:217], v[76:79]
	v_mfma_f32_16x16x32_bf16 v[72:75], v[156:159], v[214:217], v[72:75]
	v_mfma_f32_16x16x32_bf16 v[116:119], v[160:163], v[176:179], v[116:119]
	v_mfma_f32_16x16x32_bf16 v[112:115], v[168:171], v[176:179], v[112:115]
	v_mfma_f32_16x16x32_bf16 v[100:103], v[160:163], v[194:197], v[100:103]
	v_mfma_f32_16x16x32_bf16 v[96:99], v[168:171], v[194:197], v[96:99]
	v_mfma_f32_16x16x32_bf16 v[84:87], v[160:163], v[202:205], v[84:87]
	v_mfma_f32_16x16x32_bf16 v[80:83], v[168:171], v[202:205], v[80:83]
	v_mfma_f32_16x16x32_bf16 v[68:71], v[160:163], v[210:213], v[68:71]
	v_mfma_f32_16x16x32_bf16 v[64:67], v[168:171], v[210:213], v[64:67]
	v_mfma_f32_16x16x32_bf16 v[116:119], v[164:167], v[180:183], v[116:119]
	v_mfma_f32_16x16x32_bf16 v[112:115], v[172:175], v[180:183], v[112:115]
	v_mfma_f32_16x16x32_bf16 v[100:103], v[164:167], v[198:201], v[100:103]
	v_mfma_f32_16x16x32_bf16 v[96:99], v[172:175], v[198:201], v[96:99]
	v_mfma_f32_16x16x32_bf16 v[84:87], v[164:167], v[206:209], v[84:87]
	v_mfma_f32_16x16x32_bf16 v[80:83], v[172:175], v[206:209], v[80:83]
	v_mfma_f32_16x16x32_bf16 v[68:71], v[164:167], v[214:217], v[68:71]
	v_mfma_f32_16x16x32_bf16 v[64:67], v[172:175], v[214:217], v[64:67]
	s_barrier
	s_setprio 0
	s_add_i32 s44, s44, s50
	v_lshl_add_u64 v[184:185], v[184:185], 0, s[24:25]
	s_mov_b32 m0, s44
	ds_read_b128 v[176:179], v191 offset:49152
	ds_read_b128 v[180:183], v191 offset:50176
	ds_read_b128 v[194:197], v191 offset:51200
	ds_read_b128 v[198:201], v191 offset:52224
	ds_read_b128 v[202:205], v191 offset:53248
	ds_read_b128 v[206:209], v191 offset:54272
	ds_read_b128 v[210:213], v191 offset:55296
	ds_read_b128 v[214:217], v191 offset:56320
	global_load_lds_dwordx4 v[184:185], off
	s_add_i32 m0, s44, 0x2000
	s_add_u32 s44, s48, 0x40080
	v_lshl_add_u64 v[184:185], v[218:219], 0, s[24:25]
	s_addc_u32 s45, s49, 0
	s_add_i32 s48, s70, s50
	global_load_lds_dwordx4 v[184:185], off
	s_mov_b32 m0, s48
	v_lshl_add_u64 v[184:185], s[44:45], 0, v[130:131]
	global_load_lds_dwordx4 v[184:185], off
	s_add_i32 m0, s48, 0x2000
	v_lshl_add_u64 v[184:185], s[44:45], 0, v[134:135]
	global_load_lds_dwordx4 v[184:185], off
	s_mov_b32 m0, s58
	v_lshl_add_u64 v[184:185], v[220:221], 0, s[24:25]
	global_load_lds_dwordx4 v[184:185], off
	s_mov_b32 m0, s59
	v_lshl_add_u64 v[184:185], v[222:223], 0, s[30:31]
	global_load_lds_dwordx4 v[184:185], off
	s_setprio 1
	s_waitcnt vmcnt(8) lgkmcnt(0)
	s_barrier
	v_mfma_f32_16x16x32_bf16 v[60:63], v[144:147], v[176:179], v[60:63]
	v_mfma_f32_16x16x32_bf16 v[56:59], v[152:155], v[176:179], v[56:59]
	v_mfma_f32_16x16x32_bf16 v[44:47], v[144:147], v[194:197], v[44:47]
	v_mfma_f32_16x16x32_bf16 v[40:43], v[152:155], v[194:197], v[40:43]
	v_mfma_f32_16x16x32_bf16 v[28:31], v[144:147], v[202:205], v[28:31]
	v_mfma_f32_16x16x32_bf16 v[24:27], v[152:155], v[202:205], v[24:27]
	v_mfma_f32_16x16x32_bf16 v[12:15], v[144:147], v[210:213], v[12:15]
	v_mfma_f32_16x16x32_bf16 v[8:11], v[152:155], v[210:213], v[8:11]
	v_mfma_f32_16x16x32_bf16 v[60:63], v[148:151], v[180:183], v[60:63]
	v_mfma_f32_16x16x32_bf16 v[56:59], v[156:159], v[180:183], v[56:59]
	v_mfma_f32_16x16x32_bf16 v[44:47], v[148:151], v[198:201], v[44:47]
	v_mfma_f32_16x16x32_bf16 v[40:43], v[156:159], v[198:201], v[40:43]
	v_mfma_f32_16x16x32_bf16 v[28:31], v[148:151], v[206:209], v[28:31]
	v_mfma_f32_16x16x32_bf16 v[24:27], v[156:159], v[206:209], v[24:27]
	v_mfma_f32_16x16x32_bf16 v[12:15], v[148:151], v[214:217], v[12:15]
	v_mfma_f32_16x16x32_bf16 v[8:11], v[156:159], v[214:217], v[8:11]
	v_mfma_f32_16x16x32_bf16 v[52:55], v[160:163], v[176:179], v[52:55]
	v_mfma_f32_16x16x32_bf16 v[48:51], v[168:171], v[176:179], v[48:51]
	v_mfma_f32_16x16x32_bf16 v[36:39], v[160:163], v[194:197], v[36:39]
	v_mfma_f32_16x16x32_bf16 v[32:35], v[168:171], v[194:197], v[32:35]
	v_mfma_f32_16x16x32_bf16 v[20:23], v[160:163], v[202:205], v[20:23]
	v_mfma_f32_16x16x32_bf16 v[16:19], v[168:171], v[202:205], v[16:19]
	v_mfma_f32_16x16x32_bf16 v[4:7], v[160:163], v[210:213], v[4:7]
	v_mfma_f32_16x16x32_bf16 v[0:3], v[168:171], v[210:213], v[0:3]
	v_mfma_f32_16x16x32_bf16 v[52:55], v[164:167], v[180:183], v[52:55]
	v_mfma_f32_16x16x32_bf16 v[48:51], v[172:175], v[180:183], v[48:51]
	v_mfma_f32_16x16x32_bf16 v[36:39], v[164:167], v[198:201], v[36:39]
	v_mfma_f32_16x16x32_bf16 v[32:35], v[172:175], v[198:201], v[32:35]
	v_mfma_f32_16x16x32_bf16 v[20:23], v[164:167], v[206:209], v[20:23]
	v_mfma_f32_16x16x32_bf16 v[16:19], v[172:175], v[206:209], v[16:19]
	v_mfma_f32_16x16x32_bf16 v[4:7], v[164:167], v[214:217], v[4:7]
	v_mfma_f32_16x16x32_bf16 v[0:3], v[172:175], v[214:217], v[0:3]
	s_barrier
	s_setprio 0
	s_add_i32 s72, s72, 2
	s_add_u32 s69, s69, 0x100
	s_addc_u32 s71, s71, 0
	s_cmp_gt_u32 s72, 13
	s_mov_b64 s[44:45], s[46:47]
	s_cbranch_scc0 .LBB0_751
	s_and_b64 vcc, exec, s[34:35]
	s_cbranch_vccz .LBB0_754
	s_barrier
